# GEMM main loops: MFMA-segment priority 3 instead of 1
# speedup vs baseline: 1.0037x; 1.0037x over previous
; #define PG8_STAGE(bufoff, gbase, voff) do { _Pragma("unroll") for (int _i = 0; _i < 2; ++_i) \
;         __builtin_amdgcn_global_load_lds((const unsigned*)((const char*)(gbase) + (voff)[_i]), (LAS unsigned*)(lds + (bufoff) + ldsw + _i * 8192), 16, 0, 0); } while (0)
; #define PG8_LDA(dst, b, h) do { _Pragma("unroll") for (int m = 0; m < 4; ++m) _Pragma("unroll") for (int k = 0; k < 2; ++k) dst[m][k] = *(const LAS bf16x8*)(lds + PG8_SA(b, h) + aoff + m * 2048 + k * 1024); } while (0)
; #define PG8_LDB(dst, b, h) do { _Pragma("unroll") for (int n = 0; n < 2; ++n) _Pragma("unroll") for (int k = 0; k < 2; ++k) dst[n][k] = *(const LAS bf16x8*)(lds + PG8_SB(b, h) + boff + n * 2048 + k * 1024); } while (0)
; #define PG8_MMA(ai, bj, At, Bt) do { __builtin_amdgcn_s_setprio(1); _Pragma("unroll") for (int m = 0; m < 4; ++m) _Pragma("unroll") for (int n = 0; n < 2; ++n) _Pragma("unroll") for (int k = 0; k < 2; ++k) \
;         acc[ai][bj][m][n] = __builtin_amdgcn_mfma_f32_16x16x32_bf16(Bt[n][k], At[m][k], acc[ai][bj][m][n], 0, 0, 0); __builtin_amdgcn_s_setprio(0); } while (0)
; #define PG8_WAIT_V(n) asm volatile("s_waitcnt vmcnt(" #n ")" ::: "memory")
; #define PG8_WAIT_L(n) asm volatile("s_waitcnt lgkmcnt(" #n ")" ::: "memory")
; #define PG8_BAR __builtin_amdgcn_s_barrier()
; template <class Epi, class Sched, int LDA, int LDB, bool ALIGN_EPI = true>
; __device__ __forceinline__ void gemm_phase(LAS unsigned char* lds, const Gemm g, const Sched& S, const Epi& E, int wave) {
;     ...
;         for (int t = 0; t < nt; t += 2) {
;             const bool last = (t == nt - 2);
;             const char* a1 = cA + (size_t)(t + 1) * kstep;
;             const char* a2 = last ? nA : cA + (size_t)(t + 2) * kstep; const char* b2 = last ? nB : cB + (size_t)(t + 2) * kstep;
;             const char* a3 = a2 + kstep; const char* b3 = b2 + kstep;
;             PG8_LDB(B0, 0, 0); PG8_LDB(B1, 0, 1); PG8_SCHED; PG8_LDA(At, 0, 0); PG8_STAGE(PG8_SA(1, 1), a1 + hstepA, voffA);
;             PG8_WAIT_V(8); PG8_WAIT_L(0); PG8_BAR; PG8_MMA(0, 0, At, B0); PG8_MMA(0, 1, At, B1); PG8_BAR; PG8_SCHED;
;             PG8_LDA(At, 0, 1); PG8_STAGE(PG8_SB(0, 0), b2, voffB); PG8_STAGE(PG8_SB(0, 1), b2 + hstepB, voffB); PG8_STAGE(PG8_SA(0, 0), a2, voffA);
;             PG8_WAIT_V(8); PG8_WAIT_L(0); PG8_BAR; PG8_MMA(1, 0, At, B0); PG8_MMA(1, 1, At, B1); PG8_BAR; PG8_SCHED;
.LBB0_485:
	s_add_u32 s24, s18, 0x100
	s_addc_u32 s25, s19, 0
	s_add_i32 s54, 0, 0x10000
	s_cmp_eq_u32 s53, 28
	s_cselect_b32 s35, s3, s25
	s_cselect_b32 s34, s2, s24
	v_add_u32_e32 v140, s54, v143
	s_cselect_b32 s29, s1, s45
	s_cselect_b32 s28, s17, s44
	s_add_i32 s55, 0, 0x14000
	ds_read_b128 v[146:149], v140
	ds_read_b128 v[150:153], v140 offset:1024
	ds_read_b128 v[154:157], v140 offset:2048
	ds_read_b128 v[158:161], v140 offset:3072
	v_add_u32_e32 v140, s55, v143
	ds_read_b128 v[162:165], v140
	ds_read_b128 v[166:169], v140 offset:1024
	ds_read_b128 v[170:173], v140 offset:2048
	ds_read_b128 v[180:183], v140 offset:3072
	v_lshl_add_u64 v[140:141], s[18:19], 0, v[136:137]
	s_add_i32 m0, s38, 0xc000
	ds_read_b128 v[184:187], v145
	ds_read_b128 v[188:191], v145 offset:1024
	ds_read_b128 v[192:195], v145 offset:2048
	ds_read_b128 v[196:199], v145 offset:3072
	ds_read_b128 v[200:203], v145 offset:4096
	ds_read_b128 v[204:207], v145 offset:5120
	ds_read_b128 v[208:211], v145 offset:6144
	ds_read_b128 v[212:215], v145 offset:7168
	global_load_lds_dwordx4 v[140:141], off
	v_lshl_add_u64 v[140:141], s[18:19], 0, v[138:139]
	s_add_i32 m0, s38, 0xe000
	s_nop 0
	global_load_lds_dwordx4 v[140:141], off
	s_waitcnt vmcnt(8)
	s_waitcnt lgkmcnt(0)
	s_setprio 3
	s_barrier
	v_mfma_f32_16x16x32_bf16 v[126:129], v[146:149], v[184:187], v[126:129]
	v_mfma_f32_16x16x32_bf16 v[118:121], v[154:157], v[184:187], v[118:121]
	v_mfma_f32_16x16x32_bf16 v[110:113], v[146:149], v[192:195], v[110:113]
	v_mfma_f32_16x16x32_bf16 v[102:105], v[154:157], v[192:195], v[102:105]
	v_mfma_f32_16x16x32_bf16 v[94:97], v[146:149], v[200:203], v[94:97]
	v_mfma_f32_16x16x32_bf16 v[86:89], v[154:157], v[200:203], v[86:89]
	v_mfma_f32_16x16x32_bf16 v[78:81], v[146:149], v[208:211], v[78:81]
	v_mfma_f32_16x16x32_bf16 v[70:73], v[154:157], v[208:211], v[70:73]
	v_mfma_f32_16x16x32_bf16 v[126:129], v[150:153], v[188:191], v[126:129]
	v_mfma_f32_16x16x32_bf16 v[118:121], v[158:161], v[188:191], v[118:121]
	v_mfma_f32_16x16x32_bf16 v[110:113], v[150:153], v[196:199], v[110:113]
	v_mfma_f32_16x16x32_bf16 v[102:105], v[158:161], v[196:199], v[102:105]
	v_mfma_f32_16x16x32_bf16 v[94:97], v[150:153], v[204:207], v[94:97]
	v_mfma_f32_16x16x32_bf16 v[86:89], v[158:161], v[204:207], v[86:89]
	v_mfma_f32_16x16x32_bf16 v[78:81], v[150:153], v[212:215], v[78:81]
	v_mfma_f32_16x16x32_bf16 v[70:73], v[158:161], v[212:215], v[70:73]
	v_mfma_f32_16x16x32_bf16 v[122:125], v[162:165], v[184:187], v[122:125]
	v_mfma_f32_16x16x32_bf16 v[114:117], v[170:173], v[184:187], v[114:117]
	v_mfma_f32_16x16x32_bf16 v[106:109], v[162:165], v[192:195], v[106:109]
	v_mfma_f32_16x16x32_bf16 v[98:101], v[170:173], v[192:195], v[98:101]
	v_mfma_f32_16x16x32_bf16 v[90:93], v[162:165], v[200:203], v[90:93]
	v_mfma_f32_16x16x32_bf16 v[82:85], v[170:173], v[200:203], v[82:85]
	v_mfma_f32_16x16x32_bf16 v[74:77], v[162:165], v[208:211], v[74:77]
	v_mfma_f32_16x16x32_bf16 v[66:69], v[170:173], v[208:211], v[66:69]
	v_mfma_f32_16x16x32_bf16 v[122:125], v[166:169], v[188:191], v[122:125]
	v_mfma_f32_16x16x32_bf16 v[114:117], v[180:183], v[188:191], v[114:117]
	v_mfma_f32_16x16x32_bf16 v[106:109], v[166:169], v[196:199], v[106:109]
	v_mfma_f32_16x16x32_bf16 v[98:101], v[180:183], v[196:199], v[98:101]
	v_mfma_f32_16x16x32_bf16 v[90:93], v[166:169], v[204:207], v[90:93]
	v_mfma_f32_16x16x32_bf16 v[82:85], v[180:183], v[204:207], v[82:85]
	v_mfma_f32_16x16x32_bf16 v[74:77], v[166:169], v[212:215], v[74:77]
	v_mfma_f32_16x16x32_bf16 v[66:69], v[180:183], v[212:215], v[66:69]
	s_barrier
	s_setprio 0
	s_add_i32 s18, s54, s5
	v_lshl_add_u64 v[140:141], s[28:29], 0, v[0:1]
	s_mov_b32 m0, s18
	ds_read_b128 v[184:187], v145 offset:16384
	ds_read_b128 v[188:191], v145 offset:17408
	ds_read_b128 v[192:195], v145 offset:18432
	ds_read_b128 v[196:199], v145 offset:19456
	ds_read_b128 v[200:203], v145 offset:20480
	ds_read_b128 v[204:207], v145 offset:21504
	ds_read_b128 v[208:211], v145 offset:22528
	ds_read_b128 v[212:215], v145 offset:23552
	global_load_lds_dwordx4 v[140:141], off
	s_add_i32 m0, s18, 0x2000
	s_add_u32 s18, s28, 0x80000
	v_lshl_add_u64 v[174:175], s[28:29], 0, v[130:131]
	s_addc_u32 s19, s29, 0
	s_add_i32 s54, s55, s5
	global_load_lds_dwordx4 v[174:175], off
	v_lshl_add_u64 v[216:217], s[18:19], 0, v[0:1]
	s_mov_b32 m0, s54
	v_lshl_add_u64 v[218:219], s[34:35], 0, v[132:133]
	global_load_lds_dwordx4 v[216:217], off
	v_lshl_add_u64 v[216:217], s[18:19], 0, v[130:131]
	s_add_i32 m0, s54, 0x2000
	s_nop 0
	global_load_lds_dwordx4 v[216:217], off
	v_lshl_add_u64 v[216:217], s[34:35], 0, v[134:135]
	s_mov_b32 m0, s38
	s_nop 0
	global_load_lds_dwordx4 v[216:217], off
	s_mov_b32 m0, s39
	s_nop 0
	global_load_lds_dwordx4 v[218:219], off
	s_waitcnt vmcnt(8)
	s_waitcnt lgkmcnt(0)
	s_setprio 3
	s_barrier
; #define PG8_STAGE(bufoff, gbase, voff) do { _Pragma("unroll") for (int _i = 0; _i < 2; ++_i) \
;         __builtin_amdgcn_global_load_lds((const unsigned*)((const char*)(gbase) + (voff)[_i]), (LAS unsigned*)(lds + (bufoff) + ldsw + _i * 8192), 16, 0, 0); } while (0)
; #define PG8_LDA(dst, b, h) do { _Pragma("unroll") for (int m = 0; m < 4; ++m) _Pragma("unroll") for (int k = 0; k < 2; ++k) dst[m][k] = *(const LAS bf16x8*)(lds + PG8_SA(b, h) + aoff + m * 2048 + k * 1024); } while (0)
; #define PG8_LDB(dst, b, h) do { _Pragma("unroll") for (int n = 0; n < 2; ++n) _Pragma("unroll") for (int k = 0; k < 2; ++k) dst[n][k] = *(const LAS bf16x8*)(lds + PG8_SB(b, h) + boff + n * 2048 + k * 1024); } while (0)
; #define PG8_MMA(ai, bj, At, Bt) do { __builtin_amdgcn_s_setprio(1); _Pragma("unroll") for (int m = 0; m < 4; ++m) _Pragma("unroll") for (int n = 0; n < 2; ++n) _Pragma("unroll") for (int k = 0; k < 2; ++k) \
;         acc[ai][bj][m][n] = __builtin_amdgcn_mfma_f32_16x16x32_bf16(Bt[n][k], At[m][k], acc[ai][bj][m][n], 0, 0, 0); __builtin_amdgcn_s_setprio(0); } while (0)
; #define PG8_WAIT_V(n) asm volatile("s_waitcnt vmcnt(" #n ")" ::: "memory")
; #define PG8_WAIT_L(n) asm volatile("s_waitcnt lgkmcnt(" #n ")" ::: "memory")
; #define PG8_BAR __builtin_amdgcn_s_barrier()
; #define PG8_SCHED __builtin_amdgcn_sched_barrier(0)
; template <class Epi, class Sched, int LDA, int LDB, bool ALIGN_EPI = true>
; __device__ __forceinline__ void gemm_phase(LAS unsigned char* lds, const Gemm g, const Sched& S, const Epi& E, int wave) {
;     ...
;             PG8_WAIT_V(8); PG8_WAIT_L(0); PG8_BAR; PG8_MMA(1, 0, At, B0); PG8_MMA(1, 1, At, B1); PG8_BAR; PG8_SCHED;
;             PG8_LDB(B0, 1, 0); PG8_LDB(B1, 1, 1); PG8_SCHED; PG8_LDA(At, 1, 0); PG8_STAGE(PG8_SA(0, 1), a2 + hstepA, voffA);
;             PG8_WAIT_V(8); PG8_WAIT_L(0); PG8_BAR; PG8_MMA(0, 0, At, B0); PG8_MMA(0, 1, At, B1); PG8_BAR; PG8_SCHED;
	v_mfma_f32_16x16x32_bf16 v[62:65], v[146:149], v[184:187], v[62:65]
	v_mfma_f32_16x16x32_bf16 v[54:57], v[154:157], v[184:187], v[54:57]
	v_mfma_f32_16x16x32_bf16 v[46:49], v[146:149], v[192:195], v[46:49]
	v_mfma_f32_16x16x32_bf16 v[38:41], v[154:157], v[192:195], v[38:41]
	v_mfma_f32_16x16x32_bf16 v[30:33], v[146:149], v[200:203], v[30:33]
	v_mfma_f32_16x16x32_bf16 v[22:25], v[154:157], v[200:203], v[22:25]
	v_mfma_f32_16x16x32_bf16 v[14:17], v[146:149], v[208:211], v[14:17]
	v_mfma_f32_16x16x32_bf16 v[6:9], v[154:157], v[208:211], v[6:9]
	v_mfma_f32_16x16x32_bf16 v[62:65], v[150:153], v[188:191], v[62:65]
	v_mfma_f32_16x16x32_bf16 v[54:57], v[158:161], v[188:191], v[54:57]
	v_mfma_f32_16x16x32_bf16 v[46:49], v[150:153], v[196:199], v[46:49]
	v_mfma_f32_16x16x32_bf16 v[38:41], v[158:161], v[196:199], v[38:41]
	v_mfma_f32_16x16x32_bf16 v[30:33], v[150:153], v[204:207], v[30:33]
	v_mfma_f32_16x16x32_bf16 v[22:25], v[158:161], v[204:207], v[22:25]
	v_mfma_f32_16x16x32_bf16 v[14:17], v[150:153], v[212:215], v[14:17]
	v_mfma_f32_16x16x32_bf16 v[6:9], v[158:161], v[212:215], v[6:9]
	v_mfma_f32_16x16x32_bf16 v[58:61], v[162:165], v[184:187], v[58:61]
	v_mfma_f32_16x16x32_bf16 v[50:53], v[170:173], v[184:187], v[50:53]
	v_mfma_f32_16x16x32_bf16 v[42:45], v[162:165], v[192:195], v[42:45]
	v_mfma_f32_16x16x32_bf16 v[34:37], v[170:173], v[192:195], v[34:37]
	v_mfma_f32_16x16x32_bf16 v[26:29], v[162:165], v[200:203], v[26:29]
	v_mfma_f32_16x16x32_bf16 v[18:21], v[170:173], v[200:203], v[18:21]
	v_mfma_f32_16x16x32_bf16 v[10:13], v[162:165], v[208:211], v[10:13]
	v_mfma_f32_16x16x32_bf16 v[2:5], v[170:173], v[208:211], v[2:5]
	v_mfma_f32_16x16x32_bf16 v[58:61], v[166:169], v[188:191], v[58:61]
	v_mfma_f32_16x16x32_bf16 v[50:53], v[180:183], v[188:191], v[50:53]
	v_mfma_f32_16x16x32_bf16 v[42:45], v[166:169], v[196:199], v[42:45]
	v_mfma_f32_16x16x32_bf16 v[34:37], v[180:183], v[196:199], v[34:37]
	v_mfma_f32_16x16x32_bf16 v[26:29], v[166:169], v[204:207], v[26:29]
	v_mfma_f32_16x16x32_bf16 v[18:21], v[180:183], v[204:207], v[18:21]
	v_mfma_f32_16x16x32_bf16 v[10:13], v[166:169], v[212:215], v[10:13]
	v_mfma_f32_16x16x32_bf16 v[2:5], v[180:183], v[212:215], v[2:5]
	s_barrier
	s_setprio 0
	s_add_i32 s54, 0, 0x18000
	s_add_i32 s55, 0, 0x1c000
	v_add_u32_e32 v158, s54, v143
	v_add_u32_e32 v180, s55, v143
	ds_read_b128 v[146:149], v158
	ds_read_b128 v[150:153], v158 offset:1024
	ds_read_b128 v[154:157], v158 offset:2048
	ds_read_b128 v[158:161], v158 offset:3072
	ds_read_b128 v[162:165], v180
	ds_read_b128 v[166:169], v180 offset:1024
	ds_read_b128 v[170:173], v180 offset:2048
	ds_read_b128 v[180:183], v180 offset:3072
	s_add_u32 s18, s34, 0x84000
	s_addc_u32 s19, s35, 0
	s_mov_b32 m0, s46
	v_lshl_add_u64 v[220:221], s[18:19], 0, v[134:135]
	ds_read_b128 v[184:187], v145 offset:32768
	ds_read_b128 v[188:191], v145 offset:33792
	ds_read_b128 v[192:195], v145 offset:34816
	ds_read_b128 v[196:199], v145 offset:35840
	ds_read_b128 v[200:203], v145 offset:36864
	ds_read_b128 v[204:207], v145 offset:37888
	ds_read_b128 v[208:211], v145 offset:38912
	ds_read_b128 v[212:215], v145 offset:39936
	global_load_lds_dwordx4 v[220:221], off
	v_lshl_add_u64 v[220:221], s[18:19], 0, v[132:133]
	s_mov_b32 m0, s47
	s_nop 0
	global_load_lds_dwordx4 v[220:221], off
	s_waitcnt vmcnt(8)
	s_waitcnt lgkmcnt(0)
	s_setprio 3
	s_barrier
	v_mfma_f32_16x16x32_bf16 v[126:129], v[146:149], v[184:187], v[126:129]
	v_mfma_f32_16x16x32_bf16 v[118:121], v[154:157], v[184:187], v[118:121]
	v_mfma_f32_16x16x32_bf16 v[110:113], v[146:149], v[192:195], v[110:113]
	v_mfma_f32_16x16x32_bf16 v[102:105], v[154:157], v[192:195], v[102:105]
	v_mfma_f32_16x16x32_bf16 v[94:97], v[146:149], v[200:203], v[94:97]
	v_mfma_f32_16x16x32_bf16 v[86:89], v[154:157], v[200:203], v[86:89]
	v_mfma_f32_16x16x32_bf16 v[78:81], v[146:149], v[208:211], v[78:81]
	v_mfma_f32_16x16x32_bf16 v[70:73], v[154:157], v[208:211], v[70:73]
	v_mfma_f32_16x16x32_bf16 v[126:129], v[150:153], v[188:191], v[126:129]
	v_mfma_f32_16x16x32_bf16 v[118:121], v[158:161], v[188:191], v[118:121]
	v_mfma_f32_16x16x32_bf16 v[110:113], v[150:153], v[196:199], v[110:113]
	v_mfma_f32_16x16x32_bf16 v[102:105], v[158:161], v[196:199], v[102:105]
	v_mfma_f32_16x16x32_bf16 v[94:97], v[150:153], v[204:207], v[94:97]
	v_mfma_f32_16x16x32_bf16 v[86:89], v[158:161], v[204:207], v[86:89]
	v_mfma_f32_16x16x32_bf16 v[78:81], v[150:153], v[212:215], v[78:81]
	v_mfma_f32_16x16x32_bf16 v[70:73], v[158:161], v[212:215], v[70:73]
	v_mfma_f32_16x16x32_bf16 v[122:125], v[162:165], v[184:187], v[122:125]
	v_mfma_f32_16x16x32_bf16 v[114:117], v[170:173], v[184:187], v[114:117]
	v_mfma_f32_16x16x32_bf16 v[106:109], v[162:165], v[192:195], v[106:109]
	v_mfma_f32_16x16x32_bf16 v[98:101], v[170:173], v[192:195], v[98:101]
	v_mfma_f32_16x16x32_bf16 v[90:93], v[162:165], v[200:203], v[90:93]
	v_mfma_f32_16x16x32_bf16 v[82:85], v[170:173], v[200:203], v[82:85]
	v_mfma_f32_16x16x32_bf16 v[74:77], v[162:165], v[208:211], v[74:77]
	v_mfma_f32_16x16x32_bf16 v[66:69], v[170:173], v[208:211], v[66:69]
	v_mfma_f32_16x16x32_bf16 v[122:125], v[166:169], v[188:191], v[122:125]
	v_mfma_f32_16x16x32_bf16 v[114:117], v[180:183], v[188:191], v[114:117]
	v_mfma_f32_16x16x32_bf16 v[106:109], v[166:169], v[196:199], v[106:109]
	v_mfma_f32_16x16x32_bf16 v[98:101], v[180:183], v[196:199], v[98:101]
	v_mfma_f32_16x16x32_bf16 v[90:93], v[166:169], v[204:207], v[90:93]
	v_mfma_f32_16x16x32_bf16 v[82:85], v[180:183], v[204:207], v[82:85]
	v_mfma_f32_16x16x32_bf16 v[74:77], v[166:169], v[212:215], v[74:77]
	v_mfma_f32_16x16x32_bf16 v[66:69], v[180:183], v[212:215], v[66:69]
	s_barrier
; #define PG8_STAGE(bufoff, gbase, voff) do { _Pragma("unroll") for (int _i = 0; _i < 2; ++_i) \
;         __builtin_amdgcn_global_load_lds((const unsigned*)((const char*)(gbase) + (voff)[_i]), (LAS unsigned*)(lds + (bufoff) + ldsw + _i * 8192), 16, 0, 0); } while (0)
; #define PG8_LDA(dst, b, h) do { _Pragma("unroll") for (int m = 0; m < 4; ++m) _Pragma("unroll") for (int k = 0; k < 2; ++k) dst[m][k] = *(const LAS bf16x8*)(lds + PG8_SA(b, h) + aoff + m * 2048 + k * 1024); } while (0)
; #define PG8_MMA(ai, bj, At, Bt) do { __builtin_amdgcn_s_setprio(1); _Pragma("unroll") for (int m = 0; m < 4; ++m) _Pragma("unroll") for (int n = 0; n < 2; ++n) _Pragma("unroll") for (int k = 0; k < 2; ++k) \
;         acc[ai][bj][m][n] = __builtin_amdgcn_mfma_f32_16x16x32_bf16(Bt[n][k], At[m][k], acc[ai][bj][m][n], 0, 0, 0); __builtin_amdgcn_s_setprio(0); } while (0)
; #define PG8_WAIT_V(n) asm volatile("s_waitcnt vmcnt(" #n ")" ::: "memory")
; #define PG8_WAIT_L(n) asm volatile("s_waitcnt lgkmcnt(" #n ")" ::: "memory")
; #define PG8_BAR __builtin_amdgcn_s_barrier()
; #define PG8_SCHED __builtin_amdgcn_sched_barrier(0)
; template <class Epi, class Sched, int LDA, int LDB, bool ALIGN_EPI = true>
; __device__ __forceinline__ void gemm_phase(LAS unsigned char* lds, const Gemm g, const Sched& S, const Epi& E, int wave) {
;     ...
;             PG8_LDA(At, 1, 1); PG8_STAGE(PG8_SB(1, 0), b3, voffB); PG8_STAGE(PG8_SB(1, 1), b3 + hstepB, voffB); PG8_STAGE(PG8_SA(1, 0), a3, voffA);
;             PG8_WAIT_V(8); PG8_WAIT_L(0); PG8_BAR; PG8_MMA(1, 0, At, B0); PG8_MMA(1, 1, At, B1); PG8_BAR; PG8_SCHED;
;         }
;         if constexpr (ALIGN_EPI) { if (wr == 0) PG8_BAR; }
	s_setprio 0
	s_add_i32 s18, s54, s5
	v_lshl_add_u64 v[140:141], v[140:141], 0, s[6:7]
	s_mov_b32 m0, s18
	ds_read_b128 v[184:187], v145 offset:49152
	ds_read_b128 v[188:191], v145 offset:50176
	ds_read_b128 v[192:195], v145 offset:51200
	ds_read_b128 v[196:199], v145 offset:52224
	ds_read_b128 v[200:203], v145 offset:53248
	ds_read_b128 v[204:207], v145 offset:54272
	ds_read_b128 v[208:211], v145 offset:55296
	ds_read_b128 v[212:215], v145 offset:56320
	global_load_lds_dwordx4 v[140:141], off
	s_add_i32 m0, s18, 0x2000
	s_add_u32 s18, s28, 0x80080
	v_lshl_add_u64 v[140:141], v[174:175], 0, s[6:7]
	s_addc_u32 s19, s29, 0
	s_add_i32 s28, s55, s5
	global_load_lds_dwordx4 v[140:141], off
	v_lshl_add_u64 v[140:141], s[18:19], 0, v[0:1]
	s_mov_b32 m0, s28
	s_nop 0
	global_load_lds_dwordx4 v[140:141], off
	v_lshl_add_u64 v[140:141], s[18:19], 0, v[130:131]
	s_add_i32 m0, s28, 0x2000
	s_nop 0
	global_load_lds_dwordx4 v[140:141], off
	v_lshl_add_u64 v[140:141], v[216:217], 0, s[6:7]
	s_mov_b32 m0, s48
	s_nop 0
	global_load_lds_dwordx4 v[140:141], off
	v_lshl_add_u64 v[140:141], v[218:219], 0, s[6:7]
	s_mov_b32 m0, s49
	s_nop 0
	global_load_lds_dwordx4 v[140:141], off
	s_waitcnt vmcnt(8)
	s_waitcnt lgkmcnt(0)
	s_setprio 3
	s_barrier
	v_mfma_f32_16x16x32_bf16 v[62:65], v[146:149], v[184:187], v[62:65]
	v_mfma_f32_16x16x32_bf16 v[54:57], v[154:157], v[184:187], v[54:57]
	v_mfma_f32_16x16x32_bf16 v[46:49], v[146:149], v[192:195], v[46:49]
	v_mfma_f32_16x16x32_bf16 v[38:41], v[154:157], v[192:195], v[38:41]
	v_mfma_f32_16x16x32_bf16 v[30:33], v[146:149], v[200:203], v[30:33]
	v_mfma_f32_16x16x32_bf16 v[22:25], v[154:157], v[200:203], v[22:25]
	v_mfma_f32_16x16x32_bf16 v[14:17], v[146:149], v[208:211], v[14:17]
	v_mfma_f32_16x16x32_bf16 v[6:9], v[154:157], v[208:211], v[6:9]
	v_mfma_f32_16x16x32_bf16 v[62:65], v[150:153], v[188:191], v[62:65]
	v_mfma_f32_16x16x32_bf16 v[54:57], v[158:161], v[188:191], v[54:57]
	v_mfma_f32_16x16x32_bf16 v[46:49], v[150:153], v[196:199], v[46:49]
	v_mfma_f32_16x16x32_bf16 v[38:41], v[158:161], v[196:199], v[38:41]
	v_mfma_f32_16x16x32_bf16 v[30:33], v[150:153], v[204:207], v[30:33]
	v_mfma_f32_16x16x32_bf16 v[22:25], v[158:161], v[204:207], v[22:25]
	v_mfma_f32_16x16x32_bf16 v[14:17], v[150:153], v[212:215], v[14:17]
	v_mfma_f32_16x16x32_bf16 v[6:9], v[158:161], v[212:215], v[6:9]
	v_mfma_f32_16x16x32_bf16 v[58:61], v[162:165], v[184:187], v[58:61]
	v_mfma_f32_16x16x32_bf16 v[50:53], v[170:173], v[184:187], v[50:53]
	v_mfma_f32_16x16x32_bf16 v[42:45], v[162:165], v[192:195], v[42:45]
	v_mfma_f32_16x16x32_bf16 v[34:37], v[170:173], v[192:195], v[34:37]
	v_mfma_f32_16x16x32_bf16 v[26:29], v[162:165], v[200:203], v[26:29]
	v_mfma_f32_16x16x32_bf16 v[18:21], v[170:173], v[200:203], v[18:21]
	v_mfma_f32_16x16x32_bf16 v[10:13], v[162:165], v[208:211], v[10:13]
	v_mfma_f32_16x16x32_bf16 v[2:5], v[170:173], v[208:211], v[2:5]
	v_mfma_f32_16x16x32_bf16 v[58:61], v[166:169], v[188:191], v[58:61]
	v_mfma_f32_16x16x32_bf16 v[50:53], v[180:183], v[188:191], v[50:53]
	v_mfma_f32_16x16x32_bf16 v[42:45], v[166:169], v[196:199], v[42:45]
	v_mfma_f32_16x16x32_bf16 v[34:37], v[180:183], v[196:199], v[34:37]
	v_mfma_f32_16x16x32_bf16 v[26:29], v[166:169], v[204:207], v[26:29]
	v_mfma_f32_16x16x32_bf16 v[18:21], v[180:183], v[204:207], v[18:21]
	v_mfma_f32_16x16x32_bf16 v[10:13], v[166:169], v[212:215], v[10:13]
	v_mfma_f32_16x16x32_bf16 v[2:5], v[180:183], v[212:215], v[2:5]
	s_barrier
	s_setprio 0
	s_add_i32 s53, s53, 2
	s_add_u32 s44, s44, 0x100
	s_addc_u32 s45, s45, 0
	s_cmp_gt_u32 s53, 29
	s_mov_b64 s[18:19], s[24:25]
	s_cbranch_scc0 .LBB0_485
	v_readlane_b32 s6, v252, 14
	v_readlane_b32 s7, v252, 15
	s_and_b64 vcc, exec, s[6:7]
	s_cbranch_vccz .LBB0_488
	s_barrier

; #define PG8_STAGE(bufoff, gbase, voff) do { _Pragma("unroll") for (int _i = 0; _i < 2; ++_i) \
;         __builtin_amdgcn_global_load_lds((const unsigned*)((const char*)(gbase) + (voff)[_i]), (LAS unsigned*)(lds + (bufoff) + ldsw + _i * 8192), 16, 0, 0); } while (0)
; #define PG8_LDA(dst, b, h) do { _Pragma("unroll") for (int m = 0; m < 4; ++m) _Pragma("unroll") for (int k = 0; k < 2; ++k) dst[m][k] = *(const LAS bf16x8*)(lds + PG8_SA(b, h) + aoff + m * 2048 + k * 1024); } while (0)
; #define PG8_LDB(dst, b, h) do { _Pragma("unroll") for (int n = 0; n < 2; ++n) _Pragma("unroll") for (int k = 0; k < 2; ++k) dst[n][k] = *(const LAS bf16x8*)(lds + PG8_SB(b, h) + boff + n * 2048 + k * 1024); } while (0)
; #define PG8_MMA(ai, bj, At, Bt) do { __builtin_amdgcn_s_setprio(1); _Pragma("unroll") for (int m = 0; m < 4; ++m) _Pragma("unroll") for (int n = 0; n < 2; ++n) _Pragma("unroll") for (int k = 0; k < 2; ++k) \
;         acc[ai][bj][m][n] = __builtin_amdgcn_mfma_f32_16x16x32_bf16(Bt[n][k], At[m][k], acc[ai][bj][m][n], 0, 0, 0); __builtin_amdgcn_s_setprio(0); } while (0)
; #define PG8_WAIT_V(n) asm volatile("s_waitcnt vmcnt(" #n ")" ::: "memory")
; #define PG8_WAIT_L(n) asm volatile("s_waitcnt lgkmcnt(" #n ")" ::: "memory")
; #define PG8_BAR __builtin_amdgcn_s_barrier()
; template <class Epi, class Sched, int LDA, int LDB, bool ALIGN_EPI = true>
; __device__ __forceinline__ void gemm_phase(LAS unsigned char* lds, const Gemm g, const Sched& S, const Epi& E, int wave) {
;     ...
;         for (int t = 0; t < nt; t += 2) {
;             const bool last = (t == nt - 2);
;             const char* a1 = cA + (size_t)(t + 1) * kstep;
;             const char* a2 = last ? nA : cA + (size_t)(t + 2) * kstep; const char* b2 = last ? nB : cB + (size_t)(t + 2) * kstep;
;             const char* a3 = a2 + kstep; const char* b3 = b2 + kstep;
;             PG8_LDB(B0, 0, 0); PG8_LDB(B1, 0, 1); PG8_SCHED; PG8_LDA(At, 0, 0); PG8_STAGE(PG8_SA(1, 1), a1 + hstepA, voffA);
;             PG8_WAIT_V(8); PG8_WAIT_L(0); PG8_BAR; PG8_MMA(0, 0, At, B0); PG8_MMA(0, 1, At, B1); PG8_BAR; PG8_SCHED;
;             PG8_LDA(At, 0, 1); PG8_STAGE(PG8_SB(0, 0), b2, voffB); PG8_STAGE(PG8_SB(0, 1), b2 + hstepB, voffB); PG8_STAGE(PG8_SA(0, 0), a2, voffA);
;             PG8_WAIT_V(8); PG8_WAIT_L(0); PG8_BAR; PG8_MMA(1, 0, At, B0); PG8_MMA(1, 1, At, B1); PG8_BAR; PG8_SCHED;
.LBB0_1893:
	s_add_i32 s79, s46, 2
	s_add_u32 s38, s36, 0x100
	s_addc_u32 s39, s37, 0
	s_add_i32 s82, 0, 0x10000
	s_cmp_eq_u32 s25, s46
	s_cselect_b32 s49, s29, s39
	s_cselect_b32 s48, s28, s38
	s_cselect_b32 s47, s35, s78
	s_cselect_b32 s46, s34, s77
	s_add_i32 s85, 0, 0x14000
	v_add_u32_e32 v152, s82, v249
	v_add_u32_e32 v168, s85, v249
	ds_read_b128 v[130:133], v152
	ds_read_b128 v[134:137], v152 offset:1024
	ds_read_b128 v[148:151], v152 offset:2048
	ds_read_b128 v[152:155], v152 offset:3072
	ds_read_b128 v[156:159], v168
	ds_read_b128 v[160:163], v168 offset:1024
	ds_read_b128 v[164:167], v168 offset:2048
	ds_read_b128 v[168:171], v168 offset:3072
	v_lshl_add_u64 v[208:209], s[36:37], 0, v[144:145]
	s_add_i32 m0, s50, 0xc000
	ds_read_b128 v[172:175], v236
	ds_read_b128 v[180:183], v236 offset:1024
	ds_read_b128 v[184:187], v236 offset:2048
	ds_read_b128 v[188:191], v236 offset:3072
	ds_read_b128 v[192:195], v236 offset:4096
	ds_read_b128 v[196:199], v236 offset:5120
	ds_read_b128 v[200:203], v236 offset:6144
	ds_read_b128 v[204:207], v236 offset:7168
	global_load_lds_dwordx4 v[208:209], off
	v_lshl_add_u64 v[208:209], s[36:37], 0, v[146:147]
	s_add_i32 m0, s50, 0xe000
	s_nop 0
	global_load_lds_dwordx4 v[208:209], off
	s_waitcnt vmcnt(8)
	s_waitcnt lgkmcnt(0)
	s_setprio 3
	s_barrier
	v_mfma_f32_16x16x32_bf16 v[126:129], v[130:133], v[172:175], v[126:129]
	v_mfma_f32_16x16x32_bf16 v[122:125], v[148:151], v[172:175], v[122:125]
	v_mfma_f32_16x16x32_bf16 v[110:113], v[130:133], v[184:187], v[110:113]
	v_mfma_f32_16x16x32_bf16 v[106:109], v[148:151], v[184:187], v[106:109]
	v_mfma_f32_16x16x32_bf16 v[94:97], v[130:133], v[192:195], v[94:97]
	v_mfma_f32_16x16x32_bf16 v[90:93], v[148:151], v[192:195], v[90:93]
	v_mfma_f32_16x16x32_bf16 v[78:81], v[130:133], v[200:203], v[78:81]
	v_mfma_f32_16x16x32_bf16 v[74:77], v[148:151], v[200:203], v[74:77]
	v_mfma_f32_16x16x32_bf16 v[126:129], v[134:137], v[180:183], v[126:129]
	v_mfma_f32_16x16x32_bf16 v[122:125], v[152:155], v[180:183], v[122:125]
	v_mfma_f32_16x16x32_bf16 v[110:113], v[134:137], v[188:191], v[110:113]
	v_mfma_f32_16x16x32_bf16 v[106:109], v[152:155], v[188:191], v[106:109]
	v_mfma_f32_16x16x32_bf16 v[94:97], v[134:137], v[196:199], v[94:97]
	v_mfma_f32_16x16x32_bf16 v[90:93], v[152:155], v[196:199], v[90:93]
	v_mfma_f32_16x16x32_bf16 v[78:81], v[134:137], v[204:207], v[78:81]
	v_mfma_f32_16x16x32_bf16 v[74:77], v[152:155], v[204:207], v[74:77]
	v_mfma_f32_16x16x32_bf16 v[118:121], v[156:159], v[172:175], v[118:121]
	v_mfma_f32_16x16x32_bf16 v[114:117], v[164:167], v[172:175], v[114:117]
	v_mfma_f32_16x16x32_bf16 v[102:105], v[156:159], v[184:187], v[102:105]
	v_mfma_f32_16x16x32_bf16 v[98:101], v[164:167], v[184:187], v[98:101]
	v_mfma_f32_16x16x32_bf16 v[86:89], v[156:159], v[192:195], v[86:89]
	v_mfma_f32_16x16x32_bf16 v[82:85], v[164:167], v[192:195], v[82:85]
	v_mfma_f32_16x16x32_bf16 v[70:73], v[156:159], v[200:203], v[70:73]
	v_mfma_f32_16x16x32_bf16 v[66:69], v[164:167], v[200:203], v[66:69]
	v_mfma_f32_16x16x32_bf16 v[118:121], v[160:163], v[180:183], v[118:121]
	v_mfma_f32_16x16x32_bf16 v[114:117], v[168:171], v[180:183], v[114:117]
	v_mfma_f32_16x16x32_bf16 v[102:105], v[160:163], v[188:191], v[102:105]
	v_mfma_f32_16x16x32_bf16 v[98:101], v[168:171], v[188:191], v[98:101]
	v_mfma_f32_16x16x32_bf16 v[86:89], v[160:163], v[196:199], v[86:89]
	v_mfma_f32_16x16x32_bf16 v[82:85], v[168:171], v[196:199], v[82:85]
	v_mfma_f32_16x16x32_bf16 v[70:73], v[160:163], v[204:207], v[70:73]
	v_mfma_f32_16x16x32_bf16 v[66:69], v[168:171], v[204:207], v[66:69]
	s_barrier
	s_setprio 0
	s_add_i32 s36, s82, s2
	v_lshl_add_u64 v[208:209], s[46:47], 0, v[0:1]
	s_mov_b32 m0, s36
	ds_read_b128 v[172:175], v236 offset:16384
	ds_read_b128 v[180:183], v236 offset:17408
	ds_read_b128 v[184:187], v236 offset:18432
	ds_read_b128 v[188:191], v236 offset:19456
	ds_read_b128 v[192:195], v236 offset:20480
	ds_read_b128 v[196:199], v236 offset:21504
	ds_read_b128 v[200:203], v236 offset:22528
	ds_read_b128 v[204:207], v236 offset:23552
	global_load_lds_dwordx4 v[208:209], off
	s_add_i32 m0, s36, 0x2000
	s_add_u32 s36, s46, 0x160000
	v_lshl_add_u64 v[210:211], s[46:47], 0, v[142:143]
	s_addc_u32 s37, s47, 0
	s_add_i32 s82, s85, s2
	global_load_lds_dwordx4 v[210:211], off
	v_lshl_add_u64 v[212:213], s[36:37], 0, v[0:1]
	s_mov_b32 m0, s82
	v_lshl_add_u64 v[214:215], s[48:49], 0, v[140:141]
	global_load_lds_dwordx4 v[212:213], off
	v_lshl_add_u64 v[212:213], s[36:37], 0, v[142:143]
	s_add_i32 m0, s82, 0x2000
	s_nop 0
	global_load_lds_dwordx4 v[212:213], off
	v_lshl_add_u64 v[212:213], s[48:49], 0, v[138:139]
	s_mov_b32 m0, s50
	s_nop 0
	global_load_lds_dwordx4 v[212:213], off
	s_mov_b32 m0, s51
	s_nop 0
	global_load_lds_dwordx4 v[214:215], off
	s_waitcnt vmcnt(8)
	s_waitcnt lgkmcnt(0)
	s_setprio 3
	s_barrier
; #define PG8_STAGE(bufoff, gbase, voff) do { _Pragma("unroll") for (int _i = 0; _i < 2; ++_i) \
;         __builtin_amdgcn_global_load_lds((const unsigned*)((const char*)(gbase) + (voff)[_i]), (LAS unsigned*)(lds + (bufoff) + ldsw + _i * 8192), 16, 0, 0); } while (0)
; #define PG8_LDA(dst, b, h) do { _Pragma("unroll") for (int m = 0; m < 4; ++m) _Pragma("unroll") for (int k = 0; k < 2; ++k) dst[m][k] = *(const LAS bf16x8*)(lds + PG8_SA(b, h) + aoff + m * 2048 + k * 1024); } while (0)
; #define PG8_LDB(dst, b, h) do { _Pragma("unroll") for (int n = 0; n < 2; ++n) _Pragma("unroll") for (int k = 0; k < 2; ++k) dst[n][k] = *(const LAS bf16x8*)(lds + PG8_SB(b, h) + boff + n * 2048 + k * 1024); } while (0)
; #define PG8_MMA(ai, bj, At, Bt) do { __builtin_amdgcn_s_setprio(1); _Pragma("unroll") for (int m = 0; m < 4; ++m) _Pragma("unroll") for (int n = 0; n < 2; ++n) _Pragma("unroll") for (int k = 0; k < 2; ++k) \
;         acc[ai][bj][m][n] = __builtin_amdgcn_mfma_f32_16x16x32_bf16(Bt[n][k], At[m][k], acc[ai][bj][m][n], 0, 0, 0); __builtin_amdgcn_s_setprio(0); } while (0)
; #define PG8_WAIT_V(n) asm volatile("s_waitcnt vmcnt(" #n ")" ::: "memory")
; #define PG8_WAIT_L(n) asm volatile("s_waitcnt lgkmcnt(" #n ")" ::: "memory")
; #define PG8_BAR __builtin_amdgcn_s_barrier()
; #define PG8_SCHED __builtin_amdgcn_sched_barrier(0)
; template <class Epi, class Sched, int LDA, int LDB, bool ALIGN_EPI = true>
; __device__ __forceinline__ void gemm_phase(LAS unsigned char* lds, const Gemm g, const Sched& S, const Epi& E, int wave) {
;     ...
;             PG8_WAIT_V(8); PG8_WAIT_L(0); PG8_BAR; PG8_MMA(1, 0, At, B0); PG8_MMA(1, 1, At, B1); PG8_BAR; PG8_SCHED;
;             PG8_LDB(B0, 1, 0); PG8_LDB(B1, 1, 1); PG8_SCHED; PG8_LDA(At, 1, 0); PG8_STAGE(PG8_SA(0, 1), a2 + hstepA, voffA);
;             PG8_WAIT_V(8); PG8_WAIT_L(0); PG8_BAR; PG8_MMA(0, 0, At, B0); PG8_MMA(0, 1, At, B1); PG8_BAR; PG8_SCHED;
	v_mfma_f32_16x16x32_bf16 v[62:65], v[130:133], v[172:175], v[62:65]
	v_mfma_f32_16x16x32_bf16 v[58:61], v[148:151], v[172:175], v[58:61]
	v_mfma_f32_16x16x32_bf16 v[46:49], v[130:133], v[184:187], v[46:49]
	v_mfma_f32_16x16x32_bf16 v[42:45], v[148:151], v[184:187], v[42:45]
	v_mfma_f32_16x16x32_bf16 v[30:33], v[130:133], v[192:195], v[30:33]
	v_mfma_f32_16x16x32_bf16 v[26:29], v[148:151], v[192:195], v[26:29]
	v_mfma_f32_16x16x32_bf16 v[14:17], v[130:133], v[200:203], v[14:17]
	v_mfma_f32_16x16x32_bf16 v[10:13], v[148:151], v[200:203], v[10:13]
	v_mfma_f32_16x16x32_bf16 v[62:65], v[134:137], v[180:183], v[62:65]
	v_mfma_f32_16x16x32_bf16 v[58:61], v[152:155], v[180:183], v[58:61]
	v_mfma_f32_16x16x32_bf16 v[46:49], v[134:137], v[188:191], v[46:49]
	v_mfma_f32_16x16x32_bf16 v[42:45], v[152:155], v[188:191], v[42:45]
	v_mfma_f32_16x16x32_bf16 v[30:33], v[134:137], v[196:199], v[30:33]
	v_mfma_f32_16x16x32_bf16 v[26:29], v[152:155], v[196:199], v[26:29]
	v_mfma_f32_16x16x32_bf16 v[14:17], v[134:137], v[204:207], v[14:17]
	v_mfma_f32_16x16x32_bf16 v[10:13], v[152:155], v[204:207], v[10:13]
	v_mfma_f32_16x16x32_bf16 v[54:57], v[156:159], v[172:175], v[54:57]
	v_mfma_f32_16x16x32_bf16 v[50:53], v[164:167], v[172:175], v[50:53]
	v_mfma_f32_16x16x32_bf16 v[38:41], v[156:159], v[184:187], v[38:41]
	v_mfma_f32_16x16x32_bf16 v[34:37], v[164:167], v[184:187], v[34:37]
	v_mfma_f32_16x16x32_bf16 v[22:25], v[156:159], v[192:195], v[22:25]
	v_mfma_f32_16x16x32_bf16 v[18:21], v[164:167], v[192:195], v[18:21]
	v_mfma_f32_16x16x32_bf16 v[6:9], v[156:159], v[200:203], v[6:9]
	v_mfma_f32_16x16x32_bf16 v[2:5], v[164:167], v[200:203], v[2:5]
	v_mfma_f32_16x16x32_bf16 v[54:57], v[160:163], v[180:183], v[54:57]
	v_mfma_f32_16x16x32_bf16 v[50:53], v[168:171], v[180:183], v[50:53]
	v_mfma_f32_16x16x32_bf16 v[38:41], v[160:163], v[188:191], v[38:41]
	v_mfma_f32_16x16x32_bf16 v[34:37], v[168:171], v[188:191], v[34:37]
	v_mfma_f32_16x16x32_bf16 v[22:25], v[160:163], v[196:199], v[22:25]
	v_mfma_f32_16x16x32_bf16 v[18:21], v[168:171], v[196:199], v[18:21]
	v_mfma_f32_16x16x32_bf16 v[6:9], v[160:163], v[204:207], v[6:9]
	v_mfma_f32_16x16x32_bf16 v[2:5], v[168:171], v[204:207], v[2:5]
	s_barrier
	s_setprio 0
	s_add_i32 s82, 0, 0x18000
	s_add_i32 s85, 0, 0x1c000
	v_add_u32_e32 v152, s82, v249
	v_add_u32_e32 v168, s85, v249
	ds_read_b128 v[130:133], v152
	ds_read_b128 v[134:137], v152 offset:1024
	ds_read_b128 v[148:151], v152 offset:2048
	ds_read_b128 v[152:155], v152 offset:3072
	ds_read_b128 v[156:159], v168
	ds_read_b128 v[160:163], v168 offset:1024
	ds_read_b128 v[164:167], v168 offset:2048
	ds_read_b128 v[168:171], v168 offset:3072
	s_add_u32 s36, s48, 0x160000
	s_addc_u32 s37, s49, 0
	s_mov_b32 m0, s52
	v_lshl_add_u64 v[216:217], s[36:37], 0, v[138:139]
	ds_read_b128 v[172:175], v236 offset:32768
	ds_read_b128 v[180:183], v236 offset:33792
	ds_read_b128 v[184:187], v236 offset:34816
	ds_read_b128 v[188:191], v236 offset:35840
	ds_read_b128 v[192:195], v236 offset:36864
	ds_read_b128 v[196:199], v236 offset:37888
	ds_read_b128 v[200:203], v236 offset:38912
	ds_read_b128 v[204:207], v236 offset:39936
	global_load_lds_dwordx4 v[216:217], off
	v_lshl_add_u64 v[216:217], s[36:37], 0, v[140:141]
	s_mov_b32 m0, s53
	s_nop 0
	global_load_lds_dwordx4 v[216:217], off
	s_waitcnt vmcnt(8)
	s_waitcnt lgkmcnt(0)
	s_setprio 3
	s_barrier
	v_mfma_f32_16x16x32_bf16 v[126:129], v[130:133], v[172:175], v[126:129]
	v_mfma_f32_16x16x32_bf16 v[122:125], v[148:151], v[172:175], v[122:125]
	v_mfma_f32_16x16x32_bf16 v[110:113], v[130:133], v[184:187], v[110:113]
	v_mfma_f32_16x16x32_bf16 v[106:109], v[148:151], v[184:187], v[106:109]
	v_mfma_f32_16x16x32_bf16 v[94:97], v[130:133], v[192:195], v[94:97]
	v_mfma_f32_16x16x32_bf16 v[90:93], v[148:151], v[192:195], v[90:93]
	v_mfma_f32_16x16x32_bf16 v[78:81], v[130:133], v[200:203], v[78:81]
	v_mfma_f32_16x16x32_bf16 v[74:77], v[148:151], v[200:203], v[74:77]
	v_mfma_f32_16x16x32_bf16 v[126:129], v[134:137], v[180:183], v[126:129]
	v_mfma_f32_16x16x32_bf16 v[122:125], v[152:155], v[180:183], v[122:125]
	v_mfma_f32_16x16x32_bf16 v[110:113], v[134:137], v[188:191], v[110:113]
	v_mfma_f32_16x16x32_bf16 v[106:109], v[152:155], v[188:191], v[106:109]
	v_mfma_f32_16x16x32_bf16 v[94:97], v[134:137], v[196:199], v[94:97]
	v_mfma_f32_16x16x32_bf16 v[90:93], v[152:155], v[196:199], v[90:93]
	v_mfma_f32_16x16x32_bf16 v[78:81], v[134:137], v[204:207], v[78:81]
	v_mfma_f32_16x16x32_bf16 v[74:77], v[152:155], v[204:207], v[74:77]
	v_mfma_f32_16x16x32_bf16 v[118:121], v[156:159], v[172:175], v[118:121]
	v_mfma_f32_16x16x32_bf16 v[114:117], v[164:167], v[172:175], v[114:117]
	v_mfma_f32_16x16x32_bf16 v[102:105], v[156:159], v[184:187], v[102:105]
	v_mfma_f32_16x16x32_bf16 v[98:101], v[164:167], v[184:187], v[98:101]
	v_mfma_f32_16x16x32_bf16 v[86:89], v[156:159], v[192:195], v[86:89]
	v_mfma_f32_16x16x32_bf16 v[82:85], v[164:167], v[192:195], v[82:85]
	v_mfma_f32_16x16x32_bf16 v[70:73], v[156:159], v[200:203], v[70:73]
	v_mfma_f32_16x16x32_bf16 v[66:69], v[164:167], v[200:203], v[66:69]
	v_mfma_f32_16x16x32_bf16 v[118:121], v[160:163], v[180:183], v[118:121]
	v_mfma_f32_16x16x32_bf16 v[114:117], v[168:171], v[180:183], v[114:117]
	v_mfma_f32_16x16x32_bf16 v[102:105], v[160:163], v[188:191], v[102:105]
	v_mfma_f32_16x16x32_bf16 v[98:101], v[168:171], v[188:191], v[98:101]
	v_mfma_f32_16x16x32_bf16 v[86:89], v[160:163], v[196:199], v[86:89]
	v_mfma_f32_16x16x32_bf16 v[82:85], v[168:171], v[196:199], v[82:85]
	v_mfma_f32_16x16x32_bf16 v[70:73], v[160:163], v[204:207], v[70:73]
	v_mfma_f32_16x16x32_bf16 v[66:69], v[168:171], v[204:207], v[66:69]
	s_barrier
; #define PG8_STAGE(bufoff, gbase, voff) do { _Pragma("unroll") for (int _i = 0; _i < 2; ++_i) \
;         __builtin_amdgcn_global_load_lds((const unsigned*)((const char*)(gbase) + (voff)[_i]), (LAS unsigned*)(lds + (bufoff) + ldsw + _i * 8192), 16, 0, 0); } while (0)
; #define PG8_LDA(dst, b, h) do { _Pragma("unroll") for (int m = 0; m < 4; ++m) _Pragma("unroll") for (int k = 0; k < 2; ++k) dst[m][k] = *(const LAS bf16x8*)(lds + PG8_SA(b, h) + aoff + m * 2048 + k * 1024); } while (0)
; #define PG8_MMA(ai, bj, At, Bt) do { __builtin_amdgcn_s_setprio(1); _Pragma("unroll") for (int m = 0; m < 4; ++m) _Pragma("unroll") for (int n = 0; n < 2; ++n) _Pragma("unroll") for (int k = 0; k < 2; ++k) \
;         acc[ai][bj][m][n] = __builtin_amdgcn_mfma_f32_16x16x32_bf16(Bt[n][k], At[m][k], acc[ai][bj][m][n], 0, 0, 0); __builtin_amdgcn_s_setprio(0); } while (0)
; #define PG8_WAIT_V(n) asm volatile("s_waitcnt vmcnt(" #n ")" ::: "memory")
; #define PG8_WAIT_L(n) asm volatile("s_waitcnt lgkmcnt(" #n ")" ::: "memory")
; #define PG8_BAR __builtin_amdgcn_s_barrier()
; #define PG8_SCHED __builtin_amdgcn_sched_barrier(0)
; template <class Epi, class Sched, int LDA, int LDB, bool ALIGN_EPI = true>
; __device__ __forceinline__ void gemm_phase(LAS unsigned char* lds, const Gemm g, const Sched& S, const Epi& E, int wave) {
;     ...
;             PG8_LDA(At, 1, 1); PG8_STAGE(PG8_SB(1, 0), b3, voffB); PG8_STAGE(PG8_SB(1, 1), b3 + hstepB, voffB); PG8_STAGE(PG8_SA(1, 0), a3, voffA);
;             PG8_WAIT_V(8); PG8_WAIT_L(0); PG8_BAR; PG8_MMA(1, 0, At, B0); PG8_MMA(1, 1, At, B1); PG8_BAR; PG8_SCHED;
;         }
;         if constexpr (ALIGN_EPI) { if (wr == 0) PG8_BAR; }
	s_setprio 0
	s_add_i32 s36, s82, s2
	v_lshl_add_u64 v[208:209], v[208:209], 0, s[8:9]
	s_mov_b32 m0, s36
	ds_read_b128 v[172:175], v236 offset:49152
	ds_read_b128 v[180:183], v236 offset:50176
	ds_read_b128 v[184:187], v236 offset:51200
	ds_read_b128 v[188:191], v236 offset:52224
	ds_read_b128 v[192:195], v236 offset:53248
	ds_read_b128 v[196:199], v236 offset:54272
	ds_read_b128 v[200:203], v236 offset:55296
	ds_read_b128 v[204:207], v236 offset:56320
	global_load_lds_dwordx4 v[208:209], off
	s_add_i32 m0, s36, 0x2000
	s_add_u32 s36, s46, 0x160080
	v_lshl_add_u64 v[208:209], v[210:211], 0, s[8:9]
	s_addc_u32 s37, s47, 0
	s_add_i32 s46, s85, s2
	global_load_lds_dwordx4 v[208:209], off
	v_lshl_add_u64 v[208:209], s[36:37], 0, v[0:1]
	s_mov_b32 m0, s46
	s_nop 0
	global_load_lds_dwordx4 v[208:209], off
	v_lshl_add_u64 v[208:209], s[36:37], 0, v[142:143]
	s_add_i32 m0, s46, 0x2000
	s_nop 0
	global_load_lds_dwordx4 v[208:209], off
	v_lshl_add_u64 v[208:209], v[212:213], 0, s[8:9]
	s_mov_b32 m0, s5
	s_nop 0
	global_load_lds_dwordx4 v[208:209], off
	v_lshl_add_u64 v[208:209], v[214:215], 0, s[8:9]
	s_mov_b32 m0, s59
	s_nop 0
	global_load_lds_dwordx4 v[208:209], off
	s_waitcnt vmcnt(8)
	s_waitcnt lgkmcnt(0)
	s_setprio 3
	s_barrier
	v_mfma_f32_16x16x32_bf16 v[62:65], v[130:133], v[172:175], v[62:65]
	v_mfma_f32_16x16x32_bf16 v[58:61], v[148:151], v[172:175], v[58:61]
	v_mfma_f32_16x16x32_bf16 v[46:49], v[130:133], v[184:187], v[46:49]
	v_mfma_f32_16x16x32_bf16 v[42:45], v[148:151], v[184:187], v[42:45]
	v_mfma_f32_16x16x32_bf16 v[30:33], v[130:133], v[192:195], v[30:33]
	v_mfma_f32_16x16x32_bf16 v[26:29], v[148:151], v[192:195], v[26:29]
	v_mfma_f32_16x16x32_bf16 v[14:17], v[130:133], v[200:203], v[14:17]
	v_mfma_f32_16x16x32_bf16 v[10:13], v[148:151], v[200:203], v[10:13]
	v_mfma_f32_16x16x32_bf16 v[62:65], v[134:137], v[180:183], v[62:65]
	v_mfma_f32_16x16x32_bf16 v[58:61], v[152:155], v[180:183], v[58:61]
	v_mfma_f32_16x16x32_bf16 v[46:49], v[134:137], v[188:191], v[46:49]
	v_mfma_f32_16x16x32_bf16 v[42:45], v[152:155], v[188:191], v[42:45]
	v_mfma_f32_16x16x32_bf16 v[30:33], v[134:137], v[196:199], v[30:33]
	v_mfma_f32_16x16x32_bf16 v[26:29], v[152:155], v[196:199], v[26:29]
	v_mfma_f32_16x16x32_bf16 v[14:17], v[134:137], v[204:207], v[14:17]
	v_mfma_f32_16x16x32_bf16 v[10:13], v[152:155], v[204:207], v[10:13]
	v_mfma_f32_16x16x32_bf16 v[54:57], v[156:159], v[172:175], v[54:57]
	v_mfma_f32_16x16x32_bf16 v[50:53], v[164:167], v[172:175], v[50:53]
	v_mfma_f32_16x16x32_bf16 v[38:41], v[156:159], v[184:187], v[38:41]
	v_mfma_f32_16x16x32_bf16 v[34:37], v[164:167], v[184:187], v[34:37]
	v_mfma_f32_16x16x32_bf16 v[22:25], v[156:159], v[192:195], v[22:25]
	v_mfma_f32_16x16x32_bf16 v[18:21], v[164:167], v[192:195], v[18:21]
	v_mfma_f32_16x16x32_bf16 v[6:9], v[156:159], v[200:203], v[6:9]
	v_mfma_f32_16x16x32_bf16 v[2:5], v[164:167], v[200:203], v[2:5]
	v_mfma_f32_16x16x32_bf16 v[54:57], v[160:163], v[180:183], v[54:57]
	v_mfma_f32_16x16x32_bf16 v[50:53], v[168:171], v[180:183], v[50:53]
	v_mfma_f32_16x16x32_bf16 v[38:41], v[160:163], v[188:191], v[38:41]
	v_mfma_f32_16x16x32_bf16 v[34:37], v[168:171], v[188:191], v[34:37]
	v_mfma_f32_16x16x32_bf16 v[22:25], v[160:163], v[196:199], v[22:25]
	v_mfma_f32_16x16x32_bf16 v[18:21], v[168:171], v[196:199], v[18:21]
	v_mfma_f32_16x16x32_bf16 v[6:9], v[160:163], v[204:207], v[6:9]
	v_mfma_f32_16x16x32_bf16 v[2:5], v[168:171], v[204:207], v[2:5]
	s_barrier
	s_setprio 0
	s_add_u32 s77, s77, 0x100
	s_addc_u32 s78, s78, 0
	s_cmp_ge_i32 s79, s75
	s_mov_b64 s[36:37], s[38:39]
	s_mov_b32 s46, s79
	s_cbranch_scc0 .LBB0_1893
	v_readlane_b32 s2, v252, 14
	v_readlane_b32 s3, v252, 15
	s_and_b64 vcc, exec, s[2:3]
	s_cbranch_vccz .LBB0_1896
	s_barrier

; #define PG8_STAGE(bufoff, gbase, voff) do { _Pragma("unroll") for (int _i = 0; _i < 2; ++_i) \
;         __builtin_amdgcn_global_load_lds((const unsigned*)((const char*)(gbase) + (voff)[_i]), (LAS unsigned*)(lds + (bufoff) + ldsw + _i * 8192), 16, 0, 0); } while (0)
; #define PG8_LDA(dst, b, h) do { _Pragma("unroll") for (int m = 0; m < 4; ++m) _Pragma("unroll") for (int k = 0; k < 2; ++k) dst[m][k] = *(const LAS bf16x8*)(lds + PG8_SA(b, h) + aoff + m * 2048 + k * 1024); } while (0)
; #define PG8_LDB(dst, b, h) do { _Pragma("unroll") for (int n = 0; n < 2; ++n) _Pragma("unroll") for (int k = 0; k < 2; ++k) dst[n][k] = *(const LAS bf16x8*)(lds + PG8_SB(b, h) + boff + n * 2048 + k * 1024); } while (0)
; #define PG8_MMA(ai, bj, At, Bt) do { __builtin_amdgcn_s_setprio(1); _Pragma("unroll") for (int m = 0; m < 4; ++m) _Pragma("unroll") for (int n = 0; n < 2; ++n) _Pragma("unroll") for (int k = 0; k < 2; ++k) \
;         acc[ai][bj][m][n] = __builtin_amdgcn_mfma_f32_16x16x32_bf16(Bt[n][k], At[m][k], acc[ai][bj][m][n], 0, 0, 0); __builtin_amdgcn_s_setprio(0); } while (0)
; #define PG8_WAIT_V(n) asm volatile("s_waitcnt vmcnt(" #n ")" ::: "memory")
; #define PG8_WAIT_L(n) asm volatile("s_waitcnt lgkmcnt(" #n ")" ::: "memory")
; #define PG8_BAR __builtin_amdgcn_s_barrier()
; template <class Epi, class Sched, int LDA, int LDB, bool ALIGN_EPI = true>
; __device__ __forceinline__ void gemm_phase(LAS unsigned char* lds, const Gemm g, const Sched& S, const Epi& E, int wave) {
;     ...
;         for (int t = 0; t < nt; t += 2) {
;             const bool last = (t == nt - 2);
;             const char* a1 = cA + (size_t)(t + 1) * kstep;
;             const char* a2 = last ? nA : cA + (size_t)(t + 2) * kstep; const char* b2 = last ? nB : cB + (size_t)(t + 2) * kstep;
;             const char* a3 = a2 + kstep; const char* b3 = b2 + kstep;
;             PG8_LDB(B0, 0, 0); PG8_LDB(B1, 0, 1); PG8_SCHED; PG8_LDA(At, 0, 0); PG8_STAGE(PG8_SA(1, 1), a1 + hstepA, voffA);
;             PG8_WAIT_V(8); PG8_WAIT_L(0); PG8_BAR; PG8_MMA(0, 0, At, B0); PG8_MMA(0, 1, At, B1); PG8_BAR; PG8_SCHED;
;             PG8_LDA(At, 0, 1); PG8_STAGE(PG8_SB(0, 0), b2, voffB); PG8_STAGE(PG8_SB(0, 1), b2 + hstepB, voffB); PG8_STAGE(PG8_SA(0, 0), a2, voffA);
;             PG8_WAIT_V(8); PG8_WAIT_L(0); PG8_BAR; PG8_MMA(1, 0, At, B0); PG8_MMA(1, 1, At, B1); PG8_BAR; PG8_SCHED;
.LBB0_2254:
	s_add_u32 s2, s0, 0x100
	s_addc_u32 s3, s1, 0
	s_add_i32 s64, 0, 0x10000
	s_cmp_eq_u32 s59, 28
	s_cselect_b32 s29, s15, s3
	s_cselect_b32 s28, s14, s2
	v_add_u32_e32 v0, s64, v161
	s_cselect_b32 s25, s13, s58
	s_cselect_b32 s24, s48, s49
	s_add_i32 s65, 0, 0x14000
	ds_read_b128 v[144:147], v0
	ds_read_b128 v[148:151], v0 offset:1024
	ds_read_b128 v[152:155], v0 offset:2048
	ds_read_b128 v[156:159], v0 offset:3072
	v_add_u32_e32 v0, s65, v161
	ds_read_b128 v[164:167], v0
	ds_read_b128 v[168:171], v0 offset:1024
	ds_read_b128 v[172:175], v0 offset:2048
	ds_read_b128 v[180:183], v0 offset:3072
	v_lshl_add_u64 v[216:217], s[0:1], 0, v[140:141]
	s_add_i32 m0, s19, 0xc000
	ds_read_b128 v[184:187], v163
	ds_read_b128 v[188:191], v163 offset:1024
	ds_read_b128 v[192:195], v163 offset:2048
	ds_read_b128 v[196:199], v163 offset:3072
	ds_read_b128 v[200:203], v163 offset:4096
	ds_read_b128 v[204:207], v163 offset:5120
	ds_read_b128 v[208:211], v163 offset:6144
	ds_read_b128 v[212:215], v163 offset:7168
	global_load_lds_dwordx4 v[216:217], off
	v_lshl_add_u64 v[216:217], s[0:1], 0, v[142:143]
	s_add_i32 m0, s19, 0xe000
	s_nop 0
	global_load_lds_dwordx4 v[216:217], off
	s_waitcnt vmcnt(8)
	s_waitcnt lgkmcnt(0)
	s_setprio 3
	s_barrier
	v_mfma_f32_16x16x32_bf16 v[126:129], v[144:147], v[184:187], v[126:129]
	v_mfma_f32_16x16x32_bf16 v[122:125], v[152:155], v[184:187], v[122:125]
	v_mfma_f32_16x16x32_bf16 v[118:121], v[144:147], v[192:195], v[118:121]
	v_mfma_f32_16x16x32_bf16 v[114:117], v[152:155], v[192:195], v[114:117]
	v_mfma_f32_16x16x32_bf16 v[110:113], v[144:147], v[200:203], v[110:113]
	v_mfma_f32_16x16x32_bf16 v[106:109], v[152:155], v[200:203], v[106:109]
	v_mfma_f32_16x16x32_bf16 v[102:105], v[144:147], v[208:211], v[102:105]
	v_mfma_f32_16x16x32_bf16 v[98:101], v[152:155], v[208:211], v[98:101]
	v_mfma_f32_16x16x32_bf16 v[126:129], v[148:151], v[188:191], v[126:129]
	v_mfma_f32_16x16x32_bf16 v[122:125], v[156:159], v[188:191], v[122:125]
	v_mfma_f32_16x16x32_bf16 v[118:121], v[148:151], v[196:199], v[118:121]
	v_mfma_f32_16x16x32_bf16 v[114:117], v[156:159], v[196:199], v[114:117]
	v_mfma_f32_16x16x32_bf16 v[110:113], v[148:151], v[204:207], v[110:113]
	v_mfma_f32_16x16x32_bf16 v[106:109], v[156:159], v[204:207], v[106:109]
	v_mfma_f32_16x16x32_bf16 v[102:105], v[148:151], v[212:215], v[102:105]
	v_mfma_f32_16x16x32_bf16 v[98:101], v[156:159], v[212:215], v[98:101]
	v_mfma_f32_16x16x32_bf16 v[62:65], v[164:167], v[184:187], v[62:65]
	v_mfma_f32_16x16x32_bf16 v[58:61], v[172:175], v[184:187], v[58:61]
	v_mfma_f32_16x16x32_bf16 v[54:57], v[164:167], v[192:195], v[54:57]
	v_mfma_f32_16x16x32_bf16 v[50:53], v[172:175], v[192:195], v[50:53]
	v_mfma_f32_16x16x32_bf16 v[46:49], v[164:167], v[200:203], v[46:49]
	v_mfma_f32_16x16x32_bf16 v[42:45], v[172:175], v[200:203], v[42:45]
	v_mfma_f32_16x16x32_bf16 v[38:41], v[164:167], v[208:211], v[38:41]
	v_mfma_f32_16x16x32_bf16 v[34:37], v[172:175], v[208:211], v[34:37]
	v_mfma_f32_16x16x32_bf16 v[62:65], v[168:171], v[188:191], v[62:65]
	v_mfma_f32_16x16x32_bf16 v[58:61], v[180:183], v[188:191], v[58:61]
	v_mfma_f32_16x16x32_bf16 v[54:57], v[168:171], v[196:199], v[54:57]
	v_mfma_f32_16x16x32_bf16 v[50:53], v[180:183], v[196:199], v[50:53]
	v_mfma_f32_16x16x32_bf16 v[46:49], v[168:171], v[204:207], v[46:49]
	v_mfma_f32_16x16x32_bf16 v[42:45], v[180:183], v[204:207], v[42:45]
	v_mfma_f32_16x16x32_bf16 v[38:41], v[168:171], v[212:215], v[38:41]
	v_mfma_f32_16x16x32_bf16 v[34:37], v[180:183], v[212:215], v[34:37]
	s_barrier
	s_setprio 0
	s_add_i32 s0, s64, s61
	v_lshl_add_u64 v[216:217], s[24:25], 0, v[132:133]
	s_mov_b32 m0, s0
	ds_read_b128 v[184:187], v163 offset:16384
	ds_read_b128 v[188:191], v163 offset:17408
	ds_read_b128 v[192:195], v163 offset:18432
	ds_read_b128 v[196:199], v163 offset:19456
	ds_read_b128 v[200:203], v163 offset:20480
	ds_read_b128 v[204:207], v163 offset:21504
	ds_read_b128 v[208:211], v163 offset:22528
	ds_read_b128 v[212:215], v163 offset:23552
	global_load_lds_dwordx4 v[216:217], off
	s_add_i32 m0, s0, 0x2000
	s_add_u32 s0, s24, 0x80000
	v_lshl_add_u64 v[218:219], s[24:25], 0, v[136:137]
	s_addc_u32 s1, s25, 0
	s_add_i32 s64, s65, s61
	global_load_lds_dwordx4 v[218:219], off
	v_lshl_add_u64 v[220:221], s[0:1], 0, v[132:133]
	s_mov_b32 m0, s64
	v_lshl_add_u64 v[222:223], s[28:29], 0, v[134:135]
	global_load_lds_dwordx4 v[220:221], off
	v_lshl_add_u64 v[220:221], s[0:1], 0, v[136:137]
	s_add_i32 m0, s64, 0x2000
	s_nop 0
	global_load_lds_dwordx4 v[220:221], off
	v_lshl_add_u64 v[220:221], s[28:29], 0, v[130:131]
	s_mov_b32 m0, s19
	s_nop 0
	global_load_lds_dwordx4 v[220:221], off
	s_mov_b32 m0, s35
	s_nop 0
	global_load_lds_dwordx4 v[222:223], off
	s_waitcnt vmcnt(8)
	s_waitcnt lgkmcnt(0)
	s_setprio 3
	s_barrier
; #define PG8_STAGE(bufoff, gbase, voff) do { _Pragma("unroll") for (int _i = 0; _i < 2; ++_i) \
;         __builtin_amdgcn_global_load_lds((const unsigned*)((const char*)(gbase) + (voff)[_i]), (LAS unsigned*)(lds + (bufoff) + ldsw + _i * 8192), 16, 0, 0); } while (0)
; #define PG8_LDA(dst, b, h) do { _Pragma("unroll") for (int m = 0; m < 4; ++m) _Pragma("unroll") for (int k = 0; k < 2; ++k) dst[m][k] = *(const LAS bf16x8*)(lds + PG8_SA(b, h) + aoff + m * 2048 + k * 1024); } while (0)
; #define PG8_LDB(dst, b, h) do { _Pragma("unroll") for (int n = 0; n < 2; ++n) _Pragma("unroll") for (int k = 0; k < 2; ++k) dst[n][k] = *(const LAS bf16x8*)(lds + PG8_SB(b, h) + boff + n * 2048 + k * 1024); } while (0)
; #define PG8_MMA(ai, bj, At, Bt) do { __builtin_amdgcn_s_setprio(1); _Pragma("unroll") for (int m = 0; m < 4; ++m) _Pragma("unroll") for (int n = 0; n < 2; ++n) _Pragma("unroll") for (int k = 0; k < 2; ++k) \
;         acc[ai][bj][m][n] = __builtin_amdgcn_mfma_f32_16x16x32_bf16(Bt[n][k], At[m][k], acc[ai][bj][m][n], 0, 0, 0); __builtin_amdgcn_s_setprio(0); } while (0)
; #define PG8_WAIT_V(n) asm volatile("s_waitcnt vmcnt(" #n ")" ::: "memory")
; #define PG8_WAIT_L(n) asm volatile("s_waitcnt lgkmcnt(" #n ")" ::: "memory")
; #define PG8_BAR __builtin_amdgcn_s_barrier()
; #define PG8_SCHED __builtin_amdgcn_sched_barrier(0)
; template <class Epi, class Sched, int LDA, int LDB, bool ALIGN_EPI = true>
; __device__ __forceinline__ void gemm_phase(LAS unsigned char* lds, const Gemm g, const Sched& S, const Epi& E, int wave) {
;     ...
;             PG8_WAIT_V(8); PG8_WAIT_L(0); PG8_BAR; PG8_MMA(1, 0, At, B0); PG8_MMA(1, 1, At, B1); PG8_BAR; PG8_SCHED;
;             PG8_LDB(B0, 1, 0); PG8_LDB(B1, 1, 1); PG8_SCHED; PG8_LDA(At, 1, 0); PG8_STAGE(PG8_SA(0, 1), a2 + hstepA, voffA);
;             PG8_WAIT_V(8); PG8_WAIT_L(0); PG8_BAR; PG8_MMA(0, 0, At, B0); PG8_MMA(0, 1, At, B1); PG8_BAR; PG8_SCHED;
	v_mfma_f32_16x16x32_bf16 v[94:97], v[144:147], v[184:187], v[94:97]
	v_mfma_f32_16x16x32_bf16 v[90:93], v[152:155], v[184:187], v[90:93]
	v_mfma_f32_16x16x32_bf16 v[86:89], v[144:147], v[192:195], v[86:89]
	v_mfma_f32_16x16x32_bf16 v[82:85], v[152:155], v[192:195], v[82:85]
	v_mfma_f32_16x16x32_bf16 v[78:81], v[144:147], v[200:203], v[78:81]
	v_mfma_f32_16x16x32_bf16 v[74:77], v[152:155], v[200:203], v[74:77]
	v_mfma_f32_16x16x32_bf16 v[70:73], v[144:147], v[208:211], v[70:73]
	v_mfma_f32_16x16x32_bf16 v[66:69], v[152:155], v[208:211], v[66:69]
	v_mfma_f32_16x16x32_bf16 v[94:97], v[148:151], v[188:191], v[94:97]
	v_mfma_f32_16x16x32_bf16 v[90:93], v[156:159], v[188:191], v[90:93]
	v_mfma_f32_16x16x32_bf16 v[86:89], v[148:151], v[196:199], v[86:89]
	v_mfma_f32_16x16x32_bf16 v[82:85], v[156:159], v[196:199], v[82:85]
	v_mfma_f32_16x16x32_bf16 v[78:81], v[148:151], v[204:207], v[78:81]
	v_mfma_f32_16x16x32_bf16 v[74:77], v[156:159], v[204:207], v[74:77]
	v_mfma_f32_16x16x32_bf16 v[70:73], v[148:151], v[212:215], v[70:73]
	v_mfma_f32_16x16x32_bf16 v[66:69], v[156:159], v[212:215], v[66:69]
	v_mfma_f32_16x16x32_bf16 v[30:33], v[164:167], v[184:187], v[30:33]
	v_mfma_f32_16x16x32_bf16 v[26:29], v[172:175], v[184:187], v[26:29]
	v_mfma_f32_16x16x32_bf16 v[22:25], v[164:167], v[192:195], v[22:25]
	v_mfma_f32_16x16x32_bf16 v[18:21], v[172:175], v[192:195], v[18:21]
	v_mfma_f32_16x16x32_bf16 v[14:17], v[164:167], v[200:203], v[14:17]
	v_mfma_f32_16x16x32_bf16 v[10:13], v[172:175], v[200:203], v[10:13]
	v_mfma_f32_16x16x32_bf16 v[6:9], v[164:167], v[208:211], v[6:9]
	v_mfma_f32_16x16x32_bf16 v[2:5], v[172:175], v[208:211], v[2:5]
	v_mfma_f32_16x16x32_bf16 v[30:33], v[168:171], v[188:191], v[30:33]
	v_mfma_f32_16x16x32_bf16 v[26:29], v[180:183], v[188:191], v[26:29]
	v_mfma_f32_16x16x32_bf16 v[22:25], v[168:171], v[196:199], v[22:25]
	v_mfma_f32_16x16x32_bf16 v[18:21], v[180:183], v[196:199], v[18:21]
	v_mfma_f32_16x16x32_bf16 v[14:17], v[168:171], v[204:207], v[14:17]
	v_mfma_f32_16x16x32_bf16 v[10:13], v[180:183], v[204:207], v[10:13]
	v_mfma_f32_16x16x32_bf16 v[6:9], v[168:171], v[212:215], v[6:9]
	v_mfma_f32_16x16x32_bf16 v[2:5], v[180:183], v[212:215], v[2:5]
	s_barrier
	s_setprio 0
	s_add_i32 s64, 0, 0x18000
	v_add_u32_e32 v0, s64, v161
	s_add_i32 s65, 0, 0x1c000
	ds_read_b128 v[144:147], v0
	ds_read_b128 v[148:151], v0 offset:1024
	ds_read_b128 v[152:155], v0 offset:2048
	ds_read_b128 v[156:159], v0 offset:3072
	v_add_u32_e32 v0, s65, v161
	ds_read_b128 v[164:167], v0
	ds_read_b128 v[168:171], v0 offset:1024
	ds_read_b128 v[172:175], v0 offset:2048
	ds_read_b128 v[180:183], v0 offset:3072
	s_add_u32 s0, s28, 0x84000
	s_addc_u32 s1, s29, 0
	s_mov_b32 m0, s36
	v_lshl_add_u64 v[224:225], s[0:1], 0, v[130:131]
	ds_read_b128 v[184:187], v163 offset:32768
	ds_read_b128 v[188:191], v163 offset:33792
	ds_read_b128 v[192:195], v163 offset:34816
	ds_read_b128 v[196:199], v163 offset:35840
	ds_read_b128 v[200:203], v163 offset:36864
	ds_read_b128 v[204:207], v163 offset:37888
	ds_read_b128 v[208:211], v163 offset:38912
	ds_read_b128 v[212:215], v163 offset:39936
	global_load_lds_dwordx4 v[224:225], off
	v_lshl_add_u64 v[224:225], s[0:1], 0, v[134:135]
	s_mov_b32 m0, s37
	s_nop 0
	global_load_lds_dwordx4 v[224:225], off
	s_waitcnt vmcnt(8)
	s_waitcnt lgkmcnt(0)
	s_setprio 3
	s_barrier
	v_mfma_f32_16x16x32_bf16 v[126:129], v[144:147], v[184:187], v[126:129]
	v_mfma_f32_16x16x32_bf16 v[122:125], v[152:155], v[184:187], v[122:125]
	v_mfma_f32_16x16x32_bf16 v[118:121], v[144:147], v[192:195], v[118:121]
	v_mfma_f32_16x16x32_bf16 v[114:117], v[152:155], v[192:195], v[114:117]
	v_mfma_f32_16x16x32_bf16 v[110:113], v[144:147], v[200:203], v[110:113]
	v_mfma_f32_16x16x32_bf16 v[106:109], v[152:155], v[200:203], v[106:109]
	v_mfma_f32_16x16x32_bf16 v[102:105], v[144:147], v[208:211], v[102:105]
	v_mfma_f32_16x16x32_bf16 v[98:101], v[152:155], v[208:211], v[98:101]
	v_mfma_f32_16x16x32_bf16 v[126:129], v[148:151], v[188:191], v[126:129]
	v_mfma_f32_16x16x32_bf16 v[122:125], v[156:159], v[188:191], v[122:125]
	v_mfma_f32_16x16x32_bf16 v[118:121], v[148:151], v[196:199], v[118:121]
	v_mfma_f32_16x16x32_bf16 v[114:117], v[156:159], v[196:199], v[114:117]
	v_mfma_f32_16x16x32_bf16 v[110:113], v[148:151], v[204:207], v[110:113]
	v_mfma_f32_16x16x32_bf16 v[106:109], v[156:159], v[204:207], v[106:109]
	v_mfma_f32_16x16x32_bf16 v[102:105], v[148:151], v[212:215], v[102:105]
	v_mfma_f32_16x16x32_bf16 v[98:101], v[156:159], v[212:215], v[98:101]
	v_mfma_f32_16x16x32_bf16 v[62:65], v[164:167], v[184:187], v[62:65]
	v_mfma_f32_16x16x32_bf16 v[58:61], v[172:175], v[184:187], v[58:61]
	v_mfma_f32_16x16x32_bf16 v[54:57], v[164:167], v[192:195], v[54:57]
	v_mfma_f32_16x16x32_bf16 v[50:53], v[172:175], v[192:195], v[50:53]
	v_mfma_f32_16x16x32_bf16 v[46:49], v[164:167], v[200:203], v[46:49]
	v_mfma_f32_16x16x32_bf16 v[42:45], v[172:175], v[200:203], v[42:45]
	v_mfma_f32_16x16x32_bf16 v[38:41], v[164:167], v[208:211], v[38:41]
	v_mfma_f32_16x16x32_bf16 v[34:37], v[172:175], v[208:211], v[34:37]
	v_mfma_f32_16x16x32_bf16 v[62:65], v[168:171], v[188:191], v[62:65]
	v_mfma_f32_16x16x32_bf16 v[58:61], v[180:183], v[188:191], v[58:61]
	v_mfma_f32_16x16x32_bf16 v[54:57], v[168:171], v[196:199], v[54:57]
	v_mfma_f32_16x16x32_bf16 v[50:53], v[180:183], v[196:199], v[50:53]
	v_mfma_f32_16x16x32_bf16 v[46:49], v[168:171], v[204:207], v[46:49]
	v_mfma_f32_16x16x32_bf16 v[42:45], v[180:183], v[204:207], v[42:45]
	v_mfma_f32_16x16x32_bf16 v[38:41], v[168:171], v[212:215], v[38:41]
	v_mfma_f32_16x16x32_bf16 v[34:37], v[180:183], v[212:215], v[34:37]
	s_barrier
; #define PG8_STAGE(bufoff, gbase, voff) do { _Pragma("unroll") for (int _i = 0; _i < 2; ++_i) \
;         __builtin_amdgcn_global_load_lds((const unsigned*)((const char*)(gbase) + (voff)[_i]), (LAS unsigned*)(lds + (bufoff) + ldsw + _i * 8192), 16, 0, 0); } while (0)
; #define PG8_LDA(dst, b, h) do { _Pragma("unroll") for (int m = 0; m < 4; ++m) _Pragma("unroll") for (int k = 0; k < 2; ++k) dst[m][k] = *(const LAS bf16x8*)(lds + PG8_SA(b, h) + aoff + m * 2048 + k * 1024); } while (0)
; #define PG8_MMA(ai, bj, At, Bt) do { __builtin_amdgcn_s_setprio(1); _Pragma("unroll") for (int m = 0; m < 4; ++m) _Pragma("unroll") for (int n = 0; n < 2; ++n) _Pragma("unroll") for (int k = 0; k < 2; ++k) \
;         acc[ai][bj][m][n] = __builtin_amdgcn_mfma_f32_16x16x32_bf16(Bt[n][k], At[m][k], acc[ai][bj][m][n], 0, 0, 0); __builtin_amdgcn_s_setprio(0); } while (0)
; #define PG8_WAIT_V(n) asm volatile("s_waitcnt vmcnt(" #n ")" ::: "memory")
; #define PG8_WAIT_L(n) asm volatile("s_waitcnt lgkmcnt(" #n ")" ::: "memory")
; #define PG8_BAR __builtin_amdgcn_s_barrier()
; #define PG8_SCHED __builtin_amdgcn_sched_barrier(0)
; template <class Epi, class Sched, int LDA, int LDB, bool ALIGN_EPI = true>
; __device__ __forceinline__ void gemm_phase(LAS unsigned char* lds, const Gemm g, const Sched& S, const Epi& E, int wave) {
;     ...
;             PG8_LDA(At, 1, 1); PG8_STAGE(PG8_SB(1, 0), b3, voffB); PG8_STAGE(PG8_SB(1, 1), b3 + hstepB, voffB); PG8_STAGE(PG8_SA(1, 0), a3, voffA);
;             PG8_WAIT_V(8); PG8_WAIT_L(0); PG8_BAR; PG8_MMA(1, 0, At, B0); PG8_MMA(1, 1, At, B1); PG8_BAR; PG8_SCHED;
;         }
;         if constexpr (ALIGN_EPI) { if (wr == 0) PG8_BAR; }
	s_setprio 0
	s_add_i32 s0, s64, s61
	v_lshl_add_u64 v[216:217], v[216:217], 0, s[70:71]
	s_mov_b32 m0, s0
	ds_read_b128 v[184:187], v163 offset:49152
	ds_read_b128 v[188:191], v163 offset:50176
	ds_read_b128 v[192:195], v163 offset:51200
	ds_read_b128 v[196:199], v163 offset:52224
	ds_read_b128 v[200:203], v163 offset:53248
	ds_read_b128 v[204:207], v163 offset:54272
	ds_read_b128 v[208:211], v163 offset:55296
	ds_read_b128 v[212:215], v163 offset:56320
	global_load_lds_dwordx4 v[216:217], off
	s_add_i32 m0, s0, 0x2000
	s_add_u32 s0, s24, 0x80080
	v_lshl_add_u64 v[216:217], v[218:219], 0, s[70:71]
	s_addc_u32 s1, s25, 0
	s_add_i32 s24, s65, s61
	global_load_lds_dwordx4 v[216:217], off
	v_lshl_add_u64 v[216:217], s[0:1], 0, v[132:133]
	s_mov_b32 m0, s24
	s_nop 0
	global_load_lds_dwordx4 v[216:217], off
	v_lshl_add_u64 v[216:217], s[0:1], 0, v[136:137]
	s_add_i32 m0, s24, 0x2000
	s_nop 0
	global_load_lds_dwordx4 v[216:217], off
	v_lshl_add_u64 v[216:217], v[220:221], 0, s[70:71]
	s_mov_b32 m0, s38
	s_nop 0
	global_load_lds_dwordx4 v[216:217], off
	v_lshl_add_u64 v[216:217], v[222:223], 0, s[70:71]
	s_mov_b32 m0, s39
	s_nop 0
	global_load_lds_dwordx4 v[216:217], off
	s_waitcnt vmcnt(8)
	s_waitcnt lgkmcnt(0)
	s_setprio 3
	s_barrier
	v_mfma_f32_16x16x32_bf16 v[94:97], v[144:147], v[184:187], v[94:97]
	v_mfma_f32_16x16x32_bf16 v[90:93], v[152:155], v[184:187], v[90:93]
	v_mfma_f32_16x16x32_bf16 v[86:89], v[144:147], v[192:195], v[86:89]
	v_mfma_f32_16x16x32_bf16 v[82:85], v[152:155], v[192:195], v[82:85]
	v_mfma_f32_16x16x32_bf16 v[78:81], v[144:147], v[200:203], v[78:81]
	v_mfma_f32_16x16x32_bf16 v[74:77], v[152:155], v[200:203], v[74:77]
	v_mfma_f32_16x16x32_bf16 v[70:73], v[144:147], v[208:211], v[70:73]
	v_mfma_f32_16x16x32_bf16 v[66:69], v[152:155], v[208:211], v[66:69]
	v_mfma_f32_16x16x32_bf16 v[94:97], v[148:151], v[188:191], v[94:97]
	v_mfma_f32_16x16x32_bf16 v[90:93], v[156:159], v[188:191], v[90:93]
	v_mfma_f32_16x16x32_bf16 v[86:89], v[148:151], v[196:199], v[86:89]
	v_mfma_f32_16x16x32_bf16 v[82:85], v[156:159], v[196:199], v[82:85]
	v_mfma_f32_16x16x32_bf16 v[78:81], v[148:151], v[204:207], v[78:81]
	v_mfma_f32_16x16x32_bf16 v[74:77], v[156:159], v[204:207], v[74:77]
	v_mfma_f32_16x16x32_bf16 v[70:73], v[148:151], v[212:215], v[70:73]
	v_mfma_f32_16x16x32_bf16 v[66:69], v[156:159], v[212:215], v[66:69]
	v_mfma_f32_16x16x32_bf16 v[30:33], v[164:167], v[184:187], v[30:33]
	v_mfma_f32_16x16x32_bf16 v[26:29], v[172:175], v[184:187], v[26:29]
	v_mfma_f32_16x16x32_bf16 v[22:25], v[164:167], v[192:195], v[22:25]
	v_mfma_f32_16x16x32_bf16 v[18:21], v[172:175], v[192:195], v[18:21]
	v_mfma_f32_16x16x32_bf16 v[14:17], v[164:167], v[200:203], v[14:17]
	v_mfma_f32_16x16x32_bf16 v[10:13], v[172:175], v[200:203], v[10:13]
	v_mfma_f32_16x16x32_bf16 v[6:9], v[164:167], v[208:211], v[6:9]
	v_mfma_f32_16x16x32_bf16 v[2:5], v[172:175], v[208:211], v[2:5]
	v_mfma_f32_16x16x32_bf16 v[30:33], v[168:171], v[188:191], v[30:33]
	v_mfma_f32_16x16x32_bf16 v[26:29], v[180:183], v[188:191], v[26:29]
	v_mfma_f32_16x16x32_bf16 v[22:25], v[168:171], v[196:199], v[22:25]
	v_mfma_f32_16x16x32_bf16 v[18:21], v[180:183], v[196:199], v[18:21]
	v_mfma_f32_16x16x32_bf16 v[14:17], v[168:171], v[204:207], v[14:17]
	v_mfma_f32_16x16x32_bf16 v[10:13], v[180:183], v[204:207], v[10:13]
	v_mfma_f32_16x16x32_bf16 v[6:9], v[168:171], v[212:215], v[6:9]
	v_mfma_f32_16x16x32_bf16 v[2:5], v[180:183], v[212:215], v[2:5]
	s_barrier
	s_setprio 0
	s_add_i32 s59, s59, 2
	s_add_u32 s49, s49, 0x100
	s_addc_u32 s58, s58, 0
	s_cmp_gt_u32 s59, 29
	s_mov_b64 s[0:1], s[2:3]
	s_cbranch_scc0 .LBB0_2254
	v_readlane_b32 s0, v252, 14
	v_readlane_b32 s1, v252, 15
	s_and_b64 vcc, exec, s[0:1]
	s_cbranch_vccz .LBB0_2257
	s_barrier

; #define PG8_STAGE(bufoff, gbase, voff) do { _Pragma("unroll") for (int _i = 0; _i < 2; ++_i) \
;         __builtin_amdgcn_global_load_lds((const unsigned*)((const char*)(gbase) + (voff)[_i]), (LAS unsigned*)(lds + (bufoff) + ldsw + _i * 8192), 16, 0, 0); } while (0)
; #define PG8_LDA(dst, b, h) do { _Pragma("unroll") for (int m = 0; m < 4; ++m) _Pragma("unroll") for (int k = 0; k < 2; ++k) dst[m][k] = *(const LAS bf16x8*)(lds + PG8_SA(b, h) + aoff + m * 2048 + k * 1024); } while (0)
; #define PG8_LDB(dst, b, h) do { _Pragma("unroll") for (int n = 0; n < 2; ++n) _Pragma("unroll") for (int k = 0; k < 2; ++k) dst[n][k] = *(const LAS bf16x8*)(lds + PG8_SB(b, h) + boff + n * 2048 + k * 1024); } while (0)
; #define PG8_MMA(ai, bj, At, Bt) do { __builtin_amdgcn_s_setprio(1); _Pragma("unroll") for (int m = 0; m < 4; ++m) _Pragma("unroll") for (int n = 0; n < 2; ++n) _Pragma("unroll") for (int k = 0; k < 2; ++k) \
;         acc[ai][bj][m][n] = __builtin_amdgcn_mfma_f32_16x16x32_bf16(Bt[n][k], At[m][k], acc[ai][bj][m][n], 0, 0, 0); __builtin_amdgcn_s_setprio(0); } while (0)
; #define PG8_WAIT_V(n) asm volatile("s_waitcnt vmcnt(" #n ")" ::: "memory")
; #define PG8_WAIT_L(n) asm volatile("s_waitcnt lgkmcnt(" #n ")" ::: "memory")
; #define PG8_BAR __builtin_amdgcn_s_barrier()
; template <class Epi, class Sched, int LDA, int LDB, bool ALIGN_EPI = true>
; __device__ __forceinline__ void gemm_phase(LAS unsigned char* lds, const Gemm g, const Sched& S, const Epi& E, int wave) {
;     ...
;         for (int t = 0; t < nt; t += 2) {
;             const bool last = (t == nt - 2);
;             const char* a1 = cA + (size_t)(t + 1) * kstep;
;             const char* a2 = last ? nA : cA + (size_t)(t + 2) * kstep; const char* b2 = last ? nB : cB + (size_t)(t + 2) * kstep;
;             const char* a3 = a2 + kstep; const char* b3 = b2 + kstep;
;             PG8_LDB(B0, 0, 0); PG8_LDB(B1, 0, 1); PG8_SCHED; PG8_LDA(At, 0, 0); PG8_STAGE(PG8_SA(1, 1), a1 + hstepA, voffA);
;             PG8_WAIT_V(8); PG8_WAIT_L(0); PG8_BAR; PG8_MMA(0, 0, At, B0); PG8_MMA(0, 1, At, B1); PG8_BAR; PG8_SCHED;
;             PG8_LDA(At, 0, 1); PG8_STAGE(PG8_SB(0, 0), b2, voffB); PG8_STAGE(PG8_SB(0, 1), b2 + hstepB, voffB); PG8_STAGE(PG8_SA(0, 0), a2, voffA);
;             PG8_WAIT_V(8); PG8_WAIT_L(0); PG8_BAR; PG8_MMA(1, 0, At, B0); PG8_MMA(1, 1, At, B1); PG8_BAR; PG8_SCHED;
.LBB0_2415:
	s_add_u32 s12, s10, 0xfff80080
	s_addc_u32 s13, s11, -1
	s_add_i32 s39, 0, 0x10000
	s_cmp_eq_u32 s38, 28
	s_cselect_b32 s15, s1, s13
	s_cselect_b32 s14, s3, s12
	v_add_u32_e32 v140, s39, v143
	s_cselect_b32 s13, s7, s37
	s_cselect_b32 s12, s6, s36
	s_add_i32 s46, 0, 0x14000
	ds_read_b128 v[146:149], v140
	ds_read_b128 v[150:153], v140 offset:1024
	ds_read_b128 v[154:157], v140 offset:2048
	ds_read_b128 v[158:161], v140 offset:3072
	v_add_u32_e32 v140, s46, v143
	ds_read_b128 v[162:165], v140
	ds_read_b128 v[166:169], v140 offset:1024
	ds_read_b128 v[170:173], v140 offset:2048
	ds_read_b128 v[180:183], v140 offset:3072
	v_lshl_add_u64 v[140:141], s[10:11], 0, v[136:137]
	s_add_i32 m0, s18, 0xc000
	ds_read_b128 v[184:187], v145
	ds_read_b128 v[188:191], v145 offset:1024
	ds_read_b128 v[192:195], v145 offset:2048
	ds_read_b128 v[196:199], v145 offset:3072
	ds_read_b128 v[200:203], v145 offset:4096
	ds_read_b128 v[204:207], v145 offset:5120
	ds_read_b128 v[208:211], v145 offset:6144
	ds_read_b128 v[212:215], v145 offset:7168
	global_load_lds_dwordx4 v[140:141], off
	v_lshl_add_u64 v[140:141], s[10:11], 0, v[138:139]
	s_add_i32 m0, s18, 0xe000
	s_nop 0
	global_load_lds_dwordx4 v[140:141], off
	s_waitcnt vmcnt(8)
	s_waitcnt lgkmcnt(0)
	s_setprio 3
	s_barrier
	v_mfma_f32_16x16x32_bf16 v[126:129], v[146:149], v[184:187], v[126:129]
	v_mfma_f32_16x16x32_bf16 v[122:125], v[154:157], v[184:187], v[122:125]
	v_mfma_f32_16x16x32_bf16 v[114:117], v[146:149], v[192:195], v[114:117]
	v_mfma_f32_16x16x32_bf16 v[106:109], v[154:157], v[192:195], v[106:109]
	v_mfma_f32_16x16x32_bf16 v[98:101], v[146:149], v[200:203], v[98:101]
	v_mfma_f32_16x16x32_bf16 v[90:93], v[154:157], v[200:203], v[90:93]
	v_mfma_f32_16x16x32_bf16 v[82:85], v[146:149], v[208:211], v[82:85]
	v_mfma_f32_16x16x32_bf16 v[74:77], v[154:157], v[208:211], v[74:77]
	v_mfma_f32_16x16x32_bf16 v[126:129], v[150:153], v[188:191], v[126:129]
	v_mfma_f32_16x16x32_bf16 v[122:125], v[158:161], v[188:191], v[122:125]
	v_mfma_f32_16x16x32_bf16 v[114:117], v[150:153], v[196:199], v[114:117]
	v_mfma_f32_16x16x32_bf16 v[106:109], v[158:161], v[196:199], v[106:109]
	v_mfma_f32_16x16x32_bf16 v[98:101], v[150:153], v[204:207], v[98:101]
	v_mfma_f32_16x16x32_bf16 v[90:93], v[158:161], v[204:207], v[90:93]
	v_mfma_f32_16x16x32_bf16 v[82:85], v[150:153], v[212:215], v[82:85]
	v_mfma_f32_16x16x32_bf16 v[74:77], v[158:161], v[212:215], v[74:77]
	v_mfma_f32_16x16x32_bf16 v[118:121], v[162:165], v[184:187], v[118:121]
	v_mfma_f32_16x16x32_bf16 v[110:113], v[170:173], v[184:187], v[110:113]
	v_mfma_f32_16x16x32_bf16 v[102:105], v[162:165], v[192:195], v[102:105]
	v_mfma_f32_16x16x32_bf16 v[94:97], v[170:173], v[192:195], v[94:97]
	v_mfma_f32_16x16x32_bf16 v[86:89], v[162:165], v[200:203], v[86:89]
	v_mfma_f32_16x16x32_bf16 v[78:81], v[170:173], v[200:203], v[78:81]
	v_mfma_f32_16x16x32_bf16 v[70:73], v[162:165], v[208:211], v[70:73]
	v_mfma_f32_16x16x32_bf16 v[66:69], v[170:173], v[208:211], v[66:69]
	v_mfma_f32_16x16x32_bf16 v[118:121], v[166:169], v[188:191], v[118:121]
	v_mfma_f32_16x16x32_bf16 v[110:113], v[180:183], v[188:191], v[110:113]
	v_mfma_f32_16x16x32_bf16 v[102:105], v[166:169], v[196:199], v[102:105]
	v_mfma_f32_16x16x32_bf16 v[94:97], v[180:183], v[196:199], v[94:97]
	v_mfma_f32_16x16x32_bf16 v[86:89], v[166:169], v[204:207], v[86:89]
	v_mfma_f32_16x16x32_bf16 v[78:81], v[180:183], v[204:207], v[78:81]
	v_mfma_f32_16x16x32_bf16 v[70:73], v[166:169], v[212:215], v[70:73]
	v_mfma_f32_16x16x32_bf16 v[66:69], v[180:183], v[212:215], v[66:69]
	s_barrier
	s_setprio 0
	s_add_i32 s39, s39, s47
	v_lshl_add_u64 v[140:141], s[12:13], 0, v[0:1]
	s_mov_b32 m0, s39
	ds_read_b128 v[184:187], v145 offset:16384
	ds_read_b128 v[188:191], v145 offset:17408
	ds_read_b128 v[192:195], v145 offset:18432
	ds_read_b128 v[196:199], v145 offset:19456
	ds_read_b128 v[200:203], v145 offset:20480
	ds_read_b128 v[204:207], v145 offset:21504
	ds_read_b128 v[208:211], v145 offset:22528
	ds_read_b128 v[212:215], v145 offset:23552
	global_load_lds_dwordx4 v[140:141], off
	s_add_i32 m0, s39, 0x2000
	s_add_u32 s44, s12, 0x84000
	v_lshl_add_u64 v[174:175], s[12:13], 0, v[134:135]
	s_addc_u32 s45, s13, 0
	s_add_i32 s39, s46, s47
	global_load_lds_dwordx4 v[174:175], off
	v_lshl_add_u64 v[216:217], s[44:45], 0, v[0:1]
	s_mov_b32 m0, s39
	v_lshl_add_u64 v[218:219], s[14:15], 0, v[132:133]
	global_load_lds_dwordx4 v[216:217], off
	v_lshl_add_u64 v[216:217], s[44:45], 0, v[134:135]
	s_add_i32 m0, s39, 0x2000
	s_nop 0
	global_load_lds_dwordx4 v[216:217], off
	v_lshl_add_u64 v[216:217], s[14:15], 0, v[130:131]
	s_mov_b32 m0, s18
	s_nop 0
	global_load_lds_dwordx4 v[216:217], off
	s_mov_b32 m0, s19
	s_nop 0
	global_load_lds_dwordx4 v[218:219], off
	s_waitcnt vmcnt(8)
	s_waitcnt lgkmcnt(0)
	s_setprio 3
	s_barrier
; #define PG8_STAGE(bufoff, gbase, voff) do { _Pragma("unroll") for (int _i = 0; _i < 2; ++_i) \
;         __builtin_amdgcn_global_load_lds((const unsigned*)((const char*)(gbase) + (voff)[_i]), (LAS unsigned*)(lds + (bufoff) + ldsw + _i * 8192), 16, 0, 0); } while (0)
; #define PG8_LDA(dst, b, h) do { _Pragma("unroll") for (int m = 0; m < 4; ++m) _Pragma("unroll") for (int k = 0; k < 2; ++k) dst[m][k] = *(const LAS bf16x8*)(lds + PG8_SA(b, h) + aoff + m * 2048 + k * 1024); } while (0)
; #define PG8_LDB(dst, b, h) do { _Pragma("unroll") for (int n = 0; n < 2; ++n) _Pragma("unroll") for (int k = 0; k < 2; ++k) dst[n][k] = *(const LAS bf16x8*)(lds + PG8_SB(b, h) + boff + n * 2048 + k * 1024); } while (0)
; #define PG8_MMA(ai, bj, At, Bt) do { __builtin_amdgcn_s_setprio(1); _Pragma("unroll") for (int m = 0; m < 4; ++m) _Pragma("unroll") for (int n = 0; n < 2; ++n) _Pragma("unroll") for (int k = 0; k < 2; ++k) \
;         acc[ai][bj][m][n] = __builtin_amdgcn_mfma_f32_16x16x32_bf16(Bt[n][k], At[m][k], acc[ai][bj][m][n], 0, 0, 0); __builtin_amdgcn_s_setprio(0); } while (0)
; #define PG8_WAIT_V(n) asm volatile("s_waitcnt vmcnt(" #n ")" ::: "memory")
; #define PG8_WAIT_L(n) asm volatile("s_waitcnt lgkmcnt(" #n ")" ::: "memory")
; #define PG8_BAR __builtin_amdgcn_s_barrier()
; #define PG8_SCHED __builtin_amdgcn_sched_barrier(0)
; template <class Epi, class Sched, int LDA, int LDB, bool ALIGN_EPI = true>
; __device__ __forceinline__ void gemm_phase(LAS unsigned char* lds, const Gemm g, const Sched& S, const Epi& E, int wave) {
;     ...
;             PG8_WAIT_V(8); PG8_WAIT_L(0); PG8_BAR; PG8_MMA(1, 0, At, B0); PG8_MMA(1, 1, At, B1); PG8_BAR; PG8_SCHED;
;             PG8_LDB(B0, 1, 0); PG8_LDB(B1, 1, 1); PG8_SCHED; PG8_LDA(At, 1, 0); PG8_STAGE(PG8_SA(0, 1), a2 + hstepA, voffA);
;             PG8_WAIT_V(8); PG8_WAIT_L(0); PG8_BAR; PG8_MMA(0, 0, At, B0); PG8_MMA(0, 1, At, B1); PG8_BAR; PG8_SCHED;
	v_mfma_f32_16x16x32_bf16 v[62:65], v[146:149], v[184:187], v[62:65]
	v_mfma_f32_16x16x32_bf16 v[58:61], v[154:157], v[184:187], v[58:61]
	v_mfma_f32_16x16x32_bf16 v[50:53], v[146:149], v[192:195], v[50:53]
	v_mfma_f32_16x16x32_bf16 v[42:45], v[154:157], v[192:195], v[42:45]
	v_mfma_f32_16x16x32_bf16 v[34:37], v[146:149], v[200:203], v[34:37]
	v_mfma_f32_16x16x32_bf16 v[26:29], v[154:157], v[200:203], v[26:29]
	v_mfma_f32_16x16x32_bf16 v[18:21], v[146:149], v[208:211], v[18:21]
	v_mfma_f32_16x16x32_bf16 v[10:13], v[154:157], v[208:211], v[10:13]
	v_mfma_f32_16x16x32_bf16 v[62:65], v[150:153], v[188:191], v[62:65]
	v_mfma_f32_16x16x32_bf16 v[58:61], v[158:161], v[188:191], v[58:61]
	v_mfma_f32_16x16x32_bf16 v[50:53], v[150:153], v[196:199], v[50:53]
	v_mfma_f32_16x16x32_bf16 v[42:45], v[158:161], v[196:199], v[42:45]
	v_mfma_f32_16x16x32_bf16 v[34:37], v[150:153], v[204:207], v[34:37]
	v_mfma_f32_16x16x32_bf16 v[26:29], v[158:161], v[204:207], v[26:29]
	v_mfma_f32_16x16x32_bf16 v[18:21], v[150:153], v[212:215], v[18:21]
	v_mfma_f32_16x16x32_bf16 v[10:13], v[158:161], v[212:215], v[10:13]
	v_mfma_f32_16x16x32_bf16 v[54:57], v[162:165], v[184:187], v[54:57]
	v_mfma_f32_16x16x32_bf16 v[46:49], v[170:173], v[184:187], v[46:49]
	v_mfma_f32_16x16x32_bf16 v[38:41], v[162:165], v[192:195], v[38:41]
	v_mfma_f32_16x16x32_bf16 v[30:33], v[170:173], v[192:195], v[30:33]
	v_mfma_f32_16x16x32_bf16 v[22:25], v[162:165], v[200:203], v[22:25]
	v_mfma_f32_16x16x32_bf16 v[14:17], v[170:173], v[200:203], v[14:17]
	v_mfma_f32_16x16x32_bf16 v[6:9], v[162:165], v[208:211], v[6:9]
	v_mfma_f32_16x16x32_bf16 v[2:5], v[170:173], v[208:211], v[2:5]
	v_mfma_f32_16x16x32_bf16 v[54:57], v[166:169], v[188:191], v[54:57]
	v_mfma_f32_16x16x32_bf16 v[46:49], v[180:183], v[188:191], v[46:49]
	v_mfma_f32_16x16x32_bf16 v[38:41], v[166:169], v[196:199], v[38:41]
	v_mfma_f32_16x16x32_bf16 v[30:33], v[180:183], v[196:199], v[30:33]
	v_mfma_f32_16x16x32_bf16 v[22:25], v[166:169], v[204:207], v[22:25]
	v_mfma_f32_16x16x32_bf16 v[14:17], v[180:183], v[204:207], v[14:17]
	v_mfma_f32_16x16x32_bf16 v[6:9], v[166:169], v[212:215], v[6:9]
	v_mfma_f32_16x16x32_bf16 v[2:5], v[180:183], v[212:215], v[2:5]
	s_barrier
	s_setprio 0
	s_add_i32 s39, 0, 0x18000
	s_add_i32 s44, 0, 0x1c000
	v_add_u32_e32 v158, s39, v143
	v_add_u32_e32 v180, s44, v143
	ds_read_b128 v[146:149], v158
	ds_read_b128 v[150:153], v158 offset:1024
	ds_read_b128 v[154:157], v158 offset:2048
	ds_read_b128 v[158:161], v158 offset:3072
	ds_read_b128 v[162:165], v180
	ds_read_b128 v[166:169], v180 offset:1024
	ds_read_b128 v[170:173], v180 offset:2048
	ds_read_b128 v[180:183], v180 offset:3072
	s_add_u32 s14, s14, 0x80000
	s_addc_u32 s15, s15, 0
	s_mov_b32 m0, s24
	v_lshl_add_u64 v[220:221], s[14:15], 0, v[130:131]
	ds_read_b128 v[184:187], v145 offset:32768
	ds_read_b128 v[188:191], v145 offset:33792
	ds_read_b128 v[192:195], v145 offset:34816
	ds_read_b128 v[196:199], v145 offset:35840
	ds_read_b128 v[200:203], v145 offset:36864
	ds_read_b128 v[204:207], v145 offset:37888
	ds_read_b128 v[208:211], v145 offset:38912
	ds_read_b128 v[212:215], v145 offset:39936
	global_load_lds_dwordx4 v[220:221], off
	v_lshl_add_u64 v[220:221], s[14:15], 0, v[132:133]
	s_mov_b32 m0, s25
	s_nop 0
	global_load_lds_dwordx4 v[220:221], off
	s_waitcnt vmcnt(8)
	s_waitcnt lgkmcnt(0)
	s_setprio 3
	s_barrier
	v_mfma_f32_16x16x32_bf16 v[126:129], v[146:149], v[184:187], v[126:129]
	v_mfma_f32_16x16x32_bf16 v[122:125], v[154:157], v[184:187], v[122:125]
	v_mfma_f32_16x16x32_bf16 v[114:117], v[146:149], v[192:195], v[114:117]
	v_mfma_f32_16x16x32_bf16 v[106:109], v[154:157], v[192:195], v[106:109]
	v_mfma_f32_16x16x32_bf16 v[98:101], v[146:149], v[200:203], v[98:101]
	v_mfma_f32_16x16x32_bf16 v[90:93], v[154:157], v[200:203], v[90:93]
	v_mfma_f32_16x16x32_bf16 v[82:85], v[146:149], v[208:211], v[82:85]
	v_mfma_f32_16x16x32_bf16 v[74:77], v[154:157], v[208:211], v[74:77]
	v_mfma_f32_16x16x32_bf16 v[126:129], v[150:153], v[188:191], v[126:129]
	v_mfma_f32_16x16x32_bf16 v[122:125], v[158:161], v[188:191], v[122:125]
	v_mfma_f32_16x16x32_bf16 v[114:117], v[150:153], v[196:199], v[114:117]
	v_mfma_f32_16x16x32_bf16 v[106:109], v[158:161], v[196:199], v[106:109]
	v_mfma_f32_16x16x32_bf16 v[98:101], v[150:153], v[204:207], v[98:101]
	v_mfma_f32_16x16x32_bf16 v[90:93], v[158:161], v[204:207], v[90:93]
	v_mfma_f32_16x16x32_bf16 v[82:85], v[150:153], v[212:215], v[82:85]
	v_mfma_f32_16x16x32_bf16 v[74:77], v[158:161], v[212:215], v[74:77]
	v_mfma_f32_16x16x32_bf16 v[118:121], v[162:165], v[184:187], v[118:121]
	v_mfma_f32_16x16x32_bf16 v[110:113], v[170:173], v[184:187], v[110:113]
	v_mfma_f32_16x16x32_bf16 v[102:105], v[162:165], v[192:195], v[102:105]
	v_mfma_f32_16x16x32_bf16 v[94:97], v[170:173], v[192:195], v[94:97]
	v_mfma_f32_16x16x32_bf16 v[86:89], v[162:165], v[200:203], v[86:89]
	v_mfma_f32_16x16x32_bf16 v[78:81], v[170:173], v[200:203], v[78:81]
	v_mfma_f32_16x16x32_bf16 v[70:73], v[162:165], v[208:211], v[70:73]
	v_mfma_f32_16x16x32_bf16 v[66:69], v[170:173], v[208:211], v[66:69]
	v_mfma_f32_16x16x32_bf16 v[118:121], v[166:169], v[188:191], v[118:121]
	v_mfma_f32_16x16x32_bf16 v[110:113], v[180:183], v[188:191], v[110:113]
	v_mfma_f32_16x16x32_bf16 v[102:105], v[166:169], v[196:199], v[102:105]
	v_mfma_f32_16x16x32_bf16 v[94:97], v[180:183], v[196:199], v[94:97]
	v_mfma_f32_16x16x32_bf16 v[86:89], v[166:169], v[204:207], v[86:89]
	v_mfma_f32_16x16x32_bf16 v[78:81], v[180:183], v[204:207], v[78:81]
	v_mfma_f32_16x16x32_bf16 v[70:73], v[166:169], v[212:215], v[70:73]
	v_mfma_f32_16x16x32_bf16 v[66:69], v[180:183], v[212:215], v[66:69]
	s_barrier
; #define PG8_STAGE(bufoff, gbase, voff) do { _Pragma("unroll") for (int _i = 0; _i < 2; ++_i) \
;         __builtin_amdgcn_global_load_lds((const unsigned*)((const char*)(gbase) + (voff)[_i]), (LAS unsigned*)(lds + (bufoff) + ldsw + _i * 8192), 16, 0, 0); } while (0)
; #define PG8_LDA(dst, b, h) do { _Pragma("unroll") for (int m = 0; m < 4; ++m) _Pragma("unroll") for (int k = 0; k < 2; ++k) dst[m][k] = *(const LAS bf16x8*)(lds + PG8_SA(b, h) + aoff + m * 2048 + k * 1024); } while (0)
; #define PG8_MMA(ai, bj, At, Bt) do { __builtin_amdgcn_s_setprio(1); _Pragma("unroll") for (int m = 0; m < 4; ++m) _Pragma("unroll") for (int n = 0; n < 2; ++n) _Pragma("unroll") for (int k = 0; k < 2; ++k) \
;         acc[ai][bj][m][n] = __builtin_amdgcn_mfma_f32_16x16x32_bf16(Bt[n][k], At[m][k], acc[ai][bj][m][n], 0, 0, 0); __builtin_amdgcn_s_setprio(0); } while (0)
; #define PG8_WAIT_V(n) asm volatile("s_waitcnt vmcnt(" #n ")" ::: "memory")
; #define PG8_WAIT_L(n) asm volatile("s_waitcnt lgkmcnt(" #n ")" ::: "memory")
; #define PG8_BAR __builtin_amdgcn_s_barrier()
; #define PG8_SCHED __builtin_amdgcn_sched_barrier(0)
; template <class Epi, class Sched, int LDA, int LDB, bool ALIGN_EPI = true>
; __device__ __forceinline__ void gemm_phase(LAS unsigned char* lds, const Gemm g, const Sched& S, const Epi& E, int wave) {
;     ...
;             PG8_LDA(At, 1, 1); PG8_STAGE(PG8_SB(1, 0), b3, voffB); PG8_STAGE(PG8_SB(1, 1), b3 + hstepB, voffB); PG8_STAGE(PG8_SA(1, 0), a3, voffA);
;             PG8_WAIT_V(8); PG8_WAIT_L(0); PG8_BAR; PG8_MMA(1, 0, At, B0); PG8_MMA(1, 1, At, B1); PG8_BAR; PG8_SCHED;
;         }
;         if constexpr (ALIGN_EPI) { if (wr == 0) PG8_BAR; }
	s_setprio 0
	s_add_i32 s14, s39, s47
	v_lshl_add_u64 v[140:141], v[140:141], 0, s[48:49]
	s_mov_b32 m0, s14
	ds_read_b128 v[184:187], v145 offset:49152
	ds_read_b128 v[188:191], v145 offset:50176
	ds_read_b128 v[192:195], v145 offset:51200
	ds_read_b128 v[196:199], v145 offset:52224
	ds_read_b128 v[200:203], v145 offset:53248
	ds_read_b128 v[204:207], v145 offset:54272
	ds_read_b128 v[208:211], v145 offset:55296
	ds_read_b128 v[212:215], v145 offset:56320
	global_load_lds_dwordx4 v[140:141], off
	s_add_i32 m0, s14, 0x2000
	s_add_u32 s12, s12, 0x84080
	v_lshl_add_u64 v[140:141], v[174:175], 0, s[48:49]
	s_addc_u32 s13, s13, 0
	s_add_i32 s14, s44, s47
	global_load_lds_dwordx4 v[140:141], off
	v_lshl_add_u64 v[140:141], s[12:13], 0, v[0:1]
	s_mov_b32 m0, s14
	s_nop 0
	global_load_lds_dwordx4 v[140:141], off
	v_lshl_add_u64 v[140:141], s[12:13], 0, v[134:135]
	s_add_i32 m0, s14, 0x2000
	s_nop 0
	global_load_lds_dwordx4 v[140:141], off
	v_lshl_add_u64 v[140:141], v[216:217], 0, s[48:49]
	s_mov_b32 m0, s26
	s_nop 0
	global_load_lds_dwordx4 v[140:141], off
	v_lshl_add_u64 v[140:141], v[218:219], 0, s[48:49]
	s_mov_b32 m0, s27
	s_nop 0
	global_load_lds_dwordx4 v[140:141], off
	s_waitcnt vmcnt(8)
	s_waitcnt lgkmcnt(0)
	s_setprio 3
	s_barrier
	v_mfma_f32_16x16x32_bf16 v[62:65], v[146:149], v[184:187], v[62:65]
	v_mfma_f32_16x16x32_bf16 v[58:61], v[154:157], v[184:187], v[58:61]
	v_mfma_f32_16x16x32_bf16 v[50:53], v[146:149], v[192:195], v[50:53]
	v_mfma_f32_16x16x32_bf16 v[42:45], v[154:157], v[192:195], v[42:45]
	v_mfma_f32_16x16x32_bf16 v[34:37], v[146:149], v[200:203], v[34:37]
	v_mfma_f32_16x16x32_bf16 v[26:29], v[154:157], v[200:203], v[26:29]
	v_mfma_f32_16x16x32_bf16 v[18:21], v[146:149], v[208:211], v[18:21]
	v_mfma_f32_16x16x32_bf16 v[10:13], v[154:157], v[208:211], v[10:13]
	v_mfma_f32_16x16x32_bf16 v[62:65], v[150:153], v[188:191], v[62:65]
	v_mfma_f32_16x16x32_bf16 v[58:61], v[158:161], v[188:191], v[58:61]
	v_mfma_f32_16x16x32_bf16 v[50:53], v[150:153], v[196:199], v[50:53]
	v_mfma_f32_16x16x32_bf16 v[42:45], v[158:161], v[196:199], v[42:45]
	v_mfma_f32_16x16x32_bf16 v[34:37], v[150:153], v[204:207], v[34:37]
	v_mfma_f32_16x16x32_bf16 v[26:29], v[158:161], v[204:207], v[26:29]
	v_mfma_f32_16x16x32_bf16 v[18:21], v[150:153], v[212:215], v[18:21]
	v_mfma_f32_16x16x32_bf16 v[10:13], v[158:161], v[212:215], v[10:13]
	v_mfma_f32_16x16x32_bf16 v[54:57], v[162:165], v[184:187], v[54:57]
	v_mfma_f32_16x16x32_bf16 v[46:49], v[170:173], v[184:187], v[46:49]
	v_mfma_f32_16x16x32_bf16 v[38:41], v[162:165], v[192:195], v[38:41]
	v_mfma_f32_16x16x32_bf16 v[30:33], v[170:173], v[192:195], v[30:33]
	v_mfma_f32_16x16x32_bf16 v[22:25], v[162:165], v[200:203], v[22:25]
	v_mfma_f32_16x16x32_bf16 v[14:17], v[170:173], v[200:203], v[14:17]
	v_mfma_f32_16x16x32_bf16 v[6:9], v[162:165], v[208:211], v[6:9]
	v_mfma_f32_16x16x32_bf16 v[2:5], v[170:173], v[208:211], v[2:5]
	v_mfma_f32_16x16x32_bf16 v[54:57], v[166:169], v[188:191], v[54:57]
	v_mfma_f32_16x16x32_bf16 v[46:49], v[180:183], v[188:191], v[46:49]
	v_mfma_f32_16x16x32_bf16 v[38:41], v[166:169], v[196:199], v[38:41]
	v_mfma_f32_16x16x32_bf16 v[30:33], v[180:183], v[196:199], v[30:33]
	v_mfma_f32_16x16x32_bf16 v[22:25], v[166:169], v[204:207], v[22:25]
	v_mfma_f32_16x16x32_bf16 v[14:17], v[180:183], v[204:207], v[14:17]
	v_mfma_f32_16x16x32_bf16 v[6:9], v[166:169], v[212:215], v[6:9]
	v_mfma_f32_16x16x32_bf16 v[2:5], v[180:183], v[212:215], v[2:5]
	s_barrier
	s_setprio 0
	s_add_i32 s38, s38, 2
	s_add_u32 s10, s10, 0x100
	s_addc_u32 s11, s11, 0
	s_add_u32 s36, s36, 0x100
	s_addc_u32 s37, s37, 0
	s_cmp_gt_u32 s38, 29
	s_cbranch_scc0 .LBB0_2415
	v_readlane_b32 s10, v252, 14
	v_readlane_b32 s11, v252, 15
	s_and_b64 vcc, exec, s[10:11]
	s_cbranch_vccz .LBB0_2418
	s_barrier

; #define PG8_STAGE(bufoff, gbase, voff) do { _Pragma("unroll") for (int _i = 0; _i < 2; ++_i) \
;         __builtin_amdgcn_global_load_lds((const unsigned*)((const char*)(gbase) + (voff)[_i]), (LAS unsigned*)(lds + (bufoff) + ldsw + _i * 8192), 16, 0, 0); } while (0)
; #define PG8_LDA(dst, b, h) do { _Pragma("unroll") for (int m = 0; m < 4; ++m) _Pragma("unroll") for (int k = 0; k < 2; ++k) dst[m][k] = *(const LAS bf16x8*)(lds + PG8_SA(b, h) + aoff + m * 2048 + k * 1024); } while (0)
; #define PG8_LDB(dst, b, h) do { _Pragma("unroll") for (int n = 0; n < 2; ++n) _Pragma("unroll") for (int k = 0; k < 2; ++k) dst[n][k] = *(const LAS bf16x8*)(lds + PG8_SB(b, h) + boff + n * 2048 + k * 1024); } while (0)
; #define PG8_MMA(ai, bj, At, Bt) do { __builtin_amdgcn_s_setprio(1); _Pragma("unroll") for (int m = 0; m < 4; ++m) _Pragma("unroll") for (int n = 0; n < 2; ++n) _Pragma("unroll") for (int k = 0; k < 2; ++k) \
;         acc[ai][bj][m][n] = __builtin_amdgcn_mfma_f32_16x16x32_bf16(Bt[n][k], At[m][k], acc[ai][bj][m][n], 0, 0, 0); __builtin_amdgcn_s_setprio(0); } while (0)
; #define PG8_WAIT_V(n) asm volatile("s_waitcnt vmcnt(" #n ")" ::: "memory")
; #define PG8_WAIT_L(n) asm volatile("s_waitcnt lgkmcnt(" #n ")" ::: "memory")
; #define PG8_BAR __builtin_amdgcn_s_barrier()
; template <class Epi, class Sched, int LDA, int LDB, bool ALIGN_EPI = true>
; __device__ __forceinline__ void gemm_phase(LAS unsigned char* lds, const Gemm g, const Sched& S, const Epi& E, int wave) {
;     ...
;         for (int t = 0; t < nt; t += 2) {
;             const bool last = (t == nt - 2);
;             const char* a1 = cA + (size_t)(t + 1) * kstep;
;             const char* a2 = last ? nA : cA + (size_t)(t + 2) * kstep; const char* b2 = last ? nB : cB + (size_t)(t + 2) * kstep;
;             const char* a3 = a2 + kstep; const char* b3 = b2 + kstep;
;             PG8_LDB(B0, 0, 0); PG8_LDB(B1, 0, 1); PG8_SCHED; PG8_LDA(At, 0, 0); PG8_STAGE(PG8_SA(1, 1), a1 + hstepA, voffA);
;             PG8_WAIT_V(8); PG8_WAIT_L(0); PG8_BAR; PG8_MMA(0, 0, At, B0); PG8_MMA(0, 1, At, B1); PG8_BAR; PG8_SCHED;
;             PG8_LDA(At, 0, 1); PG8_STAGE(PG8_SB(0, 0), b2, voffB); PG8_STAGE(PG8_SB(0, 1), b2 + hstepB, voffB); PG8_STAGE(PG8_SA(0, 0), a2, voffA);
;             PG8_WAIT_V(8); PG8_WAIT_L(0); PG8_BAR; PG8_MMA(1, 0, At, B0); PG8_MMA(1, 1, At, B1); PG8_BAR; PG8_SCHED;
.LBB0_2513:
	s_add_u32 s14, s12, 0xfff80080
	s_addc_u32 s15, s13, -1
	s_add_i32 s44, 0, 0x10000
	s_cmp_eq_u32 s39, 28
	s_cselect_b32 s17, s1, s15
	s_cselect_b32 s16, s3, s14
	v_add_u32_e32 v140, s44, v143
	s_cselect_b32 s15, s9, s38
	s_cselect_b32 s14, s8, s37
	s_add_i32 s46, 0, 0x14000
	ds_read_b128 v[146:149], v140
	ds_read_b128 v[150:153], v140 offset:1024
	ds_read_b128 v[154:157], v140 offset:2048
	ds_read_b128 v[158:161], v140 offset:3072
	v_add_u32_e32 v140, s46, v143
	ds_read_b128 v[162:165], v140
	ds_read_b128 v[166:169], v140 offset:1024
	ds_read_b128 v[170:173], v140 offset:2048
	ds_read_b128 v[180:183], v140 offset:3072
	v_lshl_add_u64 v[140:141], s[12:13], 0, v[136:137]
	s_add_i32 m0, s24, 0xc000
	ds_read_b128 v[184:187], v145
	ds_read_b128 v[188:191], v145 offset:1024
	ds_read_b128 v[192:195], v145 offset:2048
	ds_read_b128 v[196:199], v145 offset:3072
	ds_read_b128 v[200:203], v145 offset:4096
	ds_read_b128 v[204:207], v145 offset:5120
	ds_read_b128 v[208:211], v145 offset:6144
	ds_read_b128 v[212:215], v145 offset:7168
	global_load_lds_dwordx4 v[140:141], off
	v_lshl_add_u64 v[140:141], s[12:13], 0, v[138:139]
	s_add_i32 m0, s24, 0xe000
	s_nop 0
	global_load_lds_dwordx4 v[140:141], off
	s_waitcnt vmcnt(8)
	s_waitcnt lgkmcnt(0)
	s_setprio 3
	s_barrier
	v_mfma_f32_16x16x32_bf16 v[126:129], v[146:149], v[184:187], v[126:129]
	v_mfma_f32_16x16x32_bf16 v[122:125], v[154:157], v[184:187], v[122:125]
	v_mfma_f32_16x16x32_bf16 v[114:117], v[146:149], v[192:195], v[114:117]
	v_mfma_f32_16x16x32_bf16 v[106:109], v[154:157], v[192:195], v[106:109]
	v_mfma_f32_16x16x32_bf16 v[98:101], v[146:149], v[200:203], v[98:101]
	v_mfma_f32_16x16x32_bf16 v[90:93], v[154:157], v[200:203], v[90:93]
	v_mfma_f32_16x16x32_bf16 v[82:85], v[146:149], v[208:211], v[82:85]
	v_mfma_f32_16x16x32_bf16 v[74:77], v[154:157], v[208:211], v[74:77]
	v_mfma_f32_16x16x32_bf16 v[126:129], v[150:153], v[188:191], v[126:129]
	v_mfma_f32_16x16x32_bf16 v[122:125], v[158:161], v[188:191], v[122:125]
	v_mfma_f32_16x16x32_bf16 v[114:117], v[150:153], v[196:199], v[114:117]
	v_mfma_f32_16x16x32_bf16 v[106:109], v[158:161], v[196:199], v[106:109]
	v_mfma_f32_16x16x32_bf16 v[98:101], v[150:153], v[204:207], v[98:101]
	v_mfma_f32_16x16x32_bf16 v[90:93], v[158:161], v[204:207], v[90:93]
	v_mfma_f32_16x16x32_bf16 v[82:85], v[150:153], v[212:215], v[82:85]
	v_mfma_f32_16x16x32_bf16 v[74:77], v[158:161], v[212:215], v[74:77]
	v_mfma_f32_16x16x32_bf16 v[118:121], v[162:165], v[184:187], v[118:121]
	v_mfma_f32_16x16x32_bf16 v[110:113], v[170:173], v[184:187], v[110:113]
	v_mfma_f32_16x16x32_bf16 v[102:105], v[162:165], v[192:195], v[102:105]
	v_mfma_f32_16x16x32_bf16 v[94:97], v[170:173], v[192:195], v[94:97]
	v_mfma_f32_16x16x32_bf16 v[86:89], v[162:165], v[200:203], v[86:89]
	v_mfma_f32_16x16x32_bf16 v[78:81], v[170:173], v[200:203], v[78:81]
	v_mfma_f32_16x16x32_bf16 v[70:73], v[162:165], v[208:211], v[70:73]
	v_mfma_f32_16x16x32_bf16 v[66:69], v[170:173], v[208:211], v[66:69]
	v_mfma_f32_16x16x32_bf16 v[118:121], v[166:169], v[188:191], v[118:121]
	v_mfma_f32_16x16x32_bf16 v[110:113], v[180:183], v[188:191], v[110:113]
	v_mfma_f32_16x16x32_bf16 v[102:105], v[166:169], v[196:199], v[102:105]
	v_mfma_f32_16x16x32_bf16 v[94:97], v[180:183], v[196:199], v[94:97]
	v_mfma_f32_16x16x32_bf16 v[86:89], v[166:169], v[204:207], v[86:89]
	v_mfma_f32_16x16x32_bf16 v[78:81], v[180:183], v[204:207], v[78:81]
	v_mfma_f32_16x16x32_bf16 v[70:73], v[166:169], v[212:215], v[70:73]
	v_mfma_f32_16x16x32_bf16 v[66:69], v[180:183], v[212:215], v[66:69]
	s_barrier
	s_setprio 0
	s_add_i32 s44, s44, s47
	v_lshl_add_u64 v[140:141], s[14:15], 0, v[0:1]
	s_mov_b32 m0, s44
	ds_read_b128 v[184:187], v145 offset:16384
	ds_read_b128 v[188:191], v145 offset:17408
	ds_read_b128 v[192:195], v145 offset:18432
	ds_read_b128 v[196:199], v145 offset:19456
	ds_read_b128 v[200:203], v145 offset:20480
	ds_read_b128 v[204:207], v145 offset:21504
	ds_read_b128 v[208:211], v145 offset:22528
	ds_read_b128 v[212:215], v145 offset:23552
	global_load_lds_dwordx4 v[140:141], off
	s_add_i32 m0, s44, 0x2000
	s_add_u32 s44, s14, 0x84000
	v_lshl_add_u64 v[174:175], s[14:15], 0, v[134:135]
	s_addc_u32 s45, s15, 0
	s_add_i32 s46, s46, s47
	global_load_lds_dwordx4 v[174:175], off
	v_lshl_add_u64 v[216:217], s[44:45], 0, v[0:1]
	s_mov_b32 m0, s46
	v_lshl_add_u64 v[218:219], s[16:17], 0, v[132:133]
	global_load_lds_dwordx4 v[216:217], off
	v_lshl_add_u64 v[216:217], s[44:45], 0, v[134:135]
	s_add_i32 m0, s46, 0x2000
	s_nop 0
	global_load_lds_dwordx4 v[216:217], off
	v_lshl_add_u64 v[216:217], s[16:17], 0, v[130:131]
	s_mov_b32 m0, s24
	s_nop 0
	global_load_lds_dwordx4 v[216:217], off
	s_mov_b32 m0, s25
	s_nop 0
	global_load_lds_dwordx4 v[218:219], off
	s_waitcnt vmcnt(8)
	s_waitcnt lgkmcnt(0)
	s_setprio 3
	s_barrier
; #define PG8_STAGE(bufoff, gbase, voff) do { _Pragma("unroll") for (int _i = 0; _i < 2; ++_i) \
;         __builtin_amdgcn_global_load_lds((const unsigned*)((const char*)(gbase) + (voff)[_i]), (LAS unsigned*)(lds + (bufoff) + ldsw + _i * 8192), 16, 0, 0); } while (0)
; #define PG8_LDA(dst, b, h) do { _Pragma("unroll") for (int m = 0; m < 4; ++m) _Pragma("unroll") for (int k = 0; k < 2; ++k) dst[m][k] = *(const LAS bf16x8*)(lds + PG8_SA(b, h) + aoff + m * 2048 + k * 1024); } while (0)
; #define PG8_LDB(dst, b, h) do { _Pragma("unroll") for (int n = 0; n < 2; ++n) _Pragma("unroll") for (int k = 0; k < 2; ++k) dst[n][k] = *(const LAS bf16x8*)(lds + PG8_SB(b, h) + boff + n * 2048 + k * 1024); } while (0)
; #define PG8_MMA(ai, bj, At, Bt) do { __builtin_amdgcn_s_setprio(1); _Pragma("unroll") for (int m = 0; m < 4; ++m) _Pragma("unroll") for (int n = 0; n < 2; ++n) _Pragma("unroll") for (int k = 0; k < 2; ++k) \
;         acc[ai][bj][m][n] = __builtin_amdgcn_mfma_f32_16x16x32_bf16(Bt[n][k], At[m][k], acc[ai][bj][m][n], 0, 0, 0); __builtin_amdgcn_s_setprio(0); } while (0)
; #define PG8_WAIT_V(n) asm volatile("s_waitcnt vmcnt(" #n ")" ::: "memory")
; #define PG8_WAIT_L(n) asm volatile("s_waitcnt lgkmcnt(" #n ")" ::: "memory")
; #define PG8_BAR __builtin_amdgcn_s_barrier()
; #define PG8_SCHED __builtin_amdgcn_sched_barrier(0)
; template <class Epi, class Sched, int LDA, int LDB, bool ALIGN_EPI = true>
; __device__ __forceinline__ void gemm_phase(LAS unsigned char* lds, const Gemm g, const Sched& S, const Epi& E, int wave) {
;     ...
;             PG8_WAIT_V(8); PG8_WAIT_L(0); PG8_BAR; PG8_MMA(1, 0, At, B0); PG8_MMA(1, 1, At, B1); PG8_BAR; PG8_SCHED;
;             PG8_LDB(B0, 1, 0); PG8_LDB(B1, 1, 1); PG8_SCHED; PG8_LDA(At, 1, 0); PG8_STAGE(PG8_SA(0, 1), a2 + hstepA, voffA);
;             PG8_WAIT_V(8); PG8_WAIT_L(0); PG8_BAR; PG8_MMA(0, 0, At, B0); PG8_MMA(0, 1, At, B1); PG8_BAR; PG8_SCHED;
	v_mfma_f32_16x16x32_bf16 v[62:65], v[146:149], v[184:187], v[62:65]
	v_mfma_f32_16x16x32_bf16 v[58:61], v[154:157], v[184:187], v[58:61]
	v_mfma_f32_16x16x32_bf16 v[50:53], v[146:149], v[192:195], v[50:53]
	v_mfma_f32_16x16x32_bf16 v[42:45], v[154:157], v[192:195], v[42:45]
	v_mfma_f32_16x16x32_bf16 v[34:37], v[146:149], v[200:203], v[34:37]
	v_mfma_f32_16x16x32_bf16 v[26:29], v[154:157], v[200:203], v[26:29]
	v_mfma_f32_16x16x32_bf16 v[18:21], v[146:149], v[208:211], v[18:21]
	v_mfma_f32_16x16x32_bf16 v[10:13], v[154:157], v[208:211], v[10:13]
	v_mfma_f32_16x16x32_bf16 v[62:65], v[150:153], v[188:191], v[62:65]
	v_mfma_f32_16x16x32_bf16 v[58:61], v[158:161], v[188:191], v[58:61]
	v_mfma_f32_16x16x32_bf16 v[50:53], v[150:153], v[196:199], v[50:53]
	v_mfma_f32_16x16x32_bf16 v[42:45], v[158:161], v[196:199], v[42:45]
	v_mfma_f32_16x16x32_bf16 v[34:37], v[150:153], v[204:207], v[34:37]
	v_mfma_f32_16x16x32_bf16 v[26:29], v[158:161], v[204:207], v[26:29]
	v_mfma_f32_16x16x32_bf16 v[18:21], v[150:153], v[212:215], v[18:21]
	v_mfma_f32_16x16x32_bf16 v[10:13], v[158:161], v[212:215], v[10:13]
	v_mfma_f32_16x16x32_bf16 v[54:57], v[162:165], v[184:187], v[54:57]
	v_mfma_f32_16x16x32_bf16 v[46:49], v[170:173], v[184:187], v[46:49]
	v_mfma_f32_16x16x32_bf16 v[38:41], v[162:165], v[192:195], v[38:41]
	v_mfma_f32_16x16x32_bf16 v[30:33], v[170:173], v[192:195], v[30:33]
	v_mfma_f32_16x16x32_bf16 v[22:25], v[162:165], v[200:203], v[22:25]
	v_mfma_f32_16x16x32_bf16 v[14:17], v[170:173], v[200:203], v[14:17]
	v_mfma_f32_16x16x32_bf16 v[6:9], v[162:165], v[208:211], v[6:9]
	v_mfma_f32_16x16x32_bf16 v[2:5], v[170:173], v[208:211], v[2:5]
	v_mfma_f32_16x16x32_bf16 v[54:57], v[166:169], v[188:191], v[54:57]
	v_mfma_f32_16x16x32_bf16 v[46:49], v[180:183], v[188:191], v[46:49]
	v_mfma_f32_16x16x32_bf16 v[38:41], v[166:169], v[196:199], v[38:41]
	v_mfma_f32_16x16x32_bf16 v[30:33], v[180:183], v[196:199], v[30:33]
	v_mfma_f32_16x16x32_bf16 v[22:25], v[166:169], v[204:207], v[22:25]
	v_mfma_f32_16x16x32_bf16 v[14:17], v[180:183], v[204:207], v[14:17]
	v_mfma_f32_16x16x32_bf16 v[6:9], v[166:169], v[212:215], v[6:9]
	v_mfma_f32_16x16x32_bf16 v[2:5], v[180:183], v[212:215], v[2:5]
	s_barrier
	s_setprio 0
	s_add_i32 s44, 0, 0x18000
	s_add_i32 s45, 0, 0x1c000
	v_add_u32_e32 v158, s44, v143
	v_add_u32_e32 v180, s45, v143
	ds_read_b128 v[146:149], v158
	ds_read_b128 v[150:153], v158 offset:1024
	ds_read_b128 v[154:157], v158 offset:2048
	ds_read_b128 v[158:161], v158 offset:3072
	ds_read_b128 v[162:165], v180
	ds_read_b128 v[166:169], v180 offset:1024
	ds_read_b128 v[170:173], v180 offset:2048
	ds_read_b128 v[180:183], v180 offset:3072
	s_add_u32 s16, s16, 0x80000
	s_addc_u32 s17, s17, 0
	s_mov_b32 m0, s26
	v_lshl_add_u64 v[220:221], s[16:17], 0, v[130:131]
	ds_read_b128 v[184:187], v145 offset:32768
	ds_read_b128 v[188:191], v145 offset:33792
	ds_read_b128 v[192:195], v145 offset:34816
	ds_read_b128 v[196:199], v145 offset:35840
	ds_read_b128 v[200:203], v145 offset:36864
	ds_read_b128 v[204:207], v145 offset:37888
	ds_read_b128 v[208:211], v145 offset:38912
	ds_read_b128 v[212:215], v145 offset:39936
	global_load_lds_dwordx4 v[220:221], off
	v_lshl_add_u64 v[220:221], s[16:17], 0, v[132:133]
	s_mov_b32 m0, s27
	s_nop 0
	global_load_lds_dwordx4 v[220:221], off
	s_waitcnt vmcnt(8)
	s_waitcnt lgkmcnt(0)
	s_setprio 3
	s_barrier
	v_mfma_f32_16x16x32_bf16 v[126:129], v[146:149], v[184:187], v[126:129]
	v_mfma_f32_16x16x32_bf16 v[122:125], v[154:157], v[184:187], v[122:125]
	v_mfma_f32_16x16x32_bf16 v[114:117], v[146:149], v[192:195], v[114:117]
	v_mfma_f32_16x16x32_bf16 v[106:109], v[154:157], v[192:195], v[106:109]
	v_mfma_f32_16x16x32_bf16 v[98:101], v[146:149], v[200:203], v[98:101]
	v_mfma_f32_16x16x32_bf16 v[90:93], v[154:157], v[200:203], v[90:93]
	v_mfma_f32_16x16x32_bf16 v[82:85], v[146:149], v[208:211], v[82:85]
	v_mfma_f32_16x16x32_bf16 v[74:77], v[154:157], v[208:211], v[74:77]
	v_mfma_f32_16x16x32_bf16 v[126:129], v[150:153], v[188:191], v[126:129]
	v_mfma_f32_16x16x32_bf16 v[122:125], v[158:161], v[188:191], v[122:125]
	v_mfma_f32_16x16x32_bf16 v[114:117], v[150:153], v[196:199], v[114:117]
	v_mfma_f32_16x16x32_bf16 v[106:109], v[158:161], v[196:199], v[106:109]
	v_mfma_f32_16x16x32_bf16 v[98:101], v[150:153], v[204:207], v[98:101]
	v_mfma_f32_16x16x32_bf16 v[90:93], v[158:161], v[204:207], v[90:93]
	v_mfma_f32_16x16x32_bf16 v[82:85], v[150:153], v[212:215], v[82:85]
	v_mfma_f32_16x16x32_bf16 v[74:77], v[158:161], v[212:215], v[74:77]
	v_mfma_f32_16x16x32_bf16 v[118:121], v[162:165], v[184:187], v[118:121]
	v_mfma_f32_16x16x32_bf16 v[110:113], v[170:173], v[184:187], v[110:113]
	v_mfma_f32_16x16x32_bf16 v[102:105], v[162:165], v[192:195], v[102:105]
	v_mfma_f32_16x16x32_bf16 v[94:97], v[170:173], v[192:195], v[94:97]
	v_mfma_f32_16x16x32_bf16 v[86:89], v[162:165], v[200:203], v[86:89]
	v_mfma_f32_16x16x32_bf16 v[78:81], v[170:173], v[200:203], v[78:81]
	v_mfma_f32_16x16x32_bf16 v[70:73], v[162:165], v[208:211], v[70:73]
	v_mfma_f32_16x16x32_bf16 v[66:69], v[170:173], v[208:211], v[66:69]
	v_mfma_f32_16x16x32_bf16 v[118:121], v[166:169], v[188:191], v[118:121]
	v_mfma_f32_16x16x32_bf16 v[110:113], v[180:183], v[188:191], v[110:113]
	v_mfma_f32_16x16x32_bf16 v[102:105], v[166:169], v[196:199], v[102:105]
	v_mfma_f32_16x16x32_bf16 v[94:97], v[180:183], v[196:199], v[94:97]
	v_mfma_f32_16x16x32_bf16 v[86:89], v[166:169], v[204:207], v[86:89]
	v_mfma_f32_16x16x32_bf16 v[78:81], v[180:183], v[204:207], v[78:81]
	v_mfma_f32_16x16x32_bf16 v[70:73], v[166:169], v[212:215], v[70:73]
	v_mfma_f32_16x16x32_bf16 v[66:69], v[180:183], v[212:215], v[66:69]
	s_barrier
; #define PG8_STAGE(bufoff, gbase, voff) do { _Pragma("unroll") for (int _i = 0; _i < 2; ++_i) \
;         __builtin_amdgcn_global_load_lds((const unsigned*)((const char*)(gbase) + (voff)[_i]), (LAS unsigned*)(lds + (bufoff) + ldsw + _i * 8192), 16, 0, 0); } while (0)
; #define PG8_LDA(dst, b, h) do { _Pragma("unroll") for (int m = 0; m < 4; ++m) _Pragma("unroll") for (int k = 0; k < 2; ++k) dst[m][k] = *(const LAS bf16x8*)(lds + PG8_SA(b, h) + aoff + m * 2048 + k * 1024); } while (0)
; #define PG8_MMA(ai, bj, At, Bt) do { __builtin_amdgcn_s_setprio(1); _Pragma("unroll") for (int m = 0; m < 4; ++m) _Pragma("unroll") for (int n = 0; n < 2; ++n) _Pragma("unroll") for (int k = 0; k < 2; ++k) \
;         acc[ai][bj][m][n] = __builtin_amdgcn_mfma_f32_16x16x32_bf16(Bt[n][k], At[m][k], acc[ai][bj][m][n], 0, 0, 0); __builtin_amdgcn_s_setprio(0); } while (0)
; #define PG8_WAIT_V(n) asm volatile("s_waitcnt vmcnt(" #n ")" ::: "memory")
; #define PG8_WAIT_L(n) asm volatile("s_waitcnt lgkmcnt(" #n ")" ::: "memory")
; #define PG8_BAR __builtin_amdgcn_s_barrier()
; #define PG8_SCHED __builtin_amdgcn_sched_barrier(0)
; template <class Epi, class Sched, int LDA, int LDB, bool ALIGN_EPI = true>
; __device__ __forceinline__ void gemm_phase(LAS unsigned char* lds, const Gemm g, const Sched& S, const Epi& E, int wave) {
;     ...
;             PG8_LDA(At, 1, 1); PG8_STAGE(PG8_SB(1, 0), b3, voffB); PG8_STAGE(PG8_SB(1, 1), b3 + hstepB, voffB); PG8_STAGE(PG8_SA(1, 0), a3, voffA);
;             PG8_WAIT_V(8); PG8_WAIT_L(0); PG8_BAR; PG8_MMA(1, 0, At, B0); PG8_MMA(1, 1, At, B1); PG8_BAR; PG8_SCHED;
;         }
;         if constexpr (ALIGN_EPI) { if (wr == 0) PG8_BAR; }
	s_setprio 0
	s_add_i32 s16, s44, s47
	v_lshl_add_u64 v[140:141], v[140:141], 0, s[72:73]
	s_mov_b32 m0, s16
	ds_read_b128 v[184:187], v145 offset:49152
	ds_read_b128 v[188:191], v145 offset:50176
	ds_read_b128 v[192:195], v145 offset:51200
	ds_read_b128 v[196:199], v145 offset:52224
	ds_read_b128 v[200:203], v145 offset:53248
	ds_read_b128 v[204:207], v145 offset:54272
	ds_read_b128 v[208:211], v145 offset:55296
	ds_read_b128 v[212:215], v145 offset:56320
	global_load_lds_dwordx4 v[140:141], off
	s_add_i32 m0, s16, 0x2000
	s_add_u32 s14, s14, 0x84080
	v_lshl_add_u64 v[140:141], v[174:175], 0, s[72:73]
	s_addc_u32 s15, s15, 0
	s_add_i32 s16, s45, s47
	global_load_lds_dwordx4 v[140:141], off
	v_lshl_add_u64 v[140:141], s[14:15], 0, v[0:1]
	s_mov_b32 m0, s16
	s_nop 0
	global_load_lds_dwordx4 v[140:141], off
	v_lshl_add_u64 v[140:141], s[14:15], 0, v[134:135]
	s_add_i32 m0, s16, 0x2000
	s_nop 0
	global_load_lds_dwordx4 v[140:141], off
	v_lshl_add_u64 v[140:141], v[216:217], 0, s[72:73]
	s_mov_b32 m0, s28
	s_nop 0
	global_load_lds_dwordx4 v[140:141], off
	v_lshl_add_u64 v[140:141], v[218:219], 0, s[72:73]
	s_mov_b32 m0, s29
	s_nop 0
	global_load_lds_dwordx4 v[140:141], off
	s_waitcnt vmcnt(8)
	s_waitcnt lgkmcnt(0)
	s_setprio 3
	s_barrier
	v_mfma_f32_16x16x32_bf16 v[62:65], v[146:149], v[184:187], v[62:65]
	v_mfma_f32_16x16x32_bf16 v[58:61], v[154:157], v[184:187], v[58:61]
	v_mfma_f32_16x16x32_bf16 v[50:53], v[146:149], v[192:195], v[50:53]
	v_mfma_f32_16x16x32_bf16 v[42:45], v[154:157], v[192:195], v[42:45]
	v_mfma_f32_16x16x32_bf16 v[34:37], v[146:149], v[200:203], v[34:37]
	v_mfma_f32_16x16x32_bf16 v[26:29], v[154:157], v[200:203], v[26:29]
	v_mfma_f32_16x16x32_bf16 v[18:21], v[146:149], v[208:211], v[18:21]
	v_mfma_f32_16x16x32_bf16 v[10:13], v[154:157], v[208:211], v[10:13]
	v_mfma_f32_16x16x32_bf16 v[62:65], v[150:153], v[188:191], v[62:65]
	v_mfma_f32_16x16x32_bf16 v[58:61], v[158:161], v[188:191], v[58:61]
	v_mfma_f32_16x16x32_bf16 v[50:53], v[150:153], v[196:199], v[50:53]
	v_mfma_f32_16x16x32_bf16 v[42:45], v[158:161], v[196:199], v[42:45]
	v_mfma_f32_16x16x32_bf16 v[34:37], v[150:153], v[204:207], v[34:37]
	v_mfma_f32_16x16x32_bf16 v[26:29], v[158:161], v[204:207], v[26:29]
	v_mfma_f32_16x16x32_bf16 v[18:21], v[150:153], v[212:215], v[18:21]
	v_mfma_f32_16x16x32_bf16 v[10:13], v[158:161], v[212:215], v[10:13]
	v_mfma_f32_16x16x32_bf16 v[54:57], v[162:165], v[184:187], v[54:57]
	v_mfma_f32_16x16x32_bf16 v[46:49], v[170:173], v[184:187], v[46:49]
	v_mfma_f32_16x16x32_bf16 v[38:41], v[162:165], v[192:195], v[38:41]
	v_mfma_f32_16x16x32_bf16 v[30:33], v[170:173], v[192:195], v[30:33]
	v_mfma_f32_16x16x32_bf16 v[22:25], v[162:165], v[200:203], v[22:25]
	v_mfma_f32_16x16x32_bf16 v[14:17], v[170:173], v[200:203], v[14:17]
	v_mfma_f32_16x16x32_bf16 v[6:9], v[162:165], v[208:211], v[6:9]
	v_mfma_f32_16x16x32_bf16 v[2:5], v[170:173], v[208:211], v[2:5]
	v_mfma_f32_16x16x32_bf16 v[54:57], v[166:169], v[188:191], v[54:57]
	v_mfma_f32_16x16x32_bf16 v[46:49], v[180:183], v[188:191], v[46:49]
	v_mfma_f32_16x16x32_bf16 v[38:41], v[166:169], v[196:199], v[38:41]
	v_mfma_f32_16x16x32_bf16 v[30:33], v[180:183], v[196:199], v[30:33]
	v_mfma_f32_16x16x32_bf16 v[22:25], v[166:169], v[204:207], v[22:25]
	v_mfma_f32_16x16x32_bf16 v[14:17], v[180:183], v[204:207], v[14:17]
	v_mfma_f32_16x16x32_bf16 v[6:9], v[166:169], v[212:215], v[6:9]
	v_mfma_f32_16x16x32_bf16 v[2:5], v[180:183], v[212:215], v[2:5]
	s_barrier
	s_setprio 0
	s_add_i32 s39, s39, 2
	s_add_u32 s12, s12, 0x100
	s_addc_u32 s13, s13, 0
	s_add_u32 s37, s37, 0x100
	s_addc_u32 s38, s38, 0
	s_cmp_gt_u32 s39, 29
	s_cbranch_scc0 .LBB0_2513
	v_readlane_b32 s12, v252, 14
	v_readlane_b32 s13, v252, 15
	s_and_b64 vcc, exec, s[12:13]
	s_cbranch_vccz .LBB0_2516
	s_barrier

; #define PG8_STAGE(bufoff, gbase, voff) do { _Pragma("unroll") for (int _i = 0; _i < 2; ++_i) \
;         __builtin_amdgcn_global_load_lds((const unsigned*)((const char*)(gbase) + (voff)[_i]), (LAS unsigned*)(lds + (bufoff) + ldsw + _i * 8192), 16, 0, 0); } while (0)
; #define PG8_LDA(dst, b, h) do { _Pragma("unroll") for (int m = 0; m < 4; ++m) _Pragma("unroll") for (int k = 0; k < 2; ++k) dst[m][k] = *(const LAS bf16x8*)(lds + PG8_SA(b, h) + aoff + m * 2048 + k * 1024); } while (0)
; #define PG8_LDB(dst, b, h) do { _Pragma("unroll") for (int n = 0; n < 2; ++n) _Pragma("unroll") for (int k = 0; k < 2; ++k) dst[n][k] = *(const LAS bf16x8*)(lds + PG8_SB(b, h) + boff + n * 2048 + k * 1024); } while (0)
; #define PG8_MMA(ai, bj, At, Bt) do { __builtin_amdgcn_s_setprio(1); _Pragma("unroll") for (int m = 0; m < 4; ++m) _Pragma("unroll") for (int n = 0; n < 2; ++n) _Pragma("unroll") for (int k = 0; k < 2; ++k) \
;         acc[ai][bj][m][n] = __builtin_amdgcn_mfma_f32_16x16x32_bf16(Bt[n][k], At[m][k], acc[ai][bj][m][n], 0, 0, 0); __builtin_amdgcn_s_setprio(0); } while (0)
; #define PG8_WAIT_V(n) asm volatile("s_waitcnt vmcnt(" #n ")" ::: "memory")
; #define PG8_WAIT_L(n) asm volatile("s_waitcnt lgkmcnt(" #n ")" ::: "memory")
; #define PG8_BAR __builtin_amdgcn_s_barrier()
; template <class Epi, class Sched, int LDA, int LDB, bool ALIGN_EPI = true>
; __device__ __forceinline__ void gemm_phase(LAS unsigned char* lds, const Gemm g, const Sched& S, const Epi& E, int wave) {
;     ...
;         for (int t = 0; t < nt; t += 2) {
;             const bool last = (t == nt - 2);
;             const char* a1 = cA + (size_t)(t + 1) * kstep;
;             const char* a2 = last ? nA : cA + (size_t)(t + 2) * kstep; const char* b2 = last ? nB : cB + (size_t)(t + 2) * kstep;
;             const char* a3 = a2 + kstep; const char* b3 = b2 + kstep;
;             PG8_LDB(B0, 0, 0); PG8_LDB(B1, 0, 1); PG8_SCHED; PG8_LDA(At, 0, 0); PG8_STAGE(PG8_SA(1, 1), a1 + hstepA, voffA);
;             PG8_WAIT_V(8); PG8_WAIT_L(0); PG8_BAR; PG8_MMA(0, 0, At, B0); PG8_MMA(0, 1, At, B1); PG8_BAR; PG8_SCHED;
;             PG8_LDA(At, 0, 1); PG8_STAGE(PG8_SB(0, 0), b2, voffB); PG8_STAGE(PG8_SB(0, 1), b2 + hstepB, voffB); PG8_STAGE(PG8_SA(0, 0), a2, voffA);
;             PG8_WAIT_V(8); PG8_WAIT_L(0); PG8_BAR; PG8_MMA(1, 0, At, B0); PG8_MMA(1, 1, At, B1); PG8_BAR; PG8_SCHED;
.LBB0_2551:
	s_add_u32 s2, s0, 0x100
	s_addc_u32 s3, s1, 0
	s_add_i32 s50, 0, 0x10000
	s_cmp_eq_u32 s49, 8
	s_cselect_b32 s17, s11, s3
	s_cselect_b32 s16, s10, s2
	v_add_u32_e32 v0, s50, v154
	s_cselect_b32 s15, s13, s47
	s_cselect_b32 s14, s12, s46
	s_add_i32 s51, 0, 0x14000
	ds_read_b128 v[130:133], v0
	ds_read_b128 v[148:151], v0 offset:1024
	ds_read_b128 v[158:161], v0 offset:2048
	ds_read_b128 v[162:165], v0 offset:3072
	v_add_u32_e32 v0, s51, v154
	ds_read_b128 v[166:169], v0
	ds_read_b128 v[170:173], v0 offset:1024
	ds_read_b128 v[180:183], v0 offset:2048
	ds_read_b128 v[184:187], v0 offset:3072
	v_lshl_add_u64 v[152:153], s[0:1], 0, v[144:145]
	s_add_i32 m0, s28, 0xc000
	ds_read_b128 v[188:191], v156
	ds_read_b128 v[192:195], v156 offset:1024
	ds_read_b128 v[196:199], v156 offset:2048
	ds_read_b128 v[200:203], v156 offset:3072
	ds_read_b128 v[204:207], v156 offset:4096
	ds_read_b128 v[208:211], v156 offset:5120
	ds_read_b128 v[212:215], v156 offset:6144
	ds_read_b128 v[216:219], v156 offset:7168
	global_load_lds_dwordx4 v[152:153], off
	v_lshl_add_u64 v[152:153], s[0:1], 0, v[146:147]
	s_add_i32 m0, s28, 0xe000
	s_nop 0
	global_load_lds_dwordx4 v[152:153], off
	s_waitcnt vmcnt(8)
	s_waitcnt lgkmcnt(0)
	s_setprio 3
	s_barrier
	v_mfma_f32_16x16x32_bf16 v[126:129], v[130:133], v[188:191], v[126:129]
	v_mfma_f32_16x16x32_bf16 v[122:125], v[158:161], v[188:191], v[122:125]
	v_mfma_f32_16x16x32_bf16 v[118:121], v[130:133], v[196:199], v[118:121]
	v_mfma_f32_16x16x32_bf16 v[114:117], v[158:161], v[196:199], v[114:117]
	v_mfma_f32_16x16x32_bf16 v[110:113], v[130:133], v[204:207], v[110:113]
	v_mfma_f32_16x16x32_bf16 v[106:109], v[158:161], v[204:207], v[106:109]
	v_mfma_f32_16x16x32_bf16 v[102:105], v[130:133], v[212:215], v[102:105]
	v_mfma_f32_16x16x32_bf16 v[98:101], v[158:161], v[212:215], v[98:101]
	v_mfma_f32_16x16x32_bf16 v[126:129], v[148:151], v[192:195], v[126:129]
	v_mfma_f32_16x16x32_bf16 v[122:125], v[162:165], v[192:195], v[122:125]
	v_mfma_f32_16x16x32_bf16 v[118:121], v[148:151], v[200:203], v[118:121]
	v_mfma_f32_16x16x32_bf16 v[114:117], v[162:165], v[200:203], v[114:117]
	v_mfma_f32_16x16x32_bf16 v[110:113], v[148:151], v[208:211], v[110:113]
	v_mfma_f32_16x16x32_bf16 v[106:109], v[162:165], v[208:211], v[106:109]
	v_mfma_f32_16x16x32_bf16 v[102:105], v[148:151], v[216:219], v[102:105]
	v_mfma_f32_16x16x32_bf16 v[98:101], v[162:165], v[216:219], v[98:101]
	v_mfma_f32_16x16x32_bf16 v[62:65], v[166:169], v[188:191], v[62:65]
	v_mfma_f32_16x16x32_bf16 v[58:61], v[180:183], v[188:191], v[58:61]
	v_mfma_f32_16x16x32_bf16 v[54:57], v[166:169], v[196:199], v[54:57]
	v_mfma_f32_16x16x32_bf16 v[50:53], v[180:183], v[196:199], v[50:53]
	v_mfma_f32_16x16x32_bf16 v[46:49], v[166:169], v[204:207], v[46:49]
	v_mfma_f32_16x16x32_bf16 v[42:45], v[180:183], v[204:207], v[42:45]
	v_mfma_f32_16x16x32_bf16 v[38:41], v[166:169], v[212:215], v[38:41]
	v_mfma_f32_16x16x32_bf16 v[34:37], v[180:183], v[212:215], v[34:37]
	v_mfma_f32_16x16x32_bf16 v[62:65], v[170:173], v[192:195], v[62:65]
	v_mfma_f32_16x16x32_bf16 v[58:61], v[184:187], v[192:195], v[58:61]
	v_mfma_f32_16x16x32_bf16 v[54:57], v[170:173], v[200:203], v[54:57]
	v_mfma_f32_16x16x32_bf16 v[50:53], v[184:187], v[200:203], v[50:53]
	v_mfma_f32_16x16x32_bf16 v[46:49], v[170:173], v[208:211], v[46:49]
	v_mfma_f32_16x16x32_bf16 v[42:45], v[184:187], v[208:211], v[42:45]
	v_mfma_f32_16x16x32_bf16 v[38:41], v[170:173], v[216:219], v[38:41]
	v_mfma_f32_16x16x32_bf16 v[34:37], v[184:187], v[216:219], v[34:37]
	s_barrier
	s_setprio 0
	s_add_i32 s0, s50, s54
	v_lshl_add_u64 v[152:153], s[14:15], 0, v[136:137]
	s_mov_b32 m0, s0
	ds_read_b128 v[188:191], v156 offset:16384
	ds_read_b128 v[192:195], v156 offset:17408
	ds_read_b128 v[196:199], v156 offset:18432
	ds_read_b128 v[200:203], v156 offset:19456
	ds_read_b128 v[204:207], v156 offset:20480
	ds_read_b128 v[208:211], v156 offset:21504
	ds_read_b128 v[212:215], v156 offset:22528
	ds_read_b128 v[216:219], v156 offset:23552
	global_load_lds_dwordx4 v[152:153], off
	s_add_i32 m0, s0, 0x2000
	s_add_u32 s0, s14, 0x30000
	v_lshl_add_u64 v[174:175], s[14:15], 0, v[140:141]
	s_addc_u32 s1, s15, 0
	s_add_i32 s50, s51, s54
	global_load_lds_dwordx4 v[174:175], off
	v_lshl_add_u64 v[220:221], s[0:1], 0, v[136:137]
	s_mov_b32 m0, s50
	v_lshl_add_u64 v[222:223], s[16:17], 0, v[138:139]
	global_load_lds_dwordx4 v[220:221], off
	v_lshl_add_u64 v[220:221], s[0:1], 0, v[140:141]
	s_add_i32 m0, s50, 0x2000
	s_nop 0
	global_load_lds_dwordx4 v[220:221], off
	v_lshl_add_u64 v[220:221], s[16:17], 0, v[134:135]
	s_mov_b32 m0, s28
	s_nop 0
	global_load_lds_dwordx4 v[220:221], off
	s_mov_b32 m0, s29
	s_nop 0
	global_load_lds_dwordx4 v[222:223], off
	s_waitcnt vmcnt(8)
	s_waitcnt lgkmcnt(0)
	s_setprio 3
	s_barrier
; #define PG8_STAGE(bufoff, gbase, voff) do { _Pragma("unroll") for (int _i = 0; _i < 2; ++_i) \
;         __builtin_amdgcn_global_load_lds((const unsigned*)((const char*)(gbase) + (voff)[_i]), (LAS unsigned*)(lds + (bufoff) + ldsw + _i * 8192), 16, 0, 0); } while (0)
; #define PG8_LDA(dst, b, h) do { _Pragma("unroll") for (int m = 0; m < 4; ++m) _Pragma("unroll") for (int k = 0; k < 2; ++k) dst[m][k] = *(const LAS bf16x8*)(lds + PG8_SA(b, h) + aoff + m * 2048 + k * 1024); } while (0)
; #define PG8_LDB(dst, b, h) do { _Pragma("unroll") for (int n = 0; n < 2; ++n) _Pragma("unroll") for (int k = 0; k < 2; ++k) dst[n][k] = *(const LAS bf16x8*)(lds + PG8_SB(b, h) + boff + n * 2048 + k * 1024); } while (0)
; #define PG8_MMA(ai, bj, At, Bt) do { __builtin_amdgcn_s_setprio(1); _Pragma("unroll") for (int m = 0; m < 4; ++m) _Pragma("unroll") for (int n = 0; n < 2; ++n) _Pragma("unroll") for (int k = 0; k < 2; ++k) \
;         acc[ai][bj][m][n] = __builtin_amdgcn_mfma_f32_16x16x32_bf16(Bt[n][k], At[m][k], acc[ai][bj][m][n], 0, 0, 0); __builtin_amdgcn_s_setprio(0); } while (0)
; #define PG8_WAIT_V(n) asm volatile("s_waitcnt vmcnt(" #n ")" ::: "memory")
; #define PG8_WAIT_L(n) asm volatile("s_waitcnt lgkmcnt(" #n ")" ::: "memory")
; #define PG8_BAR __builtin_amdgcn_s_barrier()
; #define PG8_SCHED __builtin_amdgcn_sched_barrier(0)
; template <class Epi, class Sched, int LDA, int LDB, bool ALIGN_EPI = true>
; __device__ __forceinline__ void gemm_phase(LAS unsigned char* lds, const Gemm g, const Sched& S, const Epi& E, int wave) {
;     ...
;             PG8_WAIT_V(8); PG8_WAIT_L(0); PG8_BAR; PG8_MMA(1, 0, At, B0); PG8_MMA(1, 1, At, B1); PG8_BAR; PG8_SCHED;
;             PG8_LDB(B0, 1, 0); PG8_LDB(B1, 1, 1); PG8_SCHED; PG8_LDA(At, 1, 0); PG8_STAGE(PG8_SA(0, 1), a2 + hstepA, voffA);
;             PG8_WAIT_V(8); PG8_WAIT_L(0); PG8_BAR; PG8_MMA(0, 0, At, B0); PG8_MMA(0, 1, At, B1); PG8_BAR; PG8_SCHED;
	v_mfma_f32_16x16x32_bf16 v[94:97], v[130:133], v[188:191], v[94:97]
	v_mfma_f32_16x16x32_bf16 v[90:93], v[158:161], v[188:191], v[90:93]
	v_mfma_f32_16x16x32_bf16 v[86:89], v[130:133], v[196:199], v[86:89]
	v_mfma_f32_16x16x32_bf16 v[82:85], v[158:161], v[196:199], v[82:85]
	v_mfma_f32_16x16x32_bf16 v[78:81], v[130:133], v[204:207], v[78:81]
	v_mfma_f32_16x16x32_bf16 v[74:77], v[158:161], v[204:207], v[74:77]
	v_mfma_f32_16x16x32_bf16 v[70:73], v[130:133], v[212:215], v[70:73]
	v_mfma_f32_16x16x32_bf16 v[66:69], v[158:161], v[212:215], v[66:69]
	v_mfma_f32_16x16x32_bf16 v[94:97], v[148:151], v[192:195], v[94:97]
	v_mfma_f32_16x16x32_bf16 v[90:93], v[162:165], v[192:195], v[90:93]
	v_mfma_f32_16x16x32_bf16 v[86:89], v[148:151], v[200:203], v[86:89]
	v_mfma_f32_16x16x32_bf16 v[82:85], v[162:165], v[200:203], v[82:85]
	v_mfma_f32_16x16x32_bf16 v[78:81], v[148:151], v[208:211], v[78:81]
	v_mfma_f32_16x16x32_bf16 v[74:77], v[162:165], v[208:211], v[74:77]
	v_mfma_f32_16x16x32_bf16 v[70:73], v[148:151], v[216:219], v[70:73]
	v_mfma_f32_16x16x32_bf16 v[66:69], v[162:165], v[216:219], v[66:69]
	v_mfma_f32_16x16x32_bf16 v[30:33], v[166:169], v[188:191], v[30:33]
	v_mfma_f32_16x16x32_bf16 v[26:29], v[180:183], v[188:191], v[26:29]
	v_mfma_f32_16x16x32_bf16 v[22:25], v[166:169], v[196:199], v[22:25]
	v_mfma_f32_16x16x32_bf16 v[18:21], v[180:183], v[196:199], v[18:21]
	v_mfma_f32_16x16x32_bf16 v[14:17], v[166:169], v[204:207], v[14:17]
	v_mfma_f32_16x16x32_bf16 v[10:13], v[180:183], v[204:207], v[10:13]
	v_mfma_f32_16x16x32_bf16 v[6:9], v[166:169], v[212:215], v[6:9]
	v_mfma_f32_16x16x32_bf16 v[2:5], v[180:183], v[212:215], v[2:5]
	v_mfma_f32_16x16x32_bf16 v[30:33], v[170:173], v[192:195], v[30:33]
	v_mfma_f32_16x16x32_bf16 v[26:29], v[184:187], v[192:195], v[26:29]
	v_mfma_f32_16x16x32_bf16 v[22:25], v[170:173], v[200:203], v[22:25]
	v_mfma_f32_16x16x32_bf16 v[18:21], v[184:187], v[200:203], v[18:21]
	v_mfma_f32_16x16x32_bf16 v[14:17], v[170:173], v[208:211], v[14:17]
	v_mfma_f32_16x16x32_bf16 v[10:13], v[184:187], v[208:211], v[10:13]
	v_mfma_f32_16x16x32_bf16 v[6:9], v[170:173], v[216:219], v[6:9]
	v_mfma_f32_16x16x32_bf16 v[2:5], v[184:187], v[216:219], v[2:5]
	s_barrier
	s_setprio 0
	s_add_i32 s50, 0, 0x18000
	v_add_u32_e32 v0, s50, v154
	s_add_i32 s51, 0, 0x1c000
	ds_read_b128 v[130:133], v0
	ds_read_b128 v[148:151], v0 offset:1024
	ds_read_b128 v[158:161], v0 offset:2048
	ds_read_b128 v[162:165], v0 offset:3072
	v_add_u32_e32 v0, s51, v154
	ds_read_b128 v[166:169], v0
	ds_read_b128 v[170:173], v0 offset:1024
	ds_read_b128 v[180:183], v0 offset:2048
	ds_read_b128 v[184:187], v0 offset:3072
	s_add_u32 s0, s16, 0x30000
	s_addc_u32 s1, s17, 0
	s_mov_b32 m0, s34
	v_lshl_add_u64 v[224:225], s[0:1], 0, v[134:135]
	ds_read_b128 v[188:191], v156 offset:32768
	ds_read_b128 v[192:195], v156 offset:33792
	ds_read_b128 v[196:199], v156 offset:34816
	ds_read_b128 v[200:203], v156 offset:35840
	ds_read_b128 v[204:207], v156 offset:36864
	ds_read_b128 v[208:211], v156 offset:37888
	ds_read_b128 v[212:215], v156 offset:38912
	ds_read_b128 v[216:219], v156 offset:39936
	global_load_lds_dwordx4 v[224:225], off
	v_lshl_add_u64 v[224:225], s[0:1], 0, v[138:139]
	s_mov_b32 m0, s35
	s_nop 0
	global_load_lds_dwordx4 v[224:225], off
	s_waitcnt vmcnt(8)
	s_waitcnt lgkmcnt(0)
	s_setprio 3
	s_barrier
	v_mfma_f32_16x16x32_bf16 v[126:129], v[130:133], v[188:191], v[126:129]
	v_mfma_f32_16x16x32_bf16 v[122:125], v[158:161], v[188:191], v[122:125]
	v_mfma_f32_16x16x32_bf16 v[118:121], v[130:133], v[196:199], v[118:121]
	v_mfma_f32_16x16x32_bf16 v[114:117], v[158:161], v[196:199], v[114:117]
	v_mfma_f32_16x16x32_bf16 v[110:113], v[130:133], v[204:207], v[110:113]
	v_mfma_f32_16x16x32_bf16 v[106:109], v[158:161], v[204:207], v[106:109]
	v_mfma_f32_16x16x32_bf16 v[102:105], v[130:133], v[212:215], v[102:105]
	v_mfma_f32_16x16x32_bf16 v[98:101], v[158:161], v[212:215], v[98:101]
	v_mfma_f32_16x16x32_bf16 v[126:129], v[148:151], v[192:195], v[126:129]
	v_mfma_f32_16x16x32_bf16 v[122:125], v[162:165], v[192:195], v[122:125]
	v_mfma_f32_16x16x32_bf16 v[118:121], v[148:151], v[200:203], v[118:121]
	v_mfma_f32_16x16x32_bf16 v[114:117], v[162:165], v[200:203], v[114:117]
	v_mfma_f32_16x16x32_bf16 v[110:113], v[148:151], v[208:211], v[110:113]
	v_mfma_f32_16x16x32_bf16 v[106:109], v[162:165], v[208:211], v[106:109]
	v_mfma_f32_16x16x32_bf16 v[102:105], v[148:151], v[216:219], v[102:105]
	v_mfma_f32_16x16x32_bf16 v[98:101], v[162:165], v[216:219], v[98:101]
	v_mfma_f32_16x16x32_bf16 v[62:65], v[166:169], v[188:191], v[62:65]
	v_mfma_f32_16x16x32_bf16 v[58:61], v[180:183], v[188:191], v[58:61]
	v_mfma_f32_16x16x32_bf16 v[54:57], v[166:169], v[196:199], v[54:57]
	v_mfma_f32_16x16x32_bf16 v[50:53], v[180:183], v[196:199], v[50:53]
	v_mfma_f32_16x16x32_bf16 v[46:49], v[166:169], v[204:207], v[46:49]
	v_mfma_f32_16x16x32_bf16 v[42:45], v[180:183], v[204:207], v[42:45]
	v_mfma_f32_16x16x32_bf16 v[38:41], v[166:169], v[212:215], v[38:41]
	v_mfma_f32_16x16x32_bf16 v[34:37], v[180:183], v[212:215], v[34:37]
	v_mfma_f32_16x16x32_bf16 v[62:65], v[170:173], v[192:195], v[62:65]
	v_mfma_f32_16x16x32_bf16 v[58:61], v[184:187], v[192:195], v[58:61]
	v_mfma_f32_16x16x32_bf16 v[54:57], v[170:173], v[200:203], v[54:57]
	v_mfma_f32_16x16x32_bf16 v[50:53], v[184:187], v[200:203], v[50:53]
	v_mfma_f32_16x16x32_bf16 v[46:49], v[170:173], v[208:211], v[46:49]
	v_mfma_f32_16x16x32_bf16 v[42:45], v[184:187], v[208:211], v[42:45]
	v_mfma_f32_16x16x32_bf16 v[38:41], v[170:173], v[216:219], v[38:41]
	v_mfma_f32_16x16x32_bf16 v[34:37], v[184:187], v[216:219], v[34:37]
	s_barrier
; #define PG8_STAGE(bufoff, gbase, voff) do { _Pragma("unroll") for (int _i = 0; _i < 2; ++_i) \
;         __builtin_amdgcn_global_load_lds((const unsigned*)((const char*)(gbase) + (voff)[_i]), (LAS unsigned*)(lds + (bufoff) + ldsw + _i * 8192), 16, 0, 0); } while (0)
; #define PG8_LDA(dst, b, h) do { _Pragma("unroll") for (int m = 0; m < 4; ++m) _Pragma("unroll") for (int k = 0; k < 2; ++k) dst[m][k] = *(const LAS bf16x8*)(lds + PG8_SA(b, h) + aoff + m * 2048 + k * 1024); } while (0)
; #define PG8_MMA(ai, bj, At, Bt) do { __builtin_amdgcn_s_setprio(1); _Pragma("unroll") for (int m = 0; m < 4; ++m) _Pragma("unroll") for (int n = 0; n < 2; ++n) _Pragma("unroll") for (int k = 0; k < 2; ++k) \
;         acc[ai][bj][m][n] = __builtin_amdgcn_mfma_f32_16x16x32_bf16(Bt[n][k], At[m][k], acc[ai][bj][m][n], 0, 0, 0); __builtin_amdgcn_s_setprio(0); } while (0)
; #define PG8_WAIT_V(n) asm volatile("s_waitcnt vmcnt(" #n ")" ::: "memory")
; #define PG8_WAIT_L(n) asm volatile("s_waitcnt lgkmcnt(" #n ")" ::: "memory")
; #define PG8_BAR __builtin_amdgcn_s_barrier()
; #define PG8_SCHED __builtin_amdgcn_sched_barrier(0)
; template <class Epi, class Sched, int LDA, int LDB, bool ALIGN_EPI = true>
; __device__ __forceinline__ void gemm_phase(LAS unsigned char* lds, const Gemm g, const Sched& S, const Epi& E, int wave) {
;     ...
;             PG8_LDA(At, 1, 1); PG8_STAGE(PG8_SB(1, 0), b3, voffB); PG8_STAGE(PG8_SB(1, 1), b3 + hstepB, voffB); PG8_STAGE(PG8_SA(1, 0), a3, voffA);
;             PG8_WAIT_V(8); PG8_WAIT_L(0); PG8_BAR; PG8_MMA(1, 0, At, B0); PG8_MMA(1, 1, At, B1); PG8_BAR; PG8_SCHED;
;         }
;         if constexpr (ALIGN_EPI) { if (wr == 0) PG8_BAR; }
	s_setprio 0
	s_add_i32 s0, s50, s54
	v_lshl_add_u64 v[152:153], v[152:153], 0, s[72:73]
	s_mov_b32 m0, s0
	ds_read_b128 v[188:191], v156 offset:49152
	ds_read_b128 v[192:195], v156 offset:50176
	ds_read_b128 v[196:199], v156 offset:51200
	ds_read_b128 v[200:203], v156 offset:52224
	ds_read_b128 v[204:207], v156 offset:53248
	ds_read_b128 v[208:211], v156 offset:54272
	ds_read_b128 v[212:215], v156 offset:55296
	ds_read_b128 v[216:219], v156 offset:56320
	global_load_lds_dwordx4 v[152:153], off
	s_add_i32 m0, s0, 0x2000
	s_add_u32 s0, s14, 0x30080
	v_lshl_add_u64 v[152:153], v[174:175], 0, s[72:73]
	s_addc_u32 s1, s15, 0
	s_add_i32 s14, s51, s54
	global_load_lds_dwordx4 v[152:153], off
	v_lshl_add_u64 v[152:153], s[0:1], 0, v[136:137]
	s_mov_b32 m0, s14
	s_nop 0
	global_load_lds_dwordx4 v[152:153], off
	v_lshl_add_u64 v[152:153], s[0:1], 0, v[140:141]
	s_add_i32 m0, s14, 0x2000
	s_nop 0
	global_load_lds_dwordx4 v[152:153], off
	v_lshl_add_u64 v[152:153], v[220:221], 0, s[72:73]
	s_mov_b32 m0, s36
	s_nop 0
	global_load_lds_dwordx4 v[152:153], off
	v_lshl_add_u64 v[152:153], v[222:223], 0, s[72:73]
	s_mov_b32 m0, s37
	s_nop 0
	global_load_lds_dwordx4 v[152:153], off
	s_waitcnt vmcnt(8)
	s_waitcnt lgkmcnt(0)
	s_setprio 3
	s_barrier
	v_mfma_f32_16x16x32_bf16 v[94:97], v[130:133], v[188:191], v[94:97]
	v_mfma_f32_16x16x32_bf16 v[90:93], v[158:161], v[188:191], v[90:93]
	v_mfma_f32_16x16x32_bf16 v[86:89], v[130:133], v[196:199], v[86:89]
	v_mfma_f32_16x16x32_bf16 v[82:85], v[158:161], v[196:199], v[82:85]
	v_mfma_f32_16x16x32_bf16 v[78:81], v[130:133], v[204:207], v[78:81]
	v_mfma_f32_16x16x32_bf16 v[74:77], v[158:161], v[204:207], v[74:77]
	v_mfma_f32_16x16x32_bf16 v[70:73], v[130:133], v[212:215], v[70:73]
	v_mfma_f32_16x16x32_bf16 v[66:69], v[158:161], v[212:215], v[66:69]
	v_mfma_f32_16x16x32_bf16 v[94:97], v[148:151], v[192:195], v[94:97]
	v_mfma_f32_16x16x32_bf16 v[90:93], v[162:165], v[192:195], v[90:93]
	v_mfma_f32_16x16x32_bf16 v[86:89], v[148:151], v[200:203], v[86:89]
	v_mfma_f32_16x16x32_bf16 v[82:85], v[162:165], v[200:203], v[82:85]
	v_mfma_f32_16x16x32_bf16 v[78:81], v[148:151], v[208:211], v[78:81]
	v_mfma_f32_16x16x32_bf16 v[74:77], v[162:165], v[208:211], v[74:77]
	v_mfma_f32_16x16x32_bf16 v[70:73], v[148:151], v[216:219], v[70:73]
	v_mfma_f32_16x16x32_bf16 v[66:69], v[162:165], v[216:219], v[66:69]
	v_mfma_f32_16x16x32_bf16 v[30:33], v[166:169], v[188:191], v[30:33]
	v_mfma_f32_16x16x32_bf16 v[26:29], v[180:183], v[188:191], v[26:29]
	v_mfma_f32_16x16x32_bf16 v[22:25], v[166:169], v[196:199], v[22:25]
	v_mfma_f32_16x16x32_bf16 v[18:21], v[180:183], v[196:199], v[18:21]
	v_mfma_f32_16x16x32_bf16 v[14:17], v[166:169], v[204:207], v[14:17]
	v_mfma_f32_16x16x32_bf16 v[10:13], v[180:183], v[204:207], v[10:13]
	v_mfma_f32_16x16x32_bf16 v[6:9], v[166:169], v[212:215], v[6:9]
	v_mfma_f32_16x16x32_bf16 v[2:5], v[180:183], v[212:215], v[2:5]
	v_mfma_f32_16x16x32_bf16 v[30:33], v[170:173], v[192:195], v[30:33]
	v_mfma_f32_16x16x32_bf16 v[26:29], v[184:187], v[192:195], v[26:29]
	v_mfma_f32_16x16x32_bf16 v[22:25], v[170:173], v[200:203], v[22:25]
	v_mfma_f32_16x16x32_bf16 v[18:21], v[184:187], v[200:203], v[18:21]
	v_mfma_f32_16x16x32_bf16 v[14:17], v[170:173], v[208:211], v[14:17]
	v_mfma_f32_16x16x32_bf16 v[10:13], v[184:187], v[208:211], v[10:13]
	v_mfma_f32_16x16x32_bf16 v[6:9], v[170:173], v[216:219], v[6:9]
	v_mfma_f32_16x16x32_bf16 v[2:5], v[184:187], v[216:219], v[2:5]
	s_barrier
	s_setprio 0
	s_add_i32 s49, s49, 2
	s_add_u32 s46, s46, 0x100
	s_addc_u32 s47, s47, 0
	s_cmp_gt_u32 s49, 9
	s_mov_b64 s[0:1], s[2:3]
	s_cbranch_scc0 .LBB0_2551
	v_readlane_b32 s0, v252, 14
	v_readlane_b32 s1, v252, 15
	s_and_b64 vcc, exec, s[0:1]
	s_cbranch_vccz .LBB0_2554
	s_barrier

; #define PG8_STAGE(bufoff, gbase, voff) do { _Pragma("unroll") for (int _i = 0; _i < 2; ++_i) \
;         __builtin_amdgcn_global_load_lds((const unsigned*)((const char*)(gbase) + (voff)[_i]), (LAS unsigned*)(lds + (bufoff) + ldsw + _i * 8192), 16, 0, 0); } while (0)
; #define PG8_LDA(dst, b, h) do { _Pragma("unroll") for (int m = 0; m < 4; ++m) _Pragma("unroll") for (int k = 0; k < 2; ++k) dst[m][k] = *(const LAS bf16x8*)(lds + PG8_SA(b, h) + aoff + m * 2048 + k * 1024); } while (0)
; #define PG8_LDB(dst, b, h) do { _Pragma("unroll") for (int n = 0; n < 2; ++n) _Pragma("unroll") for (int k = 0; k < 2; ++k) dst[n][k] = *(const LAS bf16x8*)(lds + PG8_SB(b, h) + boff + n * 2048 + k * 1024); } while (0)
; #define PG8_MMA(ai, bj, At, Bt) do { __builtin_amdgcn_s_setprio(1); _Pragma("unroll") for (int m = 0; m < 4; ++m) _Pragma("unroll") for (int n = 0; n < 2; ++n) _Pragma("unroll") for (int k = 0; k < 2; ++k) \
;         acc[ai][bj][m][n] = __builtin_amdgcn_mfma_f32_16x16x32_bf16(Bt[n][k], At[m][k], acc[ai][bj][m][n], 0, 0, 0); __builtin_amdgcn_s_setprio(0); } while (0)
; #define PG8_WAIT_V(n) asm volatile("s_waitcnt vmcnt(" #n ")" ::: "memory")
; #define PG8_WAIT_L(n) asm volatile("s_waitcnt lgkmcnt(" #n ")" ::: "memory")
; #define PG8_BAR __builtin_amdgcn_s_barrier()
; template <class Epi, class Sched, int LDA, int LDB, bool ALIGN_EPI = true>
; __device__ __forceinline__ void gemm_phase(LAS unsigned char* lds, const Gemm g, const Sched& S, const Epi& E, int wave) {
;     ...
;         for (int t = 0; t < nt; t += 2) {
;             const bool last = (t == nt - 2);
;             const char* a1 = cA + (size_t)(t + 1) * kstep;
;             const char* a2 = last ? nA : cA + (size_t)(t + 2) * kstep; const char* b2 = last ? nB : cB + (size_t)(t + 2) * kstep;
;             const char* a3 = a2 + kstep; const char* b3 = b2 + kstep;
;             PG8_LDB(B0, 0, 0); PG8_LDB(B1, 0, 1); PG8_SCHED; PG8_LDA(At, 0, 0); PG8_STAGE(PG8_SA(1, 1), a1 + hstepA, voffA);
;             PG8_WAIT_V(8); PG8_WAIT_L(0); PG8_BAR; PG8_MMA(0, 0, At, B0); PG8_MMA(0, 1, At, B1); PG8_BAR; PG8_SCHED;
;             PG8_LDA(At, 0, 1); PG8_STAGE(PG8_SB(0, 0), b2, voffB); PG8_STAGE(PG8_SB(0, 1), b2 + hstepB, voffB); PG8_STAGE(PG8_SA(0, 0), a2, voffA);
;             PG8_WAIT_V(8); PG8_WAIT_L(0); PG8_BAR; PG8_MMA(1, 0, At, B0); PG8_MMA(1, 1, At, B1); PG8_BAR; PG8_SCHED;
.LBB0_2619:
	s_add_u32 s16, s14, 0xfffe0080
	s_addc_u32 s17, s15, -1
	s_add_i32 s53, 0, 0x10000
	s_cmp_eq_u32 s52, 4
	s_cselect_b32 s19, s7, s17
	s_cselect_b32 s18, s13, s16
	v_add_u32_e32 v0, s53, v150
	s_cselect_b32 s17, s3, s51
	s_cselect_b32 s16, s44, s45
	s_add_i32 s58, 0, 0x14000
	ds_read_b128 v[144:147], v0
	ds_read_b128 v[152:155], v0 offset:1024
	ds_read_b128 v[156:159], v0 offset:2048
	ds_read_b128 v[160:163], v0 offset:3072
	v_add_u32_e32 v0, s58, v150
	ds_read_b128 v[164:167], v0
	ds_read_b128 v[168:171], v0 offset:1024
	ds_read_b128 v[172:175], v0 offset:2048
	ds_read_b128 v[180:183], v0 offset:3072
	v_lshl_add_u64 v[148:149], s[14:15], 0, v[140:141]
	s_add_i32 m0, s36, 0xc000
	ds_read_b128 v[184:187], v151
	ds_read_b128 v[188:191], v151 offset:1024
	ds_read_b128 v[192:195], v151 offset:2048
	ds_read_b128 v[196:199], v151 offset:3072
	ds_read_b128 v[200:203], v151 offset:4096
	ds_read_b128 v[204:207], v151 offset:5120
	ds_read_b128 v[208:211], v151 offset:6144
	ds_read_b128 v[212:215], v151 offset:7168
	global_load_lds_dwordx4 v[148:149], off
	v_lshl_add_u64 v[148:149], s[14:15], 0, v[142:143]
	s_add_i32 m0, s36, 0xe000
	s_nop 0
	global_load_lds_dwordx4 v[148:149], off
	s_waitcnt vmcnt(8)
	s_waitcnt lgkmcnt(0)
	s_setprio 3
	s_barrier
	v_mfma_f32_16x16x32_bf16 v[126:129], v[144:147], v[184:187], v[126:129]
	v_mfma_f32_16x16x32_bf16 v[122:125], v[156:159], v[184:187], v[122:125]
	v_mfma_f32_16x16x32_bf16 v[118:121], v[144:147], v[192:195], v[118:121]
	v_mfma_f32_16x16x32_bf16 v[114:117], v[156:159], v[192:195], v[114:117]
	v_mfma_f32_16x16x32_bf16 v[110:113], v[144:147], v[200:203], v[110:113]
	v_mfma_f32_16x16x32_bf16 v[106:109], v[156:159], v[200:203], v[106:109]
	v_mfma_f32_16x16x32_bf16 v[102:105], v[144:147], v[208:211], v[102:105]
	v_mfma_f32_16x16x32_bf16 v[98:101], v[156:159], v[208:211], v[98:101]
	v_mfma_f32_16x16x32_bf16 v[126:129], v[152:155], v[188:191], v[126:129]
	v_mfma_f32_16x16x32_bf16 v[122:125], v[160:163], v[188:191], v[122:125]
	v_mfma_f32_16x16x32_bf16 v[118:121], v[152:155], v[196:199], v[118:121]
	v_mfma_f32_16x16x32_bf16 v[114:117], v[160:163], v[196:199], v[114:117]
	v_mfma_f32_16x16x32_bf16 v[110:113], v[152:155], v[204:207], v[110:113]
	v_mfma_f32_16x16x32_bf16 v[106:109], v[160:163], v[204:207], v[106:109]
	v_mfma_f32_16x16x32_bf16 v[102:105], v[152:155], v[212:215], v[102:105]
	v_mfma_f32_16x16x32_bf16 v[98:101], v[160:163], v[212:215], v[98:101]
	v_mfma_f32_16x16x32_bf16 v[62:65], v[164:167], v[184:187], v[62:65]
	v_mfma_f32_16x16x32_bf16 v[58:61], v[172:175], v[184:187], v[58:61]
	v_mfma_f32_16x16x32_bf16 v[54:57], v[164:167], v[192:195], v[54:57]
	v_mfma_f32_16x16x32_bf16 v[50:53], v[172:175], v[192:195], v[50:53]
	v_mfma_f32_16x16x32_bf16 v[46:49], v[164:167], v[200:203], v[46:49]
	v_mfma_f32_16x16x32_bf16 v[42:45], v[172:175], v[200:203], v[42:45]
	v_mfma_f32_16x16x32_bf16 v[38:41], v[164:167], v[208:211], v[38:41]
	v_mfma_f32_16x16x32_bf16 v[34:37], v[172:175], v[208:211], v[34:37]
	v_mfma_f32_16x16x32_bf16 v[62:65], v[168:171], v[188:191], v[62:65]
	v_mfma_f32_16x16x32_bf16 v[58:61], v[180:183], v[188:191], v[58:61]
	v_mfma_f32_16x16x32_bf16 v[54:57], v[168:171], v[196:199], v[54:57]
	v_mfma_f32_16x16x32_bf16 v[50:53], v[180:183], v[196:199], v[50:53]
	v_mfma_f32_16x16x32_bf16 v[46:49], v[168:171], v[204:207], v[46:49]
	v_mfma_f32_16x16x32_bf16 v[42:45], v[180:183], v[204:207], v[42:45]
	v_mfma_f32_16x16x32_bf16 v[38:41], v[168:171], v[212:215], v[38:41]
	v_mfma_f32_16x16x32_bf16 v[34:37], v[180:183], v[212:215], v[34:37]
	s_barrier
	s_setprio 0
	s_add_i32 s53, s53, s59
	v_lshl_add_u64 v[148:149], s[16:17], 0, v[132:133]
	s_mov_b32 m0, s53
	ds_read_b128 v[184:187], v151 offset:16384
	ds_read_b128 v[188:191], v151 offset:17408
	ds_read_b128 v[192:195], v151 offset:18432
	ds_read_b128 v[196:199], v151 offset:19456
	ds_read_b128 v[200:203], v151 offset:20480
	ds_read_b128 v[204:207], v151 offset:21504
	ds_read_b128 v[208:211], v151 offset:22528
	ds_read_b128 v[212:215], v151 offset:23552
	global_load_lds_dwordx4 v[148:149], off
	s_add_i32 m0, s53, 0x2000
	s_add_u32 s54, s16, 0x20000
	v_lshl_add_u64 v[216:217], s[16:17], 0, v[136:137]
	s_addc_u32 s55, s17, 0
	s_add_i32 s53, s58, s59
	global_load_lds_dwordx4 v[216:217], off
	v_lshl_add_u64 v[218:219], s[54:55], 0, v[132:133]
	s_mov_b32 m0, s53
	v_lshl_add_u64 v[220:221], s[18:19], 0, v[134:135]
	global_load_lds_dwordx4 v[218:219], off
	v_lshl_add_u64 v[218:219], s[54:55], 0, v[136:137]
	s_add_i32 m0, s53, 0x2000
	s_nop 0
	global_load_lds_dwordx4 v[218:219], off
	v_lshl_add_u64 v[218:219], s[18:19], 0, v[130:131]
	s_mov_b32 m0, s36
	s_nop 0
	global_load_lds_dwordx4 v[218:219], off
	s_mov_b32 m0, s37
	s_nop 0
	global_load_lds_dwordx4 v[220:221], off
	s_waitcnt vmcnt(8)
	s_waitcnt lgkmcnt(0)
	s_setprio 3
	s_barrier
; #define PG8_STAGE(bufoff, gbase, voff) do { _Pragma("unroll") for (int _i = 0; _i < 2; ++_i) \
;         __builtin_amdgcn_global_load_lds((const unsigned*)((const char*)(gbase) + (voff)[_i]), (LAS unsigned*)(lds + (bufoff) + ldsw + _i * 8192), 16, 0, 0); } while (0)
; #define PG8_LDA(dst, b, h) do { _Pragma("unroll") for (int m = 0; m < 4; ++m) _Pragma("unroll") for (int k = 0; k < 2; ++k) dst[m][k] = *(const LAS bf16x8*)(lds + PG8_SA(b, h) + aoff + m * 2048 + k * 1024); } while (0)
; #define PG8_LDB(dst, b, h) do { _Pragma("unroll") for (int n = 0; n < 2; ++n) _Pragma("unroll") for (int k = 0; k < 2; ++k) dst[n][k] = *(const LAS bf16x8*)(lds + PG8_SB(b, h) + boff + n * 2048 + k * 1024); } while (0)
; #define PG8_MMA(ai, bj, At, Bt) do { __builtin_amdgcn_s_setprio(1); _Pragma("unroll") for (int m = 0; m < 4; ++m) _Pragma("unroll") for (int n = 0; n < 2; ++n) _Pragma("unroll") for (int k = 0; k < 2; ++k) \
;         acc[ai][bj][m][n] = __builtin_amdgcn_mfma_f32_16x16x32_bf16(Bt[n][k], At[m][k], acc[ai][bj][m][n], 0, 0, 0); __builtin_amdgcn_s_setprio(0); } while (0)
; #define PG8_WAIT_V(n) asm volatile("s_waitcnt vmcnt(" #n ")" ::: "memory")
; #define PG8_WAIT_L(n) asm volatile("s_waitcnt lgkmcnt(" #n ")" ::: "memory")
; #define PG8_BAR __builtin_amdgcn_s_barrier()
; #define PG8_SCHED __builtin_amdgcn_sched_barrier(0)
; template <class Epi, class Sched, int LDA, int LDB, bool ALIGN_EPI = true>
; __device__ __forceinline__ void gemm_phase(LAS unsigned char* lds, const Gemm g, const Sched& S, const Epi& E, int wave) {
;     ...
;             PG8_WAIT_V(8); PG8_WAIT_L(0); PG8_BAR; PG8_MMA(1, 0, At, B0); PG8_MMA(1, 1, At, B1); PG8_BAR; PG8_SCHED;
;             PG8_LDB(B0, 1, 0); PG8_LDB(B1, 1, 1); PG8_SCHED; PG8_LDA(At, 1, 0); PG8_STAGE(PG8_SA(0, 1), a2 + hstepA, voffA);
;             PG8_WAIT_V(8); PG8_WAIT_L(0); PG8_BAR; PG8_MMA(0, 0, At, B0); PG8_MMA(0, 1, At, B1); PG8_BAR; PG8_SCHED;
	v_mfma_f32_16x16x32_bf16 v[94:97], v[144:147], v[184:187], v[94:97]
	v_mfma_f32_16x16x32_bf16 v[90:93], v[156:159], v[184:187], v[90:93]
	v_mfma_f32_16x16x32_bf16 v[86:89], v[144:147], v[192:195], v[86:89]
	v_mfma_f32_16x16x32_bf16 v[82:85], v[156:159], v[192:195], v[82:85]
	v_mfma_f32_16x16x32_bf16 v[78:81], v[144:147], v[200:203], v[78:81]
	v_mfma_f32_16x16x32_bf16 v[74:77], v[156:159], v[200:203], v[74:77]
	v_mfma_f32_16x16x32_bf16 v[70:73], v[144:147], v[208:211], v[70:73]
	v_mfma_f32_16x16x32_bf16 v[66:69], v[156:159], v[208:211], v[66:69]
	v_mfma_f32_16x16x32_bf16 v[94:97], v[152:155], v[188:191], v[94:97]
	v_mfma_f32_16x16x32_bf16 v[90:93], v[160:163], v[188:191], v[90:93]
	v_mfma_f32_16x16x32_bf16 v[86:89], v[152:155], v[196:199], v[86:89]
	v_mfma_f32_16x16x32_bf16 v[82:85], v[160:163], v[196:199], v[82:85]
	v_mfma_f32_16x16x32_bf16 v[78:81], v[152:155], v[204:207], v[78:81]
	v_mfma_f32_16x16x32_bf16 v[74:77], v[160:163], v[204:207], v[74:77]
	v_mfma_f32_16x16x32_bf16 v[70:73], v[152:155], v[212:215], v[70:73]
	v_mfma_f32_16x16x32_bf16 v[66:69], v[160:163], v[212:215], v[66:69]
	v_mfma_f32_16x16x32_bf16 v[30:33], v[164:167], v[184:187], v[30:33]
	v_mfma_f32_16x16x32_bf16 v[26:29], v[172:175], v[184:187], v[26:29]
	v_mfma_f32_16x16x32_bf16 v[22:25], v[164:167], v[192:195], v[22:25]
	v_mfma_f32_16x16x32_bf16 v[18:21], v[172:175], v[192:195], v[18:21]
	v_mfma_f32_16x16x32_bf16 v[14:17], v[164:167], v[200:203], v[14:17]
	v_mfma_f32_16x16x32_bf16 v[10:13], v[172:175], v[200:203], v[10:13]
	v_mfma_f32_16x16x32_bf16 v[6:9], v[164:167], v[208:211], v[6:9]
	v_mfma_f32_16x16x32_bf16 v[2:5], v[172:175], v[208:211], v[2:5]
	v_mfma_f32_16x16x32_bf16 v[30:33], v[168:171], v[188:191], v[30:33]
	v_mfma_f32_16x16x32_bf16 v[26:29], v[180:183], v[188:191], v[26:29]
	v_mfma_f32_16x16x32_bf16 v[22:25], v[168:171], v[196:199], v[22:25]
	v_mfma_f32_16x16x32_bf16 v[18:21], v[180:183], v[196:199], v[18:21]
	v_mfma_f32_16x16x32_bf16 v[14:17], v[168:171], v[204:207], v[14:17]
	v_mfma_f32_16x16x32_bf16 v[10:13], v[180:183], v[204:207], v[10:13]
	v_mfma_f32_16x16x32_bf16 v[6:9], v[168:171], v[212:215], v[6:9]
	v_mfma_f32_16x16x32_bf16 v[2:5], v[180:183], v[212:215], v[2:5]
	s_barrier
	s_setprio 0
	s_add_i32 s53, 0, 0x18000
	v_add_u32_e32 v0, s53, v150
	s_add_i32 s54, 0, 0x1c000
	ds_read_b128 v[144:147], v0
	ds_read_b128 v[152:155], v0 offset:1024
	ds_read_b128 v[156:159], v0 offset:2048
	ds_read_b128 v[160:163], v0 offset:3072
	v_add_u32_e32 v0, s54, v150
	ds_read_b128 v[164:167], v0
	ds_read_b128 v[168:171], v0 offset:1024
	ds_read_b128 v[172:175], v0 offset:2048
	ds_read_b128 v[180:183], v0 offset:3072
	s_add_u32 s18, s18, 0x20000
	s_addc_u32 s19, s19, 0
	s_mov_b32 m0, s38
	v_lshl_add_u64 v[222:223], s[18:19], 0, v[130:131]
	ds_read_b128 v[184:187], v151 offset:32768
	ds_read_b128 v[188:191], v151 offset:33792
	ds_read_b128 v[192:195], v151 offset:34816
	ds_read_b128 v[196:199], v151 offset:35840
	ds_read_b128 v[200:203], v151 offset:36864
	ds_read_b128 v[204:207], v151 offset:37888
	ds_read_b128 v[208:211], v151 offset:38912
	ds_read_b128 v[212:215], v151 offset:39936
	global_load_lds_dwordx4 v[222:223], off
	v_lshl_add_u64 v[222:223], s[18:19], 0, v[134:135]
	s_mov_b32 m0, s39
	s_nop 0
	global_load_lds_dwordx4 v[222:223], off
	s_waitcnt vmcnt(8)
	s_waitcnt lgkmcnt(0)
	s_setprio 3
	s_barrier
	v_mfma_f32_16x16x32_bf16 v[126:129], v[144:147], v[184:187], v[126:129]
	v_mfma_f32_16x16x32_bf16 v[122:125], v[156:159], v[184:187], v[122:125]
	v_mfma_f32_16x16x32_bf16 v[118:121], v[144:147], v[192:195], v[118:121]
	v_mfma_f32_16x16x32_bf16 v[114:117], v[156:159], v[192:195], v[114:117]
	v_mfma_f32_16x16x32_bf16 v[110:113], v[144:147], v[200:203], v[110:113]
	v_mfma_f32_16x16x32_bf16 v[106:109], v[156:159], v[200:203], v[106:109]
	v_mfma_f32_16x16x32_bf16 v[102:105], v[144:147], v[208:211], v[102:105]
	v_mfma_f32_16x16x32_bf16 v[98:101], v[156:159], v[208:211], v[98:101]
	v_mfma_f32_16x16x32_bf16 v[126:129], v[152:155], v[188:191], v[126:129]
	v_mfma_f32_16x16x32_bf16 v[122:125], v[160:163], v[188:191], v[122:125]
	v_mfma_f32_16x16x32_bf16 v[118:121], v[152:155], v[196:199], v[118:121]
	v_mfma_f32_16x16x32_bf16 v[114:117], v[160:163], v[196:199], v[114:117]
	v_mfma_f32_16x16x32_bf16 v[110:113], v[152:155], v[204:207], v[110:113]
	v_mfma_f32_16x16x32_bf16 v[106:109], v[160:163], v[204:207], v[106:109]
	v_mfma_f32_16x16x32_bf16 v[102:105], v[152:155], v[212:215], v[102:105]
	v_mfma_f32_16x16x32_bf16 v[98:101], v[160:163], v[212:215], v[98:101]
	v_mfma_f32_16x16x32_bf16 v[62:65], v[164:167], v[184:187], v[62:65]
	v_mfma_f32_16x16x32_bf16 v[58:61], v[172:175], v[184:187], v[58:61]
	v_mfma_f32_16x16x32_bf16 v[54:57], v[164:167], v[192:195], v[54:57]
	v_mfma_f32_16x16x32_bf16 v[50:53], v[172:175], v[192:195], v[50:53]
	v_mfma_f32_16x16x32_bf16 v[46:49], v[164:167], v[200:203], v[46:49]
	v_mfma_f32_16x16x32_bf16 v[42:45], v[172:175], v[200:203], v[42:45]
	v_mfma_f32_16x16x32_bf16 v[38:41], v[164:167], v[208:211], v[38:41]
	v_mfma_f32_16x16x32_bf16 v[34:37], v[172:175], v[208:211], v[34:37]
	v_mfma_f32_16x16x32_bf16 v[62:65], v[168:171], v[188:191], v[62:65]
	v_mfma_f32_16x16x32_bf16 v[58:61], v[180:183], v[188:191], v[58:61]
	v_mfma_f32_16x16x32_bf16 v[54:57], v[168:171], v[196:199], v[54:57]
	v_mfma_f32_16x16x32_bf16 v[50:53], v[180:183], v[196:199], v[50:53]
	v_mfma_f32_16x16x32_bf16 v[46:49], v[168:171], v[204:207], v[46:49]
	v_mfma_f32_16x16x32_bf16 v[42:45], v[180:183], v[204:207], v[42:45]
	v_mfma_f32_16x16x32_bf16 v[38:41], v[168:171], v[212:215], v[38:41]
	v_mfma_f32_16x16x32_bf16 v[34:37], v[180:183], v[212:215], v[34:37]
	s_barrier
; #define PG8_STAGE(bufoff, gbase, voff) do { _Pragma("unroll") for (int _i = 0; _i < 2; ++_i) \
;         __builtin_amdgcn_global_load_lds((const unsigned*)((const char*)(gbase) + (voff)[_i]), (LAS unsigned*)(lds + (bufoff) + ldsw + _i * 8192), 16, 0, 0); } while (0)
; #define PG8_LDA(dst, b, h) do { _Pragma("unroll") for (int m = 0; m < 4; ++m) _Pragma("unroll") for (int k = 0; k < 2; ++k) dst[m][k] = *(const LAS bf16x8*)(lds + PG8_SA(b, h) + aoff + m * 2048 + k * 1024); } while (0)
; #define PG8_MMA(ai, bj, At, Bt) do { __builtin_amdgcn_s_setprio(1); _Pragma("unroll") for (int m = 0; m < 4; ++m) _Pragma("unroll") for (int n = 0; n < 2; ++n) _Pragma("unroll") for (int k = 0; k < 2; ++k) \
;         acc[ai][bj][m][n] = __builtin_amdgcn_mfma_f32_16x16x32_bf16(Bt[n][k], At[m][k], acc[ai][bj][m][n], 0, 0, 0); __builtin_amdgcn_s_setprio(0); } while (0)
; #define PG8_WAIT_V(n) asm volatile("s_waitcnt vmcnt(" #n ")" ::: "memory")
; #define PG8_WAIT_L(n) asm volatile("s_waitcnt lgkmcnt(" #n ")" ::: "memory")
; #define PG8_BAR __builtin_amdgcn_s_barrier()
; #define PG8_SCHED __builtin_amdgcn_sched_barrier(0)
; template <class Epi, class Sched, int LDA, int LDB, bool ALIGN_EPI = true>
; __device__ __forceinline__ void gemm_phase(LAS unsigned char* lds, const Gemm g, const Sched& S, const Epi& E, int wave) {
;     ...
;             PG8_LDA(At, 1, 1); PG8_STAGE(PG8_SB(1, 0), b3, voffB); PG8_STAGE(PG8_SB(1, 1), b3 + hstepB, voffB); PG8_STAGE(PG8_SA(1, 0), a3, voffA);
;             PG8_WAIT_V(8); PG8_WAIT_L(0); PG8_BAR; PG8_MMA(1, 0, At, B0); PG8_MMA(1, 1, At, B1); PG8_BAR; PG8_SCHED;
;         }
;         if constexpr (ALIGN_EPI) { if (wr == 0) PG8_BAR; }
	s_setprio 0
	s_add_i32 s18, s53, s59
	v_lshl_add_u64 v[148:149], v[148:149], 0, s[70:71]
	s_mov_b32 m0, s18
	ds_read_b128 v[184:187], v151 offset:49152
	ds_read_b128 v[188:191], v151 offset:50176
	ds_read_b128 v[192:195], v151 offset:51200
	ds_read_b128 v[196:199], v151 offset:52224
	ds_read_b128 v[200:203], v151 offset:53248
	ds_read_b128 v[204:207], v151 offset:54272
	ds_read_b128 v[208:211], v151 offset:55296
	ds_read_b128 v[212:215], v151 offset:56320
	global_load_lds_dwordx4 v[148:149], off
	s_add_i32 m0, s18, 0x2000
	s_add_u32 s16, s16, 0x20080
	v_lshl_add_u64 v[148:149], v[216:217], 0, s[70:71]
	s_addc_u32 s17, s17, 0
	s_add_i32 s18, s54, s59
	global_load_lds_dwordx4 v[148:149], off
	v_lshl_add_u64 v[148:149], s[16:17], 0, v[132:133]
	s_mov_b32 m0, s18
	s_nop 0
	global_load_lds_dwordx4 v[148:149], off
	v_lshl_add_u64 v[148:149], s[16:17], 0, v[136:137]
	s_add_i32 m0, s18, 0x2000
	s_nop 0
	global_load_lds_dwordx4 v[148:149], off
	v_lshl_add_u64 v[148:149], v[218:219], 0, s[70:71]
	s_mov_b32 m0, s46
	s_nop 0
	global_load_lds_dwordx4 v[148:149], off
	v_lshl_add_u64 v[148:149], v[220:221], 0, s[70:71]
	s_mov_b32 m0, s47
	s_nop 0
	global_load_lds_dwordx4 v[148:149], off
	s_waitcnt vmcnt(8)
	s_waitcnt lgkmcnt(0)
	s_setprio 3
	s_barrier
	v_mfma_f32_16x16x32_bf16 v[94:97], v[144:147], v[184:187], v[94:97]
	v_mfma_f32_16x16x32_bf16 v[90:93], v[156:159], v[184:187], v[90:93]
	v_mfma_f32_16x16x32_bf16 v[86:89], v[144:147], v[192:195], v[86:89]
	v_mfma_f32_16x16x32_bf16 v[82:85], v[156:159], v[192:195], v[82:85]
	v_mfma_f32_16x16x32_bf16 v[78:81], v[144:147], v[200:203], v[78:81]
	v_mfma_f32_16x16x32_bf16 v[74:77], v[156:159], v[200:203], v[74:77]
	v_mfma_f32_16x16x32_bf16 v[70:73], v[144:147], v[208:211], v[70:73]
	v_mfma_f32_16x16x32_bf16 v[66:69], v[156:159], v[208:211], v[66:69]
	v_mfma_f32_16x16x32_bf16 v[94:97], v[152:155], v[188:191], v[94:97]
	v_mfma_f32_16x16x32_bf16 v[90:93], v[160:163], v[188:191], v[90:93]
	v_mfma_f32_16x16x32_bf16 v[86:89], v[152:155], v[196:199], v[86:89]
	v_mfma_f32_16x16x32_bf16 v[82:85], v[160:163], v[196:199], v[82:85]
	v_mfma_f32_16x16x32_bf16 v[78:81], v[152:155], v[204:207], v[78:81]
	v_mfma_f32_16x16x32_bf16 v[74:77], v[160:163], v[204:207], v[74:77]
	v_mfma_f32_16x16x32_bf16 v[70:73], v[152:155], v[212:215], v[70:73]
	v_mfma_f32_16x16x32_bf16 v[66:69], v[160:163], v[212:215], v[66:69]
	v_mfma_f32_16x16x32_bf16 v[30:33], v[164:167], v[184:187], v[30:33]
	v_mfma_f32_16x16x32_bf16 v[26:29], v[172:175], v[184:187], v[26:29]
	v_mfma_f32_16x16x32_bf16 v[22:25], v[164:167], v[192:195], v[22:25]
	v_mfma_f32_16x16x32_bf16 v[18:21], v[172:175], v[192:195], v[18:21]
	v_mfma_f32_16x16x32_bf16 v[14:17], v[164:167], v[200:203], v[14:17]
	v_mfma_f32_16x16x32_bf16 v[10:13], v[172:175], v[200:203], v[10:13]
	v_mfma_f32_16x16x32_bf16 v[6:9], v[164:167], v[208:211], v[6:9]
	v_mfma_f32_16x16x32_bf16 v[2:5], v[172:175], v[208:211], v[2:5]
	v_mfma_f32_16x16x32_bf16 v[30:33], v[168:171], v[188:191], v[30:33]
	v_mfma_f32_16x16x32_bf16 v[26:29], v[180:183], v[188:191], v[26:29]
	v_mfma_f32_16x16x32_bf16 v[22:25], v[168:171], v[196:199], v[22:25]
	v_mfma_f32_16x16x32_bf16 v[18:21], v[180:183], v[196:199], v[18:21]
	v_mfma_f32_16x16x32_bf16 v[14:17], v[168:171], v[204:207], v[14:17]
	v_mfma_f32_16x16x32_bf16 v[10:13], v[180:183], v[204:207], v[10:13]
	v_mfma_f32_16x16x32_bf16 v[6:9], v[168:171], v[212:215], v[6:9]
	v_mfma_f32_16x16x32_bf16 v[2:5], v[180:183], v[212:215], v[2:5]
	s_barrier
	s_setprio 0
	s_add_i32 s52, s52, 2
	s_add_u32 s14, s14, 0x100
	s_addc_u32 s15, s15, 0
	s_add_u32 s45, s45, 0x100
	s_addc_u32 s51, s51, 0
	s_cmp_gt_u32 s52, 5
	s_cbranch_scc0 .LBB0_2619
	v_readlane_b32 s14, v252, 14
	v_readlane_b32 s15, v252, 15
	s_and_b64 vcc, exec, s[14:15]
	s_cbranch_vccz .LBB0_2622
	s_barrier

; #define PG8_STAGE(bufoff, gbase, voff) do { _Pragma("unroll") for (int _i = 0; _i < 2; ++_i) \
;         __builtin_amdgcn_global_load_lds((const unsigned*)((const char*)(gbase) + (voff)[_i]), (LAS unsigned*)(lds + (bufoff) + ldsw + _i * 8192), 16, 0, 0); } while (0)
; #define PG8_LDA(dst, b, h) do { _Pragma("unroll") for (int m = 0; m < 4; ++m) _Pragma("unroll") for (int k = 0; k < 2; ++k) dst[m][k] = *(const LAS bf16x8*)(lds + PG8_SA(b, h) + aoff + m * 2048 + k * 1024); } while (0)
; #define PG8_LDB(dst, b, h) do { _Pragma("unroll") for (int n = 0; n < 2; ++n) _Pragma("unroll") for (int k = 0; k < 2; ++k) dst[n][k] = *(const LAS bf16x8*)(lds + PG8_SB(b, h) + boff + n * 2048 + k * 1024); } while (0)
; #define PG8_MMA(ai, bj, At, Bt) do { __builtin_amdgcn_s_setprio(1); _Pragma("unroll") for (int m = 0; m < 4; ++m) _Pragma("unroll") for (int n = 0; n < 2; ++n) _Pragma("unroll") for (int k = 0; k < 2; ++k) \
;         acc[ai][bj][m][n] = __builtin_amdgcn_mfma_f32_16x16x32_bf16(Bt[n][k], At[m][k], acc[ai][bj][m][n], 0, 0, 0); __builtin_amdgcn_s_setprio(0); } while (0)
; #define PG8_WAIT_V(n) asm volatile("s_waitcnt vmcnt(" #n ")" ::: "memory")
; #define PG8_WAIT_L(n) asm volatile("s_waitcnt lgkmcnt(" #n ")" ::: "memory")
; #define PG8_BAR __builtin_amdgcn_s_barrier()
; template <class Epi, class Sched, int LDA, int LDB, bool ALIGN_EPI = true>
; __device__ __forceinline__ void gemm_phase(LAS unsigned char* lds, const Gemm g, const Sched& S, const Epi& E, int wave) {
;     ...
;         for (int t = 0; t < nt; t += 2) {
;             const bool last = (t == nt - 2);
;             const char* a1 = cA + (size_t)(t + 1) * kstep;
;             const char* a2 = last ? nA : cA + (size_t)(t + 2) * kstep; const char* b2 = last ? nB : cB + (size_t)(t + 2) * kstep;
;             const char* a3 = a2 + kstep; const char* b3 = b2 + kstep;
;             PG8_LDB(B0, 0, 0); PG8_LDB(B1, 0, 1); PG8_SCHED; PG8_LDA(At, 0, 0); PG8_STAGE(PG8_SA(1, 1), a1 + hstepA, voffA);
;             PG8_WAIT_V(8); PG8_WAIT_L(0); PG8_BAR; PG8_MMA(0, 0, At, B0); PG8_MMA(0, 1, At, B1); PG8_BAR; PG8_SCHED;
;             PG8_LDA(At, 0, 1); PG8_STAGE(PG8_SB(0, 0), b2, voffB); PG8_STAGE(PG8_SB(0, 1), b2 + hstepB, voffB); PG8_STAGE(PG8_SA(0, 0), a2, voffA);
;             PG8_WAIT_V(8); PG8_WAIT_L(0); PG8_BAR; PG8_MMA(1, 0, At, B0); PG8_MMA(1, 1, At, B1); PG8_BAR; PG8_SCHED;
.LBB0_2649:
	s_add_u32 s18, s16, 0xfffe0080
	s_addc_u32 s19, s17, -1
	s_add_i32 s48, 0, 0x10000
	s_cmp_eq_u32 s47, 4
	s_cselect_b32 s25, s7, s19
	s_cselect_b32 s24, s13, s18
	s_cselect_b32 s19, s3, s46
	s_cselect_b32 s18, s44, s45
	s_add_i32 s50, 0, 0x14000
	v_add_u32_e32 v152, s48, v161
	v_add_u32_e32 v172, s50, v161
	ds_read_b128 v[130:133], v152
	ds_read_b128 v[134:137], v152 offset:1024
	ds_read_b128 v[148:151], v152 offset:2048
	ds_read_b128 v[152:155], v152 offset:3072
	ds_read_b128 v[156:159], v172
	ds_read_b128 v[164:167], v172 offset:1024
	ds_read_b128 v[168:171], v172 offset:2048
	ds_read_b128 v[172:175], v172 offset:3072
	v_lshl_add_u64 v[212:213], s[16:17], 0, v[144:145]
	s_add_i32 m0, s15, 0xc000
	ds_read_b128 v[180:183], v163
	ds_read_b128 v[184:187], v163 offset:1024
	ds_read_b128 v[188:191], v163 offset:2048
	ds_read_b128 v[192:195], v163 offset:3072
	ds_read_b128 v[196:199], v163 offset:4096
	ds_read_b128 v[200:203], v163 offset:5120
	ds_read_b128 v[204:207], v163 offset:6144
	ds_read_b128 v[208:211], v163 offset:7168
	global_load_lds_dwordx4 v[212:213], off
	v_lshl_add_u64 v[212:213], s[16:17], 0, v[146:147]
	s_add_i32 m0, s15, 0xe000
	s_nop 0
	global_load_lds_dwordx4 v[212:213], off
	s_waitcnt vmcnt(8)
	s_waitcnt lgkmcnt(0)
	s_setprio 3
	s_barrier
	v_mfma_f32_16x16x32_bf16 v[126:129], v[130:133], v[180:183], v[126:129]
	v_mfma_f32_16x16x32_bf16 v[122:125], v[148:151], v[180:183], v[122:125]
	v_mfma_f32_16x16x32_bf16 v[110:113], v[130:133], v[188:191], v[110:113]
	v_mfma_f32_16x16x32_bf16 v[106:109], v[148:151], v[188:191], v[106:109]
	v_mfma_f32_16x16x32_bf16 v[94:97], v[130:133], v[196:199], v[94:97]
	v_mfma_f32_16x16x32_bf16 v[90:93], v[148:151], v[196:199], v[90:93]
	v_mfma_f32_16x16x32_bf16 v[78:81], v[130:133], v[204:207], v[78:81]
	v_mfma_f32_16x16x32_bf16 v[74:77], v[148:151], v[204:207], v[74:77]
	v_mfma_f32_16x16x32_bf16 v[126:129], v[134:137], v[184:187], v[126:129]
	v_mfma_f32_16x16x32_bf16 v[122:125], v[152:155], v[184:187], v[122:125]
	v_mfma_f32_16x16x32_bf16 v[110:113], v[134:137], v[192:195], v[110:113]
	v_mfma_f32_16x16x32_bf16 v[106:109], v[152:155], v[192:195], v[106:109]
	v_mfma_f32_16x16x32_bf16 v[94:97], v[134:137], v[200:203], v[94:97]
	v_mfma_f32_16x16x32_bf16 v[90:93], v[152:155], v[200:203], v[90:93]
	v_mfma_f32_16x16x32_bf16 v[78:81], v[134:137], v[208:211], v[78:81]
	v_mfma_f32_16x16x32_bf16 v[74:77], v[152:155], v[208:211], v[74:77]
	v_mfma_f32_16x16x32_bf16 v[118:121], v[156:159], v[180:183], v[118:121]
	v_mfma_f32_16x16x32_bf16 v[114:117], v[168:171], v[180:183], v[114:117]
	v_mfma_f32_16x16x32_bf16 v[102:105], v[156:159], v[188:191], v[102:105]
	v_mfma_f32_16x16x32_bf16 v[98:101], v[168:171], v[188:191], v[98:101]
	v_mfma_f32_16x16x32_bf16 v[86:89], v[156:159], v[196:199], v[86:89]
	v_mfma_f32_16x16x32_bf16 v[82:85], v[168:171], v[196:199], v[82:85]
	v_mfma_f32_16x16x32_bf16 v[70:73], v[156:159], v[204:207], v[70:73]
	v_mfma_f32_16x16x32_bf16 v[66:69], v[168:171], v[204:207], v[66:69]
	v_mfma_f32_16x16x32_bf16 v[118:121], v[164:167], v[184:187], v[118:121]
	v_mfma_f32_16x16x32_bf16 v[114:117], v[172:175], v[184:187], v[114:117]
	v_mfma_f32_16x16x32_bf16 v[102:105], v[164:167], v[192:195], v[102:105]
	v_mfma_f32_16x16x32_bf16 v[98:101], v[172:175], v[192:195], v[98:101]
	v_mfma_f32_16x16x32_bf16 v[86:89], v[164:167], v[200:203], v[86:89]
	v_mfma_f32_16x16x32_bf16 v[82:85], v[172:175], v[200:203], v[82:85]
	v_mfma_f32_16x16x32_bf16 v[70:73], v[164:167], v[208:211], v[70:73]
	v_mfma_f32_16x16x32_bf16 v[66:69], v[172:175], v[208:211], v[66:69]
	s_barrier
	s_setprio 0
	s_add_i32 s48, s48, s51
	v_lshl_add_u64 v[212:213], s[18:19], 0, v[0:1]
	s_mov_b32 m0, s48
	ds_read_b128 v[180:183], v163 offset:16384
	ds_read_b128 v[184:187], v163 offset:17408
	ds_read_b128 v[188:191], v163 offset:18432
	ds_read_b128 v[192:195], v163 offset:19456
	ds_read_b128 v[196:199], v163 offset:20480
	ds_read_b128 v[200:203], v163 offset:21504
	ds_read_b128 v[204:207], v163 offset:22528
	ds_read_b128 v[208:211], v163 offset:23552
	global_load_lds_dwordx4 v[212:213], off
	s_add_i32 m0, s48, 0x2000
	s_add_u32 s48, s18, 0x20000
	v_lshl_add_u64 v[214:215], s[18:19], 0, v[142:143]
	s_addc_u32 s49, s19, 0
	s_add_i32 s50, s50, s51
	global_load_lds_dwordx4 v[214:215], off
	v_lshl_add_u64 v[216:217], s[48:49], 0, v[0:1]
	s_mov_b32 m0, s50
	v_lshl_add_u64 v[218:219], s[24:25], 0, v[140:141]
	global_load_lds_dwordx4 v[216:217], off
	v_lshl_add_u64 v[216:217], s[48:49], 0, v[142:143]
	s_add_i32 m0, s50, 0x2000
	s_nop 0
	global_load_lds_dwordx4 v[216:217], off
	v_lshl_add_u64 v[216:217], s[24:25], 0, v[138:139]
	s_mov_b32 m0, s15
	s_nop 0
	global_load_lds_dwordx4 v[216:217], off
	s_mov_b32 m0, s28
	s_nop 0
	global_load_lds_dwordx4 v[218:219], off
	s_waitcnt vmcnt(8)
	s_waitcnt lgkmcnt(0)
	s_setprio 3
	s_barrier
; #define PG8_STAGE(bufoff, gbase, voff) do { _Pragma("unroll") for (int _i = 0; _i < 2; ++_i) \
;         __builtin_amdgcn_global_load_lds((const unsigned*)((const char*)(gbase) + (voff)[_i]), (LAS unsigned*)(lds + (bufoff) + ldsw + _i * 8192), 16, 0, 0); } while (0)
; #define PG8_LDA(dst, b, h) do { _Pragma("unroll") for (int m = 0; m < 4; ++m) _Pragma("unroll") for (int k = 0; k < 2; ++k) dst[m][k] = *(const LAS bf16x8*)(lds + PG8_SA(b, h) + aoff + m * 2048 + k * 1024); } while (0)
; #define PG8_LDB(dst, b, h) do { _Pragma("unroll") for (int n = 0; n < 2; ++n) _Pragma("unroll") for (int k = 0; k < 2; ++k) dst[n][k] = *(const LAS bf16x8*)(lds + PG8_SB(b, h) + boff + n * 2048 + k * 1024); } while (0)
; #define PG8_MMA(ai, bj, At, Bt) do { __builtin_amdgcn_s_setprio(1); _Pragma("unroll") for (int m = 0; m < 4; ++m) _Pragma("unroll") for (int n = 0; n < 2; ++n) _Pragma("unroll") for (int k = 0; k < 2; ++k) \
;         acc[ai][bj][m][n] = __builtin_amdgcn_mfma_f32_16x16x32_bf16(Bt[n][k], At[m][k], acc[ai][bj][m][n], 0, 0, 0); __builtin_amdgcn_s_setprio(0); } while (0)
; #define PG8_WAIT_V(n) asm volatile("s_waitcnt vmcnt(" #n ")" ::: "memory")
; #define PG8_WAIT_L(n) asm volatile("s_waitcnt lgkmcnt(" #n ")" ::: "memory")
; #define PG8_BAR __builtin_amdgcn_s_barrier()
; #define PG8_SCHED __builtin_amdgcn_sched_barrier(0)
; template <class Epi, class Sched, int LDA, int LDB, bool ALIGN_EPI = true>
; __device__ __forceinline__ void gemm_phase(LAS unsigned char* lds, const Gemm g, const Sched& S, const Epi& E, int wave) {
;     ...
;             PG8_WAIT_V(8); PG8_WAIT_L(0); PG8_BAR; PG8_MMA(1, 0, At, B0); PG8_MMA(1, 1, At, B1); PG8_BAR; PG8_SCHED;
;             PG8_LDB(B0, 1, 0); PG8_LDB(B1, 1, 1); PG8_SCHED; PG8_LDA(At, 1, 0); PG8_STAGE(PG8_SA(0, 1), a2 + hstepA, voffA);
;             PG8_WAIT_V(8); PG8_WAIT_L(0); PG8_BAR; PG8_MMA(0, 0, At, B0); PG8_MMA(0, 1, At, B1); PG8_BAR; PG8_SCHED;
	v_mfma_f32_16x16x32_bf16 v[62:65], v[130:133], v[180:183], v[62:65]
	v_mfma_f32_16x16x32_bf16 v[58:61], v[148:151], v[180:183], v[58:61]
	v_mfma_f32_16x16x32_bf16 v[46:49], v[130:133], v[188:191], v[46:49]
	v_mfma_f32_16x16x32_bf16 v[42:45], v[148:151], v[188:191], v[42:45]
	v_mfma_f32_16x16x32_bf16 v[30:33], v[130:133], v[196:199], v[30:33]
	v_mfma_f32_16x16x32_bf16 v[26:29], v[148:151], v[196:199], v[26:29]
	v_mfma_f32_16x16x32_bf16 v[14:17], v[130:133], v[204:207], v[14:17]
	v_mfma_f32_16x16x32_bf16 v[10:13], v[148:151], v[204:207], v[10:13]
	v_mfma_f32_16x16x32_bf16 v[62:65], v[134:137], v[184:187], v[62:65]
	v_mfma_f32_16x16x32_bf16 v[58:61], v[152:155], v[184:187], v[58:61]
	v_mfma_f32_16x16x32_bf16 v[46:49], v[134:137], v[192:195], v[46:49]
	v_mfma_f32_16x16x32_bf16 v[42:45], v[152:155], v[192:195], v[42:45]
	v_mfma_f32_16x16x32_bf16 v[30:33], v[134:137], v[200:203], v[30:33]
	v_mfma_f32_16x16x32_bf16 v[26:29], v[152:155], v[200:203], v[26:29]
	v_mfma_f32_16x16x32_bf16 v[14:17], v[134:137], v[208:211], v[14:17]
	v_mfma_f32_16x16x32_bf16 v[10:13], v[152:155], v[208:211], v[10:13]
	v_mfma_f32_16x16x32_bf16 v[54:57], v[156:159], v[180:183], v[54:57]
	v_mfma_f32_16x16x32_bf16 v[50:53], v[168:171], v[180:183], v[50:53]
	v_mfma_f32_16x16x32_bf16 v[38:41], v[156:159], v[188:191], v[38:41]
	v_mfma_f32_16x16x32_bf16 v[34:37], v[168:171], v[188:191], v[34:37]
	v_mfma_f32_16x16x32_bf16 v[22:25], v[156:159], v[196:199], v[22:25]
	v_mfma_f32_16x16x32_bf16 v[18:21], v[168:171], v[196:199], v[18:21]
	v_mfma_f32_16x16x32_bf16 v[6:9], v[156:159], v[204:207], v[6:9]
	v_mfma_f32_16x16x32_bf16 v[2:5], v[168:171], v[204:207], v[2:5]
	v_mfma_f32_16x16x32_bf16 v[54:57], v[164:167], v[184:187], v[54:57]
	v_mfma_f32_16x16x32_bf16 v[50:53], v[172:175], v[184:187], v[50:53]
	v_mfma_f32_16x16x32_bf16 v[38:41], v[164:167], v[192:195], v[38:41]
	v_mfma_f32_16x16x32_bf16 v[34:37], v[172:175], v[192:195], v[34:37]
	v_mfma_f32_16x16x32_bf16 v[22:25], v[164:167], v[200:203], v[22:25]
	v_mfma_f32_16x16x32_bf16 v[18:21], v[172:175], v[200:203], v[18:21]
	v_mfma_f32_16x16x32_bf16 v[6:9], v[164:167], v[208:211], v[6:9]
	v_mfma_f32_16x16x32_bf16 v[2:5], v[172:175], v[208:211], v[2:5]
	s_barrier
	s_setprio 0
	s_add_i32 s48, 0, 0x18000
	s_add_i32 s49, 0, 0x1c000
	v_add_u32_e32 v152, s48, v161
	v_add_u32_e32 v172, s49, v161
	ds_read_b128 v[130:133], v152
	ds_read_b128 v[134:137], v152 offset:1024
	ds_read_b128 v[148:151], v152 offset:2048
	ds_read_b128 v[152:155], v152 offset:3072
	ds_read_b128 v[156:159], v172
	ds_read_b128 v[164:167], v172 offset:1024
	ds_read_b128 v[168:171], v172 offset:2048
	ds_read_b128 v[172:175], v172 offset:3072
	s_add_u32 s24, s24, 0x20000
	s_addc_u32 s25, s25, 0
	s_mov_b32 m0, s29
	v_lshl_add_u64 v[220:221], s[24:25], 0, v[138:139]
	ds_read_b128 v[180:183], v163 offset:32768
	ds_read_b128 v[184:187], v163 offset:33792
	ds_read_b128 v[188:191], v163 offset:34816
	ds_read_b128 v[192:195], v163 offset:35840
	ds_read_b128 v[196:199], v163 offset:36864
	ds_read_b128 v[200:203], v163 offset:37888
	ds_read_b128 v[204:207], v163 offset:38912
	ds_read_b128 v[208:211], v163 offset:39936
	global_load_lds_dwordx4 v[220:221], off
	v_lshl_add_u64 v[220:221], s[24:25], 0, v[140:141]
	s_mov_b32 m0, s34
	s_nop 0
	global_load_lds_dwordx4 v[220:221], off
	s_waitcnt vmcnt(8)
	s_waitcnt lgkmcnt(0)
	s_setprio 3
	s_barrier
	v_mfma_f32_16x16x32_bf16 v[126:129], v[130:133], v[180:183], v[126:129]
	v_mfma_f32_16x16x32_bf16 v[122:125], v[148:151], v[180:183], v[122:125]
	v_mfma_f32_16x16x32_bf16 v[110:113], v[130:133], v[188:191], v[110:113]
	v_mfma_f32_16x16x32_bf16 v[106:109], v[148:151], v[188:191], v[106:109]
	v_mfma_f32_16x16x32_bf16 v[94:97], v[130:133], v[196:199], v[94:97]
	v_mfma_f32_16x16x32_bf16 v[90:93], v[148:151], v[196:199], v[90:93]
	v_mfma_f32_16x16x32_bf16 v[78:81], v[130:133], v[204:207], v[78:81]
	v_mfma_f32_16x16x32_bf16 v[74:77], v[148:151], v[204:207], v[74:77]
	v_mfma_f32_16x16x32_bf16 v[126:129], v[134:137], v[184:187], v[126:129]
	v_mfma_f32_16x16x32_bf16 v[122:125], v[152:155], v[184:187], v[122:125]
	v_mfma_f32_16x16x32_bf16 v[110:113], v[134:137], v[192:195], v[110:113]
	v_mfma_f32_16x16x32_bf16 v[106:109], v[152:155], v[192:195], v[106:109]
	v_mfma_f32_16x16x32_bf16 v[94:97], v[134:137], v[200:203], v[94:97]
	v_mfma_f32_16x16x32_bf16 v[90:93], v[152:155], v[200:203], v[90:93]
	v_mfma_f32_16x16x32_bf16 v[78:81], v[134:137], v[208:211], v[78:81]
	v_mfma_f32_16x16x32_bf16 v[74:77], v[152:155], v[208:211], v[74:77]
	v_mfma_f32_16x16x32_bf16 v[118:121], v[156:159], v[180:183], v[118:121]
	v_mfma_f32_16x16x32_bf16 v[114:117], v[168:171], v[180:183], v[114:117]
	v_mfma_f32_16x16x32_bf16 v[102:105], v[156:159], v[188:191], v[102:105]
	v_mfma_f32_16x16x32_bf16 v[98:101], v[168:171], v[188:191], v[98:101]
	v_mfma_f32_16x16x32_bf16 v[86:89], v[156:159], v[196:199], v[86:89]
	v_mfma_f32_16x16x32_bf16 v[82:85], v[168:171], v[196:199], v[82:85]
	v_mfma_f32_16x16x32_bf16 v[70:73], v[156:159], v[204:207], v[70:73]
	v_mfma_f32_16x16x32_bf16 v[66:69], v[168:171], v[204:207], v[66:69]
	v_mfma_f32_16x16x32_bf16 v[118:121], v[164:167], v[184:187], v[118:121]
	v_mfma_f32_16x16x32_bf16 v[114:117], v[172:175], v[184:187], v[114:117]
	v_mfma_f32_16x16x32_bf16 v[102:105], v[164:167], v[192:195], v[102:105]
	v_mfma_f32_16x16x32_bf16 v[98:101], v[172:175], v[192:195], v[98:101]
	v_mfma_f32_16x16x32_bf16 v[86:89], v[164:167], v[200:203], v[86:89]
	v_mfma_f32_16x16x32_bf16 v[82:85], v[172:175], v[200:203], v[82:85]
	v_mfma_f32_16x16x32_bf16 v[70:73], v[164:167], v[208:211], v[70:73]
	v_mfma_f32_16x16x32_bf16 v[66:69], v[172:175], v[208:211], v[66:69]
	s_barrier
; #define PG8_STAGE(bufoff, gbase, voff) do { _Pragma("unroll") for (int _i = 0; _i < 2; ++_i) \
;         __builtin_amdgcn_global_load_lds((const unsigned*)((const char*)(gbase) + (voff)[_i]), (LAS unsigned*)(lds + (bufoff) + ldsw + _i * 8192), 16, 0, 0); } while (0)
; #define PG8_LDA(dst, b, h) do { _Pragma("unroll") for (int m = 0; m < 4; ++m) _Pragma("unroll") for (int k = 0; k < 2; ++k) dst[m][k] = *(const LAS bf16x8*)(lds + PG8_SA(b, h) + aoff + m * 2048 + k * 1024); } while (0)
; #define PG8_MMA(ai, bj, At, Bt) do { __builtin_amdgcn_s_setprio(1); _Pragma("unroll") for (int m = 0; m < 4; ++m) _Pragma("unroll") for (int n = 0; n < 2; ++n) _Pragma("unroll") for (int k = 0; k < 2; ++k) \
;         acc[ai][bj][m][n] = __builtin_amdgcn_mfma_f32_16x16x32_bf16(Bt[n][k], At[m][k], acc[ai][bj][m][n], 0, 0, 0); __builtin_amdgcn_s_setprio(0); } while (0)
; #define PG8_WAIT_V(n) asm volatile("s_waitcnt vmcnt(" #n ")" ::: "memory")
; #define PG8_WAIT_L(n) asm volatile("s_waitcnt lgkmcnt(" #n ")" ::: "memory")
; #define PG8_BAR __builtin_amdgcn_s_barrier()
; #define PG8_SCHED __builtin_amdgcn_sched_barrier(0)
; template <class Epi, class Sched, int LDA, int LDB, bool ALIGN_EPI = true>
; __device__ __forceinline__ void gemm_phase(LAS unsigned char* lds, const Gemm g, const Sched& S, const Epi& E, int wave) {
;     ...
;             PG8_LDA(At, 1, 1); PG8_STAGE(PG8_SB(1, 0), b3, voffB); PG8_STAGE(PG8_SB(1, 1), b3 + hstepB, voffB); PG8_STAGE(PG8_SA(1, 0), a3, voffA);
;             PG8_WAIT_V(8); PG8_WAIT_L(0); PG8_BAR; PG8_MMA(1, 0, At, B0); PG8_MMA(1, 1, At, B1); PG8_BAR; PG8_SCHED;
;         }
;         if constexpr (ALIGN_EPI) { if (wr == 0) PG8_BAR; }
	s_setprio 0
	s_add_i32 s24, s48, s51
	v_lshl_add_u64 v[212:213], v[212:213], 0, s[52:53]
	s_mov_b32 m0, s24
	ds_read_b128 v[180:183], v163 offset:49152
	ds_read_b128 v[184:187], v163 offset:50176
	ds_read_b128 v[188:191], v163 offset:51200
	ds_read_b128 v[192:195], v163 offset:52224
	ds_read_b128 v[196:199], v163 offset:53248
	ds_read_b128 v[200:203], v163 offset:54272
	ds_read_b128 v[204:207], v163 offset:55296
	ds_read_b128 v[208:211], v163 offset:56320
	global_load_lds_dwordx4 v[212:213], off
	s_add_i32 m0, s24, 0x2000
	s_add_u32 s18, s18, 0x20080
	v_lshl_add_u64 v[212:213], v[214:215], 0, s[52:53]
	s_addc_u32 s19, s19, 0
	s_add_i32 s24, s49, s51
	global_load_lds_dwordx4 v[212:213], off
	v_lshl_add_u64 v[212:213], s[18:19], 0, v[0:1]
	s_mov_b32 m0, s24
	s_nop 0
	global_load_lds_dwordx4 v[212:213], off
	v_lshl_add_u64 v[212:213], s[18:19], 0, v[142:143]
	s_add_i32 m0, s24, 0x2000
	s_nop 0
	global_load_lds_dwordx4 v[212:213], off
	v_lshl_add_u64 v[212:213], v[216:217], 0, s[52:53]
	s_mov_b32 m0, s35
	s_nop 0
	global_load_lds_dwordx4 v[212:213], off
	v_lshl_add_u64 v[212:213], v[218:219], 0, s[52:53]
	s_mov_b32 m0, s36
	s_nop 0
	global_load_lds_dwordx4 v[212:213], off
	s_waitcnt vmcnt(8)
	s_waitcnt lgkmcnt(0)
	s_setprio 3
	s_barrier
	v_mfma_f32_16x16x32_bf16 v[62:65], v[130:133], v[180:183], v[62:65]
	v_mfma_f32_16x16x32_bf16 v[58:61], v[148:151], v[180:183], v[58:61]
	v_mfma_f32_16x16x32_bf16 v[46:49], v[130:133], v[188:191], v[46:49]
	v_mfma_f32_16x16x32_bf16 v[42:45], v[148:151], v[188:191], v[42:45]
	v_mfma_f32_16x16x32_bf16 v[30:33], v[130:133], v[196:199], v[30:33]
	v_mfma_f32_16x16x32_bf16 v[26:29], v[148:151], v[196:199], v[26:29]
	v_mfma_f32_16x16x32_bf16 v[14:17], v[130:133], v[204:207], v[14:17]
	v_mfma_f32_16x16x32_bf16 v[10:13], v[148:151], v[204:207], v[10:13]
	v_mfma_f32_16x16x32_bf16 v[62:65], v[134:137], v[184:187], v[62:65]
	v_mfma_f32_16x16x32_bf16 v[58:61], v[152:155], v[184:187], v[58:61]
	v_mfma_f32_16x16x32_bf16 v[46:49], v[134:137], v[192:195], v[46:49]
	v_mfma_f32_16x16x32_bf16 v[42:45], v[152:155], v[192:195], v[42:45]
	v_mfma_f32_16x16x32_bf16 v[30:33], v[134:137], v[200:203], v[30:33]
	v_mfma_f32_16x16x32_bf16 v[26:29], v[152:155], v[200:203], v[26:29]
	v_mfma_f32_16x16x32_bf16 v[14:17], v[134:137], v[208:211], v[14:17]
	v_mfma_f32_16x16x32_bf16 v[10:13], v[152:155], v[208:211], v[10:13]
	v_mfma_f32_16x16x32_bf16 v[54:57], v[156:159], v[180:183], v[54:57]
	v_mfma_f32_16x16x32_bf16 v[50:53], v[168:171], v[180:183], v[50:53]
	v_mfma_f32_16x16x32_bf16 v[38:41], v[156:159], v[188:191], v[38:41]
	v_mfma_f32_16x16x32_bf16 v[34:37], v[168:171], v[188:191], v[34:37]
	v_mfma_f32_16x16x32_bf16 v[22:25], v[156:159], v[196:199], v[22:25]
	v_mfma_f32_16x16x32_bf16 v[18:21], v[168:171], v[196:199], v[18:21]
	v_mfma_f32_16x16x32_bf16 v[6:9], v[156:159], v[204:207], v[6:9]
	v_mfma_f32_16x16x32_bf16 v[2:5], v[168:171], v[204:207], v[2:5]
	v_mfma_f32_16x16x32_bf16 v[54:57], v[164:167], v[184:187], v[54:57]
	v_mfma_f32_16x16x32_bf16 v[50:53], v[172:175], v[184:187], v[50:53]
	v_mfma_f32_16x16x32_bf16 v[38:41], v[164:167], v[192:195], v[38:41]
	v_mfma_f32_16x16x32_bf16 v[34:37], v[172:175], v[192:195], v[34:37]
	v_mfma_f32_16x16x32_bf16 v[22:25], v[164:167], v[200:203], v[22:25]
	v_mfma_f32_16x16x32_bf16 v[18:21], v[172:175], v[200:203], v[18:21]
	v_mfma_f32_16x16x32_bf16 v[6:9], v[164:167], v[208:211], v[6:9]
	v_mfma_f32_16x16x32_bf16 v[2:5], v[172:175], v[208:211], v[2:5]
	s_barrier
	s_setprio 0
	s_add_i32 s47, s47, 2
	s_add_u32 s16, s16, 0x100
	s_addc_u32 s17, s17, 0
	s_add_u32 s45, s45, 0x100
	s_addc_u32 s46, s46, 0
	s_cmp_gt_u32 s47, 5
	s_cbranch_scc0 .LBB0_2649
	v_readlane_b32 s16, v252, 14
	v_readlane_b32 s17, v252, 15
	s_and_b64 vcc, exec, s[16:17]
	s_cbranch_vccz .LBB0_2652
	s_barrier

; #define PG8_STAGE(bufoff, gbase, voff) do { _Pragma("unroll") for (int _i = 0; _i < 2; ++_i) \
;         __builtin_amdgcn_global_load_lds((const unsigned*)((const char*)(gbase) + (voff)[_i]), (LAS unsigned*)(lds + (bufoff) + ldsw + _i * 8192), 16, 0, 0); } while (0)
; #define PG8_LDA(dst, b, h) do { _Pragma("unroll") for (int m = 0; m < 4; ++m) _Pragma("unroll") for (int k = 0; k < 2; ++k) dst[m][k] = *(const LAS bf16x8*)(lds + PG8_SA(b, h) + aoff + m * 2048 + k * 1024); } while (0)
; #define PG8_LDB(dst, b, h) do { _Pragma("unroll") for (int n = 0; n < 2; ++n) _Pragma("unroll") for (int k = 0; k < 2; ++k) dst[n][k] = *(const LAS bf16x8*)(lds + PG8_SB(b, h) + boff + n * 2048 + k * 1024); } while (0)
; #define PG8_MMA(ai, bj, At, Bt) do { __builtin_amdgcn_s_setprio(1); _Pragma("unroll") for (int m = 0; m < 4; ++m) _Pragma("unroll") for (int n = 0; n < 2; ++n) _Pragma("unroll") for (int k = 0; k < 2; ++k) \
;         acc[ai][bj][m][n] = __builtin_amdgcn_mfma_f32_16x16x32_bf16(Bt[n][k], At[m][k], acc[ai][bj][m][n], 0, 0, 0); __builtin_amdgcn_s_setprio(0); } while (0)
; #define PG8_WAIT_V(n) asm volatile("s_waitcnt vmcnt(" #n ")" ::: "memory")
; #define PG8_WAIT_L(n) asm volatile("s_waitcnt lgkmcnt(" #n ")" ::: "memory")
; #define PG8_BAR __builtin_amdgcn_s_barrier()
; template <class Epi, class Sched, int LDA, int LDB, bool ALIGN_EPI = true>
; __device__ __forceinline__ void gemm_phase(LAS unsigned char* lds, const Gemm g, const Sched& S, const Epi& E, int wave) {
;     ...
;         for (int t = 0; t < nt; t += 2) {
;             const bool last = (t == nt - 2);
;             const char* a1 = cA + (size_t)(t + 1) * kstep;
;             const char* a2 = last ? nA : cA + (size_t)(t + 2) * kstep; const char* b2 = last ? nB : cB + (size_t)(t + 2) * kstep;
;             const char* a3 = a2 + kstep; const char* b3 = b2 + kstep;
;             PG8_LDB(B0, 0, 0); PG8_LDB(B1, 0, 1); PG8_SCHED; PG8_LDA(At, 0, 0); PG8_STAGE(PG8_SA(1, 1), a1 + hstepA, voffA);
;             PG8_WAIT_V(8); PG8_WAIT_L(0); PG8_BAR; PG8_MMA(0, 0, At, B0); PG8_MMA(0, 1, At, B1); PG8_BAR; PG8_SCHED;
;             PG8_LDA(At, 0, 1); PG8_STAGE(PG8_SB(0, 0), b2, voffB); PG8_STAGE(PG8_SB(0, 1), b2 + hstepB, voffB); PG8_STAGE(PG8_SA(0, 0), a2, voffA);
;             PG8_WAIT_V(8); PG8_WAIT_L(0); PG8_BAR; PG8_MMA(1, 0, At, B0); PG8_MMA(1, 1, At, B1); PG8_BAR; PG8_SCHED;
.LBB0_4715:
	s_add_i32 s49, s24, 2
	s_add_u32 s25, s18, 0xfff80080
	s_addc_u32 s28, s19, -1
	s_add_i32 s50, 0, 0x10000
	s_cmp_eq_u32 s17, s24
	s_cselect_b32 s29, s1, s28
	s_cselect_b32 s28, s7, s25
	v_add_u32_e32 v0, s50, v153
	s_cselect_b32 s25, s3, s45
	s_cselect_b32 s24, s15, s44
	s_add_i32 s52, 0, 0x14000
	ds_read_b128 v[144:147], v0
	ds_read_b128 v[148:151], v0 offset:1024
	ds_read_b128 v[156:159], v0 offset:2048
	ds_read_b128 v[160:163], v0 offset:3072
	v_add_u32_e32 v0, s52, v153
	ds_read_b128 v[164:167], v0
	ds_read_b128 v[168:171], v0 offset:1024
	ds_read_b128 v[172:175], v0 offset:2048
	ds_read_b128 v[180:183], v0 offset:3072
	v_lshl_add_u64 v[216:217], s[18:19], 0, v[140:141]
	s_add_i32 m0, s27, 0xc000
	ds_read_b128 v[184:187], v155
	ds_read_b128 v[188:191], v155 offset:1024
	ds_read_b128 v[192:195], v155 offset:2048
	ds_read_b128 v[196:199], v155 offset:3072
	ds_read_b128 v[200:203], v155 offset:4096
	ds_read_b128 v[204:207], v155 offset:5120
	ds_read_b128 v[208:211], v155 offset:6144
	ds_read_b128 v[212:215], v155 offset:7168
	global_load_lds_dwordx4 v[216:217], off
	v_lshl_add_u64 v[216:217], s[18:19], 0, v[142:143]
	s_add_i32 m0, s27, 0xe000
	s_nop 0
	global_load_lds_dwordx4 v[216:217], off
	s_waitcnt vmcnt(8)
	s_waitcnt lgkmcnt(0)
	s_setprio 3
	s_barrier
	v_mfma_f32_16x16x32_bf16 v[126:129], v[144:147], v[184:187], v[126:129]
	v_mfma_f32_16x16x32_bf16 v[122:125], v[156:159], v[184:187], v[122:125]
	v_mfma_f32_16x16x32_bf16 v[110:113], v[144:147], v[192:195], v[110:113]
	v_mfma_f32_16x16x32_bf16 v[106:109], v[156:159], v[192:195], v[106:109]
	v_mfma_f32_16x16x32_bf16 v[94:97], v[144:147], v[200:203], v[94:97]
	v_mfma_f32_16x16x32_bf16 v[90:93], v[156:159], v[200:203], v[90:93]
	v_mfma_f32_16x16x32_bf16 v[78:81], v[144:147], v[208:211], v[78:81]
	v_mfma_f32_16x16x32_bf16 v[74:77], v[156:159], v[208:211], v[74:77]
	v_mfma_f32_16x16x32_bf16 v[126:129], v[148:151], v[188:191], v[126:129]
	v_mfma_f32_16x16x32_bf16 v[122:125], v[160:163], v[188:191], v[122:125]
	v_mfma_f32_16x16x32_bf16 v[110:113], v[148:151], v[196:199], v[110:113]
	v_mfma_f32_16x16x32_bf16 v[106:109], v[160:163], v[196:199], v[106:109]
	v_mfma_f32_16x16x32_bf16 v[94:97], v[148:151], v[204:207], v[94:97]
	v_mfma_f32_16x16x32_bf16 v[90:93], v[160:163], v[204:207], v[90:93]
	v_mfma_f32_16x16x32_bf16 v[78:81], v[148:151], v[212:215], v[78:81]
	v_mfma_f32_16x16x32_bf16 v[74:77], v[160:163], v[212:215], v[74:77]
	v_mfma_f32_16x16x32_bf16 v[118:121], v[164:167], v[184:187], v[118:121]
	v_mfma_f32_16x16x32_bf16 v[114:117], v[172:175], v[184:187], v[114:117]
	v_mfma_f32_16x16x32_bf16 v[102:105], v[164:167], v[192:195], v[102:105]
	v_mfma_f32_16x16x32_bf16 v[98:101], v[172:175], v[192:195], v[98:101]
	v_mfma_f32_16x16x32_bf16 v[86:89], v[164:167], v[200:203], v[86:89]
	v_mfma_f32_16x16x32_bf16 v[82:85], v[172:175], v[200:203], v[82:85]
	v_mfma_f32_16x16x32_bf16 v[70:73], v[164:167], v[208:211], v[70:73]
	v_mfma_f32_16x16x32_bf16 v[66:69], v[172:175], v[208:211], v[66:69]
	v_mfma_f32_16x16x32_bf16 v[118:121], v[168:171], v[188:191], v[118:121]
	v_mfma_f32_16x16x32_bf16 v[114:117], v[180:183], v[188:191], v[114:117]
	v_mfma_f32_16x16x32_bf16 v[102:105], v[168:171], v[196:199], v[102:105]
	v_mfma_f32_16x16x32_bf16 v[98:101], v[180:183], v[196:199], v[98:101]
	v_mfma_f32_16x16x32_bf16 v[86:89], v[168:171], v[204:207], v[86:89]
	v_mfma_f32_16x16x32_bf16 v[82:85], v[180:183], v[204:207], v[82:85]
	v_mfma_f32_16x16x32_bf16 v[70:73], v[168:171], v[212:215], v[70:73]
	v_mfma_f32_16x16x32_bf16 v[66:69], v[180:183], v[212:215], v[66:69]
	s_barrier
	s_setprio 0
	s_add_i32 s50, s50, s53
	v_lshl_add_u64 v[216:217], s[24:25], 0, v[132:133]
	s_mov_b32 m0, s50
	ds_read_b128 v[184:187], v155 offset:16384
	ds_read_b128 v[188:191], v155 offset:17408
	ds_read_b128 v[192:195], v155 offset:18432
	ds_read_b128 v[196:199], v155 offset:19456
	ds_read_b128 v[200:203], v155 offset:20480
	ds_read_b128 v[204:207], v155 offset:21504
	ds_read_b128 v[208:211], v155 offset:22528
	ds_read_b128 v[212:215], v155 offset:23552
	global_load_lds_dwordx4 v[216:217], off
	s_add_i32 m0, s50, 0x2000
	s_add_u32 s50, s24, 0x80000
	v_lshl_add_u64 v[218:219], s[24:25], 0, v[136:137]
	s_addc_u32 s51, s25, 0
	s_add_i32 s52, s52, s53
	global_load_lds_dwordx4 v[218:219], off
	v_lshl_add_u64 v[220:221], s[50:51], 0, v[132:133]
	s_mov_b32 m0, s52
	v_lshl_add_u64 v[222:223], s[28:29], 0, v[134:135]
	global_load_lds_dwordx4 v[220:221], off
	v_lshl_add_u64 v[220:221], s[50:51], 0, v[136:137]
	s_add_i32 m0, s52, 0x2000
	s_nop 0
	global_load_lds_dwordx4 v[220:221], off
	v_lshl_add_u64 v[220:221], s[28:29], 0, v[130:131]
	s_mov_b32 m0, s27
	s_nop 0
	global_load_lds_dwordx4 v[220:221], off
	s_mov_b32 m0, s34
	s_nop 0
	global_load_lds_dwordx4 v[222:223], off
	s_waitcnt vmcnt(8)
	s_waitcnt lgkmcnt(0)
	s_setprio 3
	s_barrier
; #define PG8_STAGE(bufoff, gbase, voff) do { _Pragma("unroll") for (int _i = 0; _i < 2; ++_i) \
;         __builtin_amdgcn_global_load_lds((const unsigned*)((const char*)(gbase) + (voff)[_i]), (LAS unsigned*)(lds + (bufoff) + ldsw + _i * 8192), 16, 0, 0); } while (0)
; #define PG8_LDA(dst, b, h) do { _Pragma("unroll") for (int m = 0; m < 4; ++m) _Pragma("unroll") for (int k = 0; k < 2; ++k) dst[m][k] = *(const LAS bf16x8*)(lds + PG8_SA(b, h) + aoff + m * 2048 + k * 1024); } while (0)
; #define PG8_LDB(dst, b, h) do { _Pragma("unroll") for (int n = 0; n < 2; ++n) _Pragma("unroll") for (int k = 0; k < 2; ++k) dst[n][k] = *(const LAS bf16x8*)(lds + PG8_SB(b, h) + boff + n * 2048 + k * 1024); } while (0)
; #define PG8_MMA(ai, bj, At, Bt) do { __builtin_amdgcn_s_setprio(1); _Pragma("unroll") for (int m = 0; m < 4; ++m) _Pragma("unroll") for (int n = 0; n < 2; ++n) _Pragma("unroll") for (int k = 0; k < 2; ++k) \
;         acc[ai][bj][m][n] = __builtin_amdgcn_mfma_f32_16x16x32_bf16(Bt[n][k], At[m][k], acc[ai][bj][m][n], 0, 0, 0); __builtin_amdgcn_s_setprio(0); } while (0)
; #define PG8_WAIT_V(n) asm volatile("s_waitcnt vmcnt(" #n ")" ::: "memory")
; #define PG8_WAIT_L(n) asm volatile("s_waitcnt lgkmcnt(" #n ")" ::: "memory")
; #define PG8_BAR __builtin_amdgcn_s_barrier()
; #define PG8_SCHED __builtin_amdgcn_sched_barrier(0)
; template <class Epi, class Sched, int LDA, int LDB, bool ALIGN_EPI = true>
; __device__ __forceinline__ void gemm_phase(LAS unsigned char* lds, const Gemm g, const Sched& S, const Epi& E, int wave) {
;     ...
;             PG8_WAIT_V(8); PG8_WAIT_L(0); PG8_BAR; PG8_MMA(1, 0, At, B0); PG8_MMA(1, 1, At, B1); PG8_BAR; PG8_SCHED;
;             PG8_LDB(B0, 1, 0); PG8_LDB(B1, 1, 1); PG8_SCHED; PG8_LDA(At, 1, 0); PG8_STAGE(PG8_SA(0, 1), a2 + hstepA, voffA);
;             PG8_WAIT_V(8); PG8_WAIT_L(0); PG8_BAR; PG8_MMA(0, 0, At, B0); PG8_MMA(0, 1, At, B1); PG8_BAR; PG8_SCHED;
	v_mfma_f32_16x16x32_bf16 v[62:65], v[144:147], v[184:187], v[62:65]
	v_mfma_f32_16x16x32_bf16 v[58:61], v[156:159], v[184:187], v[58:61]
	v_mfma_f32_16x16x32_bf16 v[46:49], v[144:147], v[192:195], v[46:49]
	v_mfma_f32_16x16x32_bf16 v[42:45], v[156:159], v[192:195], v[42:45]
	v_mfma_f32_16x16x32_bf16 v[30:33], v[144:147], v[200:203], v[30:33]
	v_mfma_f32_16x16x32_bf16 v[26:29], v[156:159], v[200:203], v[26:29]
	v_mfma_f32_16x16x32_bf16 v[14:17], v[144:147], v[208:211], v[14:17]
	v_mfma_f32_16x16x32_bf16 v[10:13], v[156:159], v[208:211], v[10:13]
	v_mfma_f32_16x16x32_bf16 v[62:65], v[148:151], v[188:191], v[62:65]
	v_mfma_f32_16x16x32_bf16 v[58:61], v[160:163], v[188:191], v[58:61]
	v_mfma_f32_16x16x32_bf16 v[46:49], v[148:151], v[196:199], v[46:49]
	v_mfma_f32_16x16x32_bf16 v[42:45], v[160:163], v[196:199], v[42:45]
	v_mfma_f32_16x16x32_bf16 v[30:33], v[148:151], v[204:207], v[30:33]
	v_mfma_f32_16x16x32_bf16 v[26:29], v[160:163], v[204:207], v[26:29]
	v_mfma_f32_16x16x32_bf16 v[14:17], v[148:151], v[212:215], v[14:17]
	v_mfma_f32_16x16x32_bf16 v[10:13], v[160:163], v[212:215], v[10:13]
	v_mfma_f32_16x16x32_bf16 v[54:57], v[164:167], v[184:187], v[54:57]
	v_mfma_f32_16x16x32_bf16 v[50:53], v[172:175], v[184:187], v[50:53]
	v_mfma_f32_16x16x32_bf16 v[38:41], v[164:167], v[192:195], v[38:41]
	v_mfma_f32_16x16x32_bf16 v[34:37], v[172:175], v[192:195], v[34:37]
	v_mfma_f32_16x16x32_bf16 v[22:25], v[164:167], v[200:203], v[22:25]
	v_mfma_f32_16x16x32_bf16 v[18:21], v[172:175], v[200:203], v[18:21]
	v_mfma_f32_16x16x32_bf16 v[6:9], v[164:167], v[208:211], v[6:9]
	v_mfma_f32_16x16x32_bf16 v[2:5], v[172:175], v[208:211], v[2:5]
	v_mfma_f32_16x16x32_bf16 v[54:57], v[168:171], v[188:191], v[54:57]
	v_mfma_f32_16x16x32_bf16 v[50:53], v[180:183], v[188:191], v[50:53]
	v_mfma_f32_16x16x32_bf16 v[38:41], v[168:171], v[196:199], v[38:41]
	v_mfma_f32_16x16x32_bf16 v[34:37], v[180:183], v[196:199], v[34:37]
	v_mfma_f32_16x16x32_bf16 v[22:25], v[168:171], v[204:207], v[22:25]
	v_mfma_f32_16x16x32_bf16 v[18:21], v[180:183], v[204:207], v[18:21]
	v_mfma_f32_16x16x32_bf16 v[6:9], v[168:171], v[212:215], v[6:9]
	v_mfma_f32_16x16x32_bf16 v[2:5], v[180:183], v[212:215], v[2:5]
	s_barrier
	s_setprio 0
	s_add_i32 s50, 0, 0x18000
	v_add_u32_e32 v0, s50, v153
	s_add_i32 s51, 0, 0x1c000
	ds_read_b128 v[144:147], v0
	ds_read_b128 v[148:151], v0 offset:1024
	ds_read_b128 v[156:159], v0 offset:2048
	ds_read_b128 v[160:163], v0 offset:3072
	v_add_u32_e32 v0, s51, v153
	ds_read_b128 v[164:167], v0
	ds_read_b128 v[168:171], v0 offset:1024
	ds_read_b128 v[172:175], v0 offset:2048
	ds_read_b128 v[180:183], v0 offset:3072
	s_add_u32 s28, s28, 0x80000
	s_addc_u32 s29, s29, 0
	s_mov_b32 m0, s35
	v_lshl_add_u64 v[224:225], s[28:29], 0, v[130:131]
	ds_read_b128 v[184:187], v155 offset:32768
	ds_read_b128 v[188:191], v155 offset:33792
	ds_read_b128 v[192:195], v155 offset:34816
	ds_read_b128 v[196:199], v155 offset:35840
	ds_read_b128 v[200:203], v155 offset:36864
	ds_read_b128 v[204:207], v155 offset:37888
	ds_read_b128 v[208:211], v155 offset:38912
	ds_read_b128 v[212:215], v155 offset:39936
	global_load_lds_dwordx4 v[224:225], off
	v_lshl_add_u64 v[224:225], s[28:29], 0, v[134:135]
	s_mov_b32 m0, s36
	s_nop 0
	global_load_lds_dwordx4 v[224:225], off
	s_waitcnt vmcnt(8)
	s_waitcnt lgkmcnt(0)
	s_setprio 3
	s_barrier
	v_mfma_f32_16x16x32_bf16 v[126:129], v[144:147], v[184:187], v[126:129]
	v_mfma_f32_16x16x32_bf16 v[122:125], v[156:159], v[184:187], v[122:125]
	v_mfma_f32_16x16x32_bf16 v[110:113], v[144:147], v[192:195], v[110:113]
	v_mfma_f32_16x16x32_bf16 v[106:109], v[156:159], v[192:195], v[106:109]
	v_mfma_f32_16x16x32_bf16 v[94:97], v[144:147], v[200:203], v[94:97]
	v_mfma_f32_16x16x32_bf16 v[90:93], v[156:159], v[200:203], v[90:93]
	v_mfma_f32_16x16x32_bf16 v[78:81], v[144:147], v[208:211], v[78:81]
	v_mfma_f32_16x16x32_bf16 v[74:77], v[156:159], v[208:211], v[74:77]
	v_mfma_f32_16x16x32_bf16 v[126:129], v[148:151], v[188:191], v[126:129]
	v_mfma_f32_16x16x32_bf16 v[122:125], v[160:163], v[188:191], v[122:125]
	v_mfma_f32_16x16x32_bf16 v[110:113], v[148:151], v[196:199], v[110:113]
	v_mfma_f32_16x16x32_bf16 v[106:109], v[160:163], v[196:199], v[106:109]
	v_mfma_f32_16x16x32_bf16 v[94:97], v[148:151], v[204:207], v[94:97]
	v_mfma_f32_16x16x32_bf16 v[90:93], v[160:163], v[204:207], v[90:93]
	v_mfma_f32_16x16x32_bf16 v[78:81], v[148:151], v[212:215], v[78:81]
	v_mfma_f32_16x16x32_bf16 v[74:77], v[160:163], v[212:215], v[74:77]
	v_mfma_f32_16x16x32_bf16 v[118:121], v[164:167], v[184:187], v[118:121]
	v_mfma_f32_16x16x32_bf16 v[114:117], v[172:175], v[184:187], v[114:117]
	v_mfma_f32_16x16x32_bf16 v[102:105], v[164:167], v[192:195], v[102:105]
	v_mfma_f32_16x16x32_bf16 v[98:101], v[172:175], v[192:195], v[98:101]
	v_mfma_f32_16x16x32_bf16 v[86:89], v[164:167], v[200:203], v[86:89]
	v_mfma_f32_16x16x32_bf16 v[82:85], v[172:175], v[200:203], v[82:85]
	v_mfma_f32_16x16x32_bf16 v[70:73], v[164:167], v[208:211], v[70:73]
	v_mfma_f32_16x16x32_bf16 v[66:69], v[172:175], v[208:211], v[66:69]
	v_mfma_f32_16x16x32_bf16 v[118:121], v[168:171], v[188:191], v[118:121]
	v_mfma_f32_16x16x32_bf16 v[114:117], v[180:183], v[188:191], v[114:117]
	v_mfma_f32_16x16x32_bf16 v[102:105], v[168:171], v[196:199], v[102:105]
	v_mfma_f32_16x16x32_bf16 v[98:101], v[180:183], v[196:199], v[98:101]
	v_mfma_f32_16x16x32_bf16 v[86:89], v[168:171], v[204:207], v[86:89]
	v_mfma_f32_16x16x32_bf16 v[82:85], v[180:183], v[204:207], v[82:85]
	v_mfma_f32_16x16x32_bf16 v[70:73], v[168:171], v[212:215], v[70:73]
	v_mfma_f32_16x16x32_bf16 v[66:69], v[180:183], v[212:215], v[66:69]
	s_barrier
; #define PG8_STAGE(bufoff, gbase, voff) do { _Pragma("unroll") for (int _i = 0; _i < 2; ++_i) \
;         __builtin_amdgcn_global_load_lds((const unsigned*)((const char*)(gbase) + (voff)[_i]), (LAS unsigned*)(lds + (bufoff) + ldsw + _i * 8192), 16, 0, 0); } while (0)
; #define PG8_LDA(dst, b, h) do { _Pragma("unroll") for (int m = 0; m < 4; ++m) _Pragma("unroll") for (int k = 0; k < 2; ++k) dst[m][k] = *(const LAS bf16x8*)(lds + PG8_SA(b, h) + aoff + m * 2048 + k * 1024); } while (0)
; #define PG8_MMA(ai, bj, At, Bt) do { __builtin_amdgcn_s_setprio(1); _Pragma("unroll") for (int m = 0; m < 4; ++m) _Pragma("unroll") for (int n = 0; n < 2; ++n) _Pragma("unroll") for (int k = 0; k < 2; ++k) \
;         acc[ai][bj][m][n] = __builtin_amdgcn_mfma_f32_16x16x32_bf16(Bt[n][k], At[m][k], acc[ai][bj][m][n], 0, 0, 0); __builtin_amdgcn_s_setprio(0); } while (0)
; #define PG8_WAIT_V(n) asm volatile("s_waitcnt vmcnt(" #n ")" ::: "memory")
; #define PG8_WAIT_L(n) asm volatile("s_waitcnt lgkmcnt(" #n ")" ::: "memory")
; #define PG8_BAR __builtin_amdgcn_s_barrier()
; #define PG8_SCHED __builtin_amdgcn_sched_barrier(0)
; template <class Epi, class Sched, int LDA, int LDB, bool ALIGN_EPI = true>
; __device__ __forceinline__ void gemm_phase(LAS unsigned char* lds, const Gemm g, const Sched& S, const Epi& E, int wave) {
;     ...
;             PG8_WAIT_V(8); PG8_WAIT_L(0); PG8_BAR; PG8_MMA(0, 0, At, B0); PG8_MMA(0, 1, At, B1); PG8_BAR; PG8_SCHED;
;             PG8_LDA(At, 1, 1); PG8_STAGE(PG8_SB(1, 0), b3, voffB); PG8_STAGE(PG8_SB(1, 1), b3 + hstepB, voffB); PG8_STAGE(PG8_SA(1, 0), a3, voffA);
;             PG8_WAIT_V(8); PG8_WAIT_L(0); PG8_BAR; PG8_MMA(1, 0, At, B0); PG8_MMA(1, 1, At, B1); PG8_BAR; PG8_SCHED;
;         }
;         if constexpr (ALIGN_EPI) { if (wr == 0) PG8_BAR; }
;         E(acc, cur, wr, wc, fr, fq);
	s_setprio 0
	s_add_i32 s28, s50, s53
	v_lshl_add_u64 v[216:217], v[216:217], 0, s[54:55]
	s_mov_b32 m0, s28
	ds_read_b128 v[184:187], v155 offset:49152
	ds_read_b128 v[188:191], v155 offset:50176
	ds_read_b128 v[192:195], v155 offset:51200
	ds_read_b128 v[196:199], v155 offset:52224
	ds_read_b128 v[200:203], v155 offset:53248
	ds_read_b128 v[204:207], v155 offset:54272
	ds_read_b128 v[208:211], v155 offset:55296
	ds_read_b128 v[212:215], v155 offset:56320
	global_load_lds_dwordx4 v[216:217], off
	s_add_i32 m0, s28, 0x2000
	s_add_u32 s24, s24, 0x80080
	v_lshl_add_u64 v[216:217], v[218:219], 0, s[54:55]
	s_addc_u32 s25, s25, 0
	s_add_i32 s28, s51, s53
	global_load_lds_dwordx4 v[216:217], off
	v_lshl_add_u64 v[216:217], s[24:25], 0, v[132:133]
	s_mov_b32 m0, s28
	s_nop 0
	global_load_lds_dwordx4 v[216:217], off
	v_lshl_add_u64 v[216:217], s[24:25], 0, v[136:137]
	s_add_i32 m0, s28, 0x2000
	s_nop 0
	global_load_lds_dwordx4 v[216:217], off
	v_lshl_add_u64 v[216:217], v[220:221], 0, s[54:55]
	s_mov_b32 m0, s37
	s_nop 0
	global_load_lds_dwordx4 v[216:217], off
	v_lshl_add_u64 v[216:217], v[222:223], 0, s[54:55]
	s_mov_b32 m0, s38
	s_nop 0
	global_load_lds_dwordx4 v[216:217], off
	s_waitcnt vmcnt(8)
	s_waitcnt lgkmcnt(0)
	s_setprio 3
	s_barrier
	v_mfma_f32_16x16x32_bf16 v[62:65], v[144:147], v[184:187], v[62:65]
	v_mfma_f32_16x16x32_bf16 v[58:61], v[156:159], v[184:187], v[58:61]
	v_mfma_f32_16x16x32_bf16 v[46:49], v[144:147], v[192:195], v[46:49]
	v_mfma_f32_16x16x32_bf16 v[42:45], v[156:159], v[192:195], v[42:45]
	v_mfma_f32_16x16x32_bf16 v[30:33], v[144:147], v[200:203], v[30:33]
	v_mfma_f32_16x16x32_bf16 v[26:29], v[156:159], v[200:203], v[26:29]
	v_mfma_f32_16x16x32_bf16 v[14:17], v[144:147], v[208:211], v[14:17]
	v_mfma_f32_16x16x32_bf16 v[10:13], v[156:159], v[208:211], v[10:13]
	v_mfma_f32_16x16x32_bf16 v[62:65], v[148:151], v[188:191], v[62:65]
	v_mfma_f32_16x16x32_bf16 v[58:61], v[160:163], v[188:191], v[58:61]
	v_mfma_f32_16x16x32_bf16 v[46:49], v[148:151], v[196:199], v[46:49]
	v_mfma_f32_16x16x32_bf16 v[42:45], v[160:163], v[196:199], v[42:45]
	v_mfma_f32_16x16x32_bf16 v[30:33], v[148:151], v[204:207], v[30:33]
	v_mfma_f32_16x16x32_bf16 v[26:29], v[160:163], v[204:207], v[26:29]
	v_mfma_f32_16x16x32_bf16 v[14:17], v[148:151], v[212:215], v[14:17]
	v_mfma_f32_16x16x32_bf16 v[10:13], v[160:163], v[212:215], v[10:13]
	v_mfma_f32_16x16x32_bf16 v[54:57], v[164:167], v[184:187], v[54:57]
	v_mfma_f32_16x16x32_bf16 v[50:53], v[172:175], v[184:187], v[50:53]
	v_mfma_f32_16x16x32_bf16 v[38:41], v[164:167], v[192:195], v[38:41]
	v_mfma_f32_16x16x32_bf16 v[34:37], v[172:175], v[192:195], v[34:37]
	v_mfma_f32_16x16x32_bf16 v[22:25], v[164:167], v[200:203], v[22:25]
	v_mfma_f32_16x16x32_bf16 v[18:21], v[172:175], v[200:203], v[18:21]
	v_mfma_f32_16x16x32_bf16 v[6:9], v[164:167], v[208:211], v[6:9]
	v_mfma_f32_16x16x32_bf16 v[2:5], v[172:175], v[208:211], v[2:5]
	v_mfma_f32_16x16x32_bf16 v[54:57], v[168:171], v[188:191], v[54:57]
	v_mfma_f32_16x16x32_bf16 v[50:53], v[180:183], v[188:191], v[50:53]
	v_mfma_f32_16x16x32_bf16 v[38:41], v[168:171], v[196:199], v[38:41]
	v_mfma_f32_16x16x32_bf16 v[34:37], v[180:183], v[196:199], v[34:37]
	v_mfma_f32_16x16x32_bf16 v[22:25], v[168:171], v[204:207], v[22:25]
	v_mfma_f32_16x16x32_bf16 v[18:21], v[180:183], v[204:207], v[18:21]
	v_mfma_f32_16x16x32_bf16 v[6:9], v[168:171], v[212:215], v[6:9]
	v_mfma_f32_16x16x32_bf16 v[2:5], v[180:183], v[212:215], v[2:5]
	s_barrier
	s_setprio 0
	s_add_u32 s18, s18, 0x100
	s_addc_u32 s19, s19, 0
	s_add_u32 s44, s44, 0x100
	s_addc_u32 s45, s45, 0
	s_cmp_ge_i32 s49, s43
	s_mov_b32 s24, s49
	s_cbranch_scc0 .LBB0_4715
	v_readlane_b32 s18, v252, 14
	v_readlane_b32 s19, v252, 15
	s_and_b64 vcc, exec, s[18:19]
	s_cbranch_vccz .LBB0_4718
	s_barrier

; #define PG8_STAGE(bufoff, gbase, voff) do { _Pragma("unroll") for (int _i = 0; _i < 2; ++_i) \
;         __builtin_amdgcn_global_load_lds((const unsigned*)((const char*)(gbase) + (voff)[_i]), (LAS unsigned*)(lds + (bufoff) + ldsw + _i * 8192), 16, 0, 0); } while (0)
; #define PG8_LDA(dst, b, h) do { _Pragma("unroll") for (int m = 0; m < 4; ++m) _Pragma("unroll") for (int k = 0; k < 2; ++k) dst[m][k] = *(const LAS bf16x8*)(lds + PG8_SA(b, h) + aoff + m * 2048 + k * 1024); } while (0)
; #define PG8_LDB(dst, b, h) do { _Pragma("unroll") for (int n = 0; n < 2; ++n) _Pragma("unroll") for (int k = 0; k < 2; ++k) dst[n][k] = *(const LAS bf16x8*)(lds + PG8_SB(b, h) + boff + n * 2048 + k * 1024); } while (0)
; #define PG8_MMA(ai, bj, At, Bt) do { __builtin_amdgcn_s_setprio(1); _Pragma("unroll") for (int m = 0; m < 4; ++m) _Pragma("unroll") for (int n = 0; n < 2; ++n) _Pragma("unroll") for (int k = 0; k < 2; ++k) \
;         acc[ai][bj][m][n] = __builtin_amdgcn_mfma_f32_16x16x32_bf16(Bt[n][k], At[m][k], acc[ai][bj][m][n], 0, 0, 0); __builtin_amdgcn_s_setprio(0); } while (0)
; #define PG8_WAIT_V(n) asm volatile("s_waitcnt vmcnt(" #n ")" ::: "memory")
; #define PG8_WAIT_L(n) asm volatile("s_waitcnt lgkmcnt(" #n ")" ::: "memory")
; #define PG8_BAR __builtin_amdgcn_s_barrier()
; template <class Epi, class Sched, int LDA, int LDB, bool ALIGN_EPI = true>
; __device__ __forceinline__ void gemm_phase(LAS unsigned char* lds, const Gemm g, const Sched& S, const Epi& E, int wave) {
;     ...
;         for (int t = 0; t < nt; t += 2) {
;             const bool last = (t == nt - 2);
;             const char* a1 = cA + (size_t)(t + 1) * kstep;
;             const char* a2 = last ? nA : cA + (size_t)(t + 2) * kstep; const char* b2 = last ? nB : cB + (size_t)(t + 2) * kstep;
;             const char* a3 = a2 + kstep; const char* b3 = b2 + kstep;
;             PG8_LDB(B0, 0, 0); PG8_LDB(B1, 0, 1); PG8_SCHED; PG8_LDA(At, 0, 0); PG8_STAGE(PG8_SA(1, 1), a1 + hstepA, voffA);
;             PG8_WAIT_V(8); PG8_WAIT_L(0); PG8_BAR; PG8_MMA(0, 0, At, B0); PG8_MMA(0, 1, At, B1); PG8_BAR; PG8_SCHED;
;             PG8_LDA(At, 0, 1); PG8_STAGE(PG8_SB(0, 0), b2, voffB); PG8_STAGE(PG8_SB(0, 1), b2 + hstepB, voffB); PG8_STAGE(PG8_SA(0, 0), a2, voffA);
;             PG8_WAIT_V(8); PG8_WAIT_L(0); PG8_BAR; PG8_MMA(1, 0, At, B0); PG8_MMA(1, 1, At, B1); PG8_BAR; PG8_SCHED;
.LBB0_4901:
	s_add_i32 s65, s36, 2
	s_add_u32 s37, s34, 0xfff80080
	s_addc_u32 s38, s35, -1
	s_add_i32 s66, 0, 0x10000
	s_cmp_eq_u32 s29, s36
	s_cselect_b32 s39, s9, s38
	s_cselect_b32 s38, s13, s37
	s_cselect_b32 s37, s11, s64
	s_cselect_b32 s36, s25, s59
	s_add_i32 s72, 0, 0x14000
	v_add_u32_e32 v70, s66, v213
	v_add_u32_e32 v168, s72, v213
	ds_read_b128 v[50:53], v70
	ds_read_b128 v[54:57], v70 offset:1024
	ds_read_b128 v[66:69], v70 offset:2048
	ds_read_b128 v[70:73], v70 offset:3072
	ds_read_b128 v[156:159], v168
	ds_read_b128 v[160:163], v168 offset:1024
	ds_read_b128 v[164:167], v168 offset:2048
	ds_read_b128 v[168:171], v168 offset:3072
	v_lshl_add_u64 v[208:209], s[34:35], 0, v[152:153]
	s_add_i32 m0, s27, 0xc000
	ds_read_b128 v[172:175], v215
	ds_read_b128 v[180:183], v215 offset:1024
	ds_read_b128 v[184:187], v215 offset:2048
	ds_read_b128 v[188:191], v215 offset:3072
	ds_read_b128 v[192:195], v215 offset:4096
	ds_read_b128 v[196:199], v215 offset:5120
	ds_read_b128 v[200:203], v215 offset:6144
	ds_read_b128 v[204:207], v215 offset:7168
	global_load_lds_dwordx4 v[208:209], off
	v_lshl_add_u64 v[208:209], s[34:35], 0, v[154:155]
	s_add_i32 m0, s27, 0xe000
	s_nop 0
	global_load_lds_dwordx4 v[208:209], off
	s_waitcnt vmcnt(8)
	s_waitcnt lgkmcnt(0)
	s_setprio 3
	s_barrier
	v_mfma_f32_16x16x32_bf16 v[142:145], v[50:53], v[172:175], v[142:145]
	v_mfma_f32_16x16x32_bf16 v[138:141], v[66:69], v[172:175], v[138:141]
	v_mfma_f32_16x16x32_bf16 v[126:129], v[50:53], v[184:187], v[126:129]
	v_mfma_f32_16x16x32_bf16 v[122:125], v[66:69], v[184:187], v[122:125]
	v_mfma_f32_16x16x32_bf16 v[110:113], v[50:53], v[192:195], v[110:113]
	v_mfma_f32_16x16x32_bf16 v[106:109], v[66:69], v[192:195], v[106:109]
	v_mfma_f32_16x16x32_bf16 v[94:97], v[50:53], v[200:203], v[94:97]
	v_mfma_f32_16x16x32_bf16 v[90:93], v[66:69], v[200:203], v[90:93]
	v_mfma_f32_16x16x32_bf16 v[142:145], v[54:57], v[180:183], v[142:145]
	v_mfma_f32_16x16x32_bf16 v[138:141], v[70:73], v[180:183], v[138:141]
	v_mfma_f32_16x16x32_bf16 v[126:129], v[54:57], v[188:191], v[126:129]
	v_mfma_f32_16x16x32_bf16 v[122:125], v[70:73], v[188:191], v[122:125]
	v_mfma_f32_16x16x32_bf16 v[110:113], v[54:57], v[196:199], v[110:113]
	v_mfma_f32_16x16x32_bf16 v[106:109], v[70:73], v[196:199], v[106:109]
	v_mfma_f32_16x16x32_bf16 v[94:97], v[54:57], v[204:207], v[94:97]
	v_mfma_f32_16x16x32_bf16 v[90:93], v[70:73], v[204:207], v[90:93]
	v_mfma_f32_16x16x32_bf16 v[134:137], v[156:159], v[172:175], v[134:137]
	v_mfma_f32_16x16x32_bf16 v[130:133], v[164:167], v[172:175], v[130:133]
	v_mfma_f32_16x16x32_bf16 v[118:121], v[156:159], v[184:187], v[118:121]
	v_mfma_f32_16x16x32_bf16 v[114:117], v[164:167], v[184:187], v[114:117]
	v_mfma_f32_16x16x32_bf16 v[102:105], v[156:159], v[192:195], v[102:105]
	v_mfma_f32_16x16x32_bf16 v[98:101], v[164:167], v[192:195], v[98:101]
	v_mfma_f32_16x16x32_bf16 v[86:89], v[156:159], v[200:203], v[86:89]
	v_mfma_f32_16x16x32_bf16 v[82:85], v[164:167], v[200:203], v[82:85]
	v_mfma_f32_16x16x32_bf16 v[134:137], v[160:163], v[180:183], v[134:137]
	v_mfma_f32_16x16x32_bf16 v[130:133], v[168:171], v[180:183], v[130:133]
	v_mfma_f32_16x16x32_bf16 v[118:121], v[160:163], v[188:191], v[118:121]
	v_mfma_f32_16x16x32_bf16 v[114:117], v[168:171], v[188:191], v[114:117]
	v_mfma_f32_16x16x32_bf16 v[102:105], v[160:163], v[196:199], v[102:105]
	v_mfma_f32_16x16x32_bf16 v[98:101], v[168:171], v[196:199], v[98:101]
	v_mfma_f32_16x16x32_bf16 v[86:89], v[160:163], v[204:207], v[86:89]
	v_mfma_f32_16x16x32_bf16 v[82:85], v[168:171], v[204:207], v[82:85]
	s_barrier
	s_setprio 0
	s_add_i32 s66, s66, s60
	v_lshl_add_u64 v[208:209], s[36:37], 0, v[0:1]
	s_mov_b32 m0, s66
	ds_read_b128 v[172:175], v215 offset:16384
	ds_read_b128 v[180:183], v215 offset:17408
	ds_read_b128 v[184:187], v215 offset:18432
	ds_read_b128 v[188:191], v215 offset:19456
	ds_read_b128 v[192:195], v215 offset:20480
	ds_read_b128 v[196:199], v215 offset:21504
	ds_read_b128 v[200:203], v215 offset:22528
	ds_read_b128 v[204:207], v215 offset:23552
	global_load_lds_dwordx4 v[208:209], off
	s_add_i32 m0, s66, 0x2000
	s_add_u32 s66, s36, 0x80000
	v_lshl_add_u64 v[210:211], s[36:37], 0, v[150:151]
	s_addc_u32 s67, s37, 0
	s_add_i32 s72, s72, s60
	global_load_lds_dwordx4 v[210:211], off
	v_lshl_add_u64 v[216:217], s[66:67], 0, v[0:1]
	s_mov_b32 m0, s72
	v_lshl_add_u64 v[218:219], s[38:39], 0, v[148:149]
	global_load_lds_dwordx4 v[216:217], off
	v_lshl_add_u64 v[216:217], s[66:67], 0, v[150:151]
	s_add_i32 m0, s72, 0x2000
	s_nop 0
	global_load_lds_dwordx4 v[216:217], off
	v_lshl_add_u64 v[216:217], s[38:39], 0, v[146:147]
	s_mov_b32 m0, s27
	s_nop 0
	global_load_lds_dwordx4 v[216:217], off
	s_mov_b32 m0, s44
	s_nop 0
	global_load_lds_dwordx4 v[218:219], off
	s_waitcnt vmcnt(8)
	s_waitcnt lgkmcnt(0)
	s_setprio 3
	s_barrier
; #define PG8_STAGE(bufoff, gbase, voff) do { _Pragma("unroll") for (int _i = 0; _i < 2; ++_i) \
;         __builtin_amdgcn_global_load_lds((const unsigned*)((const char*)(gbase) + (voff)[_i]), (LAS unsigned*)(lds + (bufoff) + ldsw + _i * 8192), 16, 0, 0); } while (0)
; #define PG8_LDA(dst, b, h) do { _Pragma("unroll") for (int m = 0; m < 4; ++m) _Pragma("unroll") for (int k = 0; k < 2; ++k) dst[m][k] = *(const LAS bf16x8*)(lds + PG8_SA(b, h) + aoff + m * 2048 + k * 1024); } while (0)
; #define PG8_LDB(dst, b, h) do { _Pragma("unroll") for (int n = 0; n < 2; ++n) _Pragma("unroll") for (int k = 0; k < 2; ++k) dst[n][k] = *(const LAS bf16x8*)(lds + PG8_SB(b, h) + boff + n * 2048 + k * 1024); } while (0)
; #define PG8_MMA(ai, bj, At, Bt) do { __builtin_amdgcn_s_setprio(1); _Pragma("unroll") for (int m = 0; m < 4; ++m) _Pragma("unroll") for (int n = 0; n < 2; ++n) _Pragma("unroll") for (int k = 0; k < 2; ++k) \
;         acc[ai][bj][m][n] = __builtin_amdgcn_mfma_f32_16x16x32_bf16(Bt[n][k], At[m][k], acc[ai][bj][m][n], 0, 0, 0); __builtin_amdgcn_s_setprio(0); } while (0)
; #define PG8_WAIT_V(n) asm volatile("s_waitcnt vmcnt(" #n ")" ::: "memory")
; #define PG8_WAIT_L(n) asm volatile("s_waitcnt lgkmcnt(" #n ")" ::: "memory")
; #define PG8_BAR __builtin_amdgcn_s_barrier()
; #define PG8_SCHED __builtin_amdgcn_sched_barrier(0)
; template <class Epi, class Sched, int LDA, int LDB, bool ALIGN_EPI = true>
; __device__ __forceinline__ void gemm_phase(LAS unsigned char* lds, const Gemm g, const Sched& S, const Epi& E, int wave) {
;     ...
;             PG8_WAIT_V(8); PG8_WAIT_L(0); PG8_BAR; PG8_MMA(1, 0, At, B0); PG8_MMA(1, 1, At, B1); PG8_BAR; PG8_SCHED;
;             PG8_LDB(B0, 1, 0); PG8_LDB(B1, 1, 1); PG8_SCHED; PG8_LDA(At, 1, 0); PG8_STAGE(PG8_SA(0, 1), a2 + hstepA, voffA);
;             PG8_WAIT_V(8); PG8_WAIT_L(0); PG8_BAR; PG8_MMA(0, 0, At, B0); PG8_MMA(0, 1, At, B1); PG8_BAR; PG8_SCHED;
	v_mfma_f32_16x16x32_bf16 v[78:81], v[50:53], v[172:175], v[78:81]
	v_mfma_f32_16x16x32_bf16 v[74:77], v[66:69], v[172:175], v[74:77]
	v_mfma_f32_16x16x32_bf16 v[46:49], v[50:53], v[184:187], v[46:49]
	v_mfma_f32_16x16x32_bf16 v[42:45], v[66:69], v[184:187], v[42:45]
	v_mfma_f32_16x16x32_bf16 v[30:33], v[50:53], v[192:195], v[30:33]
	v_mfma_f32_16x16x32_bf16 v[26:29], v[66:69], v[192:195], v[26:29]
	v_mfma_f32_16x16x32_bf16 v[14:17], v[50:53], v[200:203], v[14:17]
	v_mfma_f32_16x16x32_bf16 v[10:13], v[66:69], v[200:203], v[10:13]
	v_mfma_f32_16x16x32_bf16 v[78:81], v[54:57], v[180:183], v[78:81]
	v_mfma_f32_16x16x32_bf16 v[74:77], v[70:73], v[180:183], v[74:77]
	v_mfma_f32_16x16x32_bf16 v[46:49], v[54:57], v[188:191], v[46:49]
	v_mfma_f32_16x16x32_bf16 v[42:45], v[70:73], v[188:191], v[42:45]
	v_mfma_f32_16x16x32_bf16 v[30:33], v[54:57], v[196:199], v[30:33]
	v_mfma_f32_16x16x32_bf16 v[26:29], v[70:73], v[196:199], v[26:29]
	v_mfma_f32_16x16x32_bf16 v[14:17], v[54:57], v[204:207], v[14:17]
	v_mfma_f32_16x16x32_bf16 v[10:13], v[70:73], v[204:207], v[10:13]
	v_mfma_f32_16x16x32_bf16 v[38:41], v[156:159], v[184:187], v[38:41]
	v_mfma_f32_16x16x32_bf16 v[34:37], v[164:167], v[184:187], v[34:37]
	v_mfma_f32_16x16x32_bf16 v[22:25], v[156:159], v[192:195], v[22:25]
	v_mfma_f32_16x16x32_bf16 v[18:21], v[164:167], v[192:195], v[18:21]
	v_mfma_f32_16x16x32_bf16 v[6:9], v[156:159], v[200:203], v[6:9]
	v_mfma_f32_16x16x32_bf16 v[2:5], v[164:167], v[200:203], v[2:5]
	v_mfma_f32_16x16x32_bf16 v[50:53], v[156:159], v[172:175], v[62:65]
	v_mfma_f32_16x16x32_bf16 v[54:57], v[164:167], v[172:175], v[58:61]
	v_mfma_f32_16x16x32_bf16 v[38:41], v[160:163], v[188:191], v[38:41]
	v_mfma_f32_16x16x32_bf16 v[34:37], v[168:171], v[188:191], v[34:37]
	v_mfma_f32_16x16x32_bf16 v[22:25], v[160:163], v[196:199], v[22:25]
	v_mfma_f32_16x16x32_bf16 v[18:21], v[168:171], v[196:199], v[18:21]
	v_mfma_f32_16x16x32_bf16 v[6:9], v[160:163], v[204:207], v[6:9]
	v_mfma_f32_16x16x32_bf16 v[2:5], v[168:171], v[204:207], v[2:5]
	v_mfma_f32_16x16x32_bf16 v[50:53], v[160:163], v[180:183], v[50:53]
	v_mfma_f32_16x16x32_bf16 v[54:57], v[168:171], v[180:183], v[54:57]
	s_barrier
	s_setprio 0
	s_add_i32 s66, 0, 0x18000
	s_add_i32 s67, 0, 0x1c000
	v_add_u32_e32 v70, s66, v213
	v_add_u32_e32 v168, s67, v213
	ds_read_b128 v[58:61], v70
	ds_read_b128 v[62:65], v70 offset:1024
	ds_read_b128 v[66:69], v70 offset:2048
	ds_read_b128 v[70:73], v70 offset:3072
	ds_read_b128 v[156:159], v168
	ds_read_b128 v[160:163], v168 offset:1024
	ds_read_b128 v[164:167], v168 offset:2048
	ds_read_b128 v[168:171], v168 offset:3072
	s_add_u32 s38, s38, 0x80000
	s_addc_u32 s39, s39, 0
	s_mov_b32 m0, s45
	v_lshl_add_u64 v[220:221], s[38:39], 0, v[146:147]
	ds_read_b128 v[172:175], v215 offset:32768
	ds_read_b128 v[180:183], v215 offset:33792
	ds_read_b128 v[184:187], v215 offset:34816
	ds_read_b128 v[188:191], v215 offset:35840
	ds_read_b128 v[192:195], v215 offset:36864
	ds_read_b128 v[196:199], v215 offset:37888
	ds_read_b128 v[200:203], v215 offset:38912
	ds_read_b128 v[204:207], v215 offset:39936
	global_load_lds_dwordx4 v[220:221], off
	v_lshl_add_u64 v[220:221], s[38:39], 0, v[148:149]
	s_mov_b32 m0, s46
	s_nop 0
	global_load_lds_dwordx4 v[220:221], off
	s_waitcnt vmcnt(8)
	s_waitcnt lgkmcnt(0)
	s_setprio 3
	s_barrier
	v_mfma_f32_16x16x32_bf16 v[142:145], v[58:61], v[172:175], v[142:145]
	v_mfma_f32_16x16x32_bf16 v[138:141], v[66:69], v[172:175], v[138:141]
	v_mfma_f32_16x16x32_bf16 v[126:129], v[58:61], v[184:187], v[126:129]
	v_mfma_f32_16x16x32_bf16 v[122:125], v[66:69], v[184:187], v[122:125]
	v_mfma_f32_16x16x32_bf16 v[110:113], v[58:61], v[192:195], v[110:113]
	v_mfma_f32_16x16x32_bf16 v[106:109], v[66:69], v[192:195], v[106:109]
	v_mfma_f32_16x16x32_bf16 v[94:97], v[58:61], v[200:203], v[94:97]
	v_mfma_f32_16x16x32_bf16 v[90:93], v[66:69], v[200:203], v[90:93]
	v_mfma_f32_16x16x32_bf16 v[142:145], v[62:65], v[180:183], v[142:145]
	v_mfma_f32_16x16x32_bf16 v[138:141], v[70:73], v[180:183], v[138:141]
	v_mfma_f32_16x16x32_bf16 v[126:129], v[62:65], v[188:191], v[126:129]
	v_mfma_f32_16x16x32_bf16 v[122:125], v[70:73], v[188:191], v[122:125]
	v_mfma_f32_16x16x32_bf16 v[110:113], v[62:65], v[196:199], v[110:113]
	v_mfma_f32_16x16x32_bf16 v[106:109], v[70:73], v[196:199], v[106:109]
	v_mfma_f32_16x16x32_bf16 v[94:97], v[62:65], v[204:207], v[94:97]
	v_mfma_f32_16x16x32_bf16 v[90:93], v[70:73], v[204:207], v[90:93]
	v_mfma_f32_16x16x32_bf16 v[134:137], v[156:159], v[172:175], v[134:137]
	v_mfma_f32_16x16x32_bf16 v[130:133], v[164:167], v[172:175], v[130:133]
	v_mfma_f32_16x16x32_bf16 v[118:121], v[156:159], v[184:187], v[118:121]
	v_mfma_f32_16x16x32_bf16 v[114:117], v[164:167], v[184:187], v[114:117]
	v_mfma_f32_16x16x32_bf16 v[102:105], v[156:159], v[192:195], v[102:105]
	v_mfma_f32_16x16x32_bf16 v[98:101], v[164:167], v[192:195], v[98:101]
	v_mfma_f32_16x16x32_bf16 v[86:89], v[156:159], v[200:203], v[86:89]
	v_mfma_f32_16x16x32_bf16 v[82:85], v[164:167], v[200:203], v[82:85]
	v_mfma_f32_16x16x32_bf16 v[134:137], v[160:163], v[180:183], v[134:137]
	v_mfma_f32_16x16x32_bf16 v[130:133], v[168:171], v[180:183], v[130:133]
	v_mfma_f32_16x16x32_bf16 v[118:121], v[160:163], v[188:191], v[118:121]
	v_mfma_f32_16x16x32_bf16 v[114:117], v[168:171], v[188:191], v[114:117]
	v_mfma_f32_16x16x32_bf16 v[102:105], v[160:163], v[196:199], v[102:105]
	v_mfma_f32_16x16x32_bf16 v[98:101], v[168:171], v[196:199], v[98:101]
	v_mfma_f32_16x16x32_bf16 v[86:89], v[160:163], v[204:207], v[86:89]
	v_mfma_f32_16x16x32_bf16 v[82:85], v[168:171], v[204:207], v[82:85]
	s_barrier
; #define PG8_STAGE(bufoff, gbase, voff) do { _Pragma("unroll") for (int _i = 0; _i < 2; ++_i) \
;         __builtin_amdgcn_global_load_lds((const unsigned*)((const char*)(gbase) + (voff)[_i]), (LAS unsigned*)(lds + (bufoff) + ldsw + _i * 8192), 16, 0, 0); } while (0)
; #define PG8_LDA(dst, b, h) do { _Pragma("unroll") for (int m = 0; m < 4; ++m) _Pragma("unroll") for (int k = 0; k < 2; ++k) dst[m][k] = *(const LAS bf16x8*)(lds + PG8_SA(b, h) + aoff + m * 2048 + k * 1024); } while (0)
; #define PG8_MMA(ai, bj, At, Bt) do { __builtin_amdgcn_s_setprio(1); _Pragma("unroll") for (int m = 0; m < 4; ++m) _Pragma("unroll") for (int n = 0; n < 2; ++n) _Pragma("unroll") for (int k = 0; k < 2; ++k) \
;         acc[ai][bj][m][n] = __builtin_amdgcn_mfma_f32_16x16x32_bf16(Bt[n][k], At[m][k], acc[ai][bj][m][n], 0, 0, 0); __builtin_amdgcn_s_setprio(0); } while (0)
; #define PG8_WAIT_V(n) asm volatile("s_waitcnt vmcnt(" #n ")" ::: "memory")
; #define PG8_WAIT_L(n) asm volatile("s_waitcnt lgkmcnt(" #n ")" ::: "memory")
; #define PG8_BAR __builtin_amdgcn_s_barrier()
; #define PG8_SCHED __builtin_amdgcn_sched_barrier(0)
; template <class Epi, class Sched, int LDA, int LDB, bool ALIGN_EPI = true>
; __device__ __forceinline__ void gemm_phase(LAS unsigned char* lds, const Gemm g, const Sched& S, const Epi& E, int wave) {
;     ...
;             PG8_WAIT_V(8); PG8_WAIT_L(0); PG8_BAR; PG8_MMA(0, 0, At, B0); PG8_MMA(0, 1, At, B1); PG8_BAR; PG8_SCHED;
;             PG8_LDA(At, 1, 1); PG8_STAGE(PG8_SB(1, 0), b3, voffB); PG8_STAGE(PG8_SB(1, 1), b3 + hstepB, voffB); PG8_STAGE(PG8_SA(1, 0), a3, voffA);
;             PG8_WAIT_V(8); PG8_WAIT_L(0); PG8_BAR; PG8_MMA(1, 0, At, B0); PG8_MMA(1, 1, At, B1); PG8_BAR; PG8_SCHED;
;         }
;         if constexpr (ALIGN_EPI) { if (wr == 0) PG8_BAR; }
;         E(acc, cur, wr, wc, fr, fq);
	s_setprio 0
	s_add_i32 s38, s66, s60
	v_lshl_add_u64 v[208:209], v[208:209], 0, s[70:71]
	s_mov_b32 m0, s38
	ds_read_b128 v[172:175], v215 offset:49152
	ds_read_b128 v[180:183], v215 offset:50176
	ds_read_b128 v[184:187], v215 offset:51200
	ds_read_b128 v[188:191], v215 offset:52224
	ds_read_b128 v[192:195], v215 offset:53248
	ds_read_b128 v[196:199], v215 offset:54272
	ds_read_b128 v[200:203], v215 offset:55296
	ds_read_b128 v[204:207], v215 offset:56320
	global_load_lds_dwordx4 v[208:209], off
	s_add_i32 m0, s38, 0x2000
	s_add_u32 s36, s36, 0x80080
	v_lshl_add_u64 v[208:209], v[210:211], 0, s[70:71]
	s_addc_u32 s37, s37, 0
	s_add_i32 s38, s67, s60
	global_load_lds_dwordx4 v[208:209], off
	v_lshl_add_u64 v[208:209], s[36:37], 0, v[0:1]
	s_mov_b32 m0, s38
	s_nop 0
	global_load_lds_dwordx4 v[208:209], off
	v_lshl_add_u64 v[208:209], s[36:37], 0, v[150:151]
	s_add_i32 m0, s38, 0x2000
	s_nop 0
	global_load_lds_dwordx4 v[208:209], off
	v_lshl_add_u64 v[208:209], v[216:217], 0, s[70:71]
	s_mov_b32 m0, s51
	s_nop 0
	global_load_lds_dwordx4 v[208:209], off
	v_lshl_add_u64 v[208:209], v[218:219], 0, s[70:71]
	s_mov_b32 m0, s52
	s_nop 0
	global_load_lds_dwordx4 v[208:209], off
	s_waitcnt vmcnt(8)
	s_waitcnt lgkmcnt(0)
	s_setprio 3
	s_barrier
	v_mfma_f32_16x16x32_bf16 v[78:81], v[58:61], v[172:175], v[78:81]
	v_mfma_f32_16x16x32_bf16 v[74:77], v[66:69], v[172:175], v[74:77]
	v_mfma_f32_16x16x32_bf16 v[46:49], v[58:61], v[184:187], v[46:49]
	v_mfma_f32_16x16x32_bf16 v[42:45], v[66:69], v[184:187], v[42:45]
	v_mfma_f32_16x16x32_bf16 v[30:33], v[58:61], v[192:195], v[30:33]
	v_mfma_f32_16x16x32_bf16 v[26:29], v[66:69], v[192:195], v[26:29]
	v_mfma_f32_16x16x32_bf16 v[14:17], v[58:61], v[200:203], v[14:17]
	v_mfma_f32_16x16x32_bf16 v[10:13], v[66:69], v[200:203], v[10:13]
	v_mfma_f32_16x16x32_bf16 v[78:81], v[62:65], v[180:183], v[78:81]
	v_mfma_f32_16x16x32_bf16 v[74:77], v[70:73], v[180:183], v[74:77]
	v_mfma_f32_16x16x32_bf16 v[46:49], v[62:65], v[188:191], v[46:49]
	v_mfma_f32_16x16x32_bf16 v[42:45], v[70:73], v[188:191], v[42:45]
	v_mfma_f32_16x16x32_bf16 v[30:33], v[62:65], v[196:199], v[30:33]
	v_mfma_f32_16x16x32_bf16 v[26:29], v[70:73], v[196:199], v[26:29]
	v_mfma_f32_16x16x32_bf16 v[14:17], v[62:65], v[204:207], v[14:17]
	v_mfma_f32_16x16x32_bf16 v[10:13], v[70:73], v[204:207], v[10:13]
	v_mfma_f32_16x16x32_bf16 v[50:53], v[156:159], v[172:175], v[50:53]
	v_mfma_f32_16x16x32_bf16 v[62:65], v[160:163], v[180:183], v[50:53]
	v_mfma_f32_16x16x32_bf16 v[50:53], v[164:167], v[172:175], v[54:57]
	v_mfma_f32_16x16x32_bf16 v[38:41], v[156:159], v[184:187], v[38:41]
	v_mfma_f32_16x16x32_bf16 v[34:37], v[164:167], v[184:187], v[34:37]
	v_mfma_f32_16x16x32_bf16 v[22:25], v[156:159], v[192:195], v[22:25]
	v_mfma_f32_16x16x32_bf16 v[18:21], v[164:167], v[192:195], v[18:21]
	v_mfma_f32_16x16x32_bf16 v[6:9], v[156:159], v[200:203], v[6:9]
	v_mfma_f32_16x16x32_bf16 v[2:5], v[164:167], v[200:203], v[2:5]
	v_mfma_f32_16x16x32_bf16 v[58:61], v[168:171], v[180:183], v[50:53]
	v_mfma_f32_16x16x32_bf16 v[38:41], v[160:163], v[188:191], v[38:41]
	v_mfma_f32_16x16x32_bf16 v[34:37], v[168:171], v[188:191], v[34:37]
	v_mfma_f32_16x16x32_bf16 v[22:25], v[160:163], v[196:199], v[22:25]
	v_mfma_f32_16x16x32_bf16 v[18:21], v[168:171], v[196:199], v[18:21]
	v_mfma_f32_16x16x32_bf16 v[6:9], v[160:163], v[204:207], v[6:9]
	v_mfma_f32_16x16x32_bf16 v[2:5], v[168:171], v[204:207], v[2:5]
	s_barrier
	s_setprio 0
	s_add_u32 s34, s34, 0x100
	s_addc_u32 s35, s35, 0
	s_add_u32 s59, s59, 0x100
	s_addc_u32 s64, s64, 0
	s_cmp_ge_i32 s65, s43
	s_mov_b32 s36, s65
	s_cbranch_scc0 .LBB0_4901
	v_readlane_b32 s34, v252, 14
	v_readlane_b32 s35, v252, 15
	s_and_b64 vcc, exec, s[34:35]
	s_cbranch_vccz .LBB0_4904
	s_barrier
